# EpiHgrn: ds_bpermute carry exchange replaced by DPP row_newbcast folded into the consuming add
# speedup vs baseline: 1.0069x; 1.0069x over previous
; DI float sigmoid_f(float x) { return __builtin_amdgcn_rcpf(1.f + __expf(-x)); }
; template <int CTRL> DI float dpp_f(float x) { return __int_as_float(__builtin_amdgcn_update_dpp(0, __float_as_int(x), CTRL, 0xF, 0xF, true)); }
;     DI void operator()(const AccT& acc, int brow, int bcol, int wr, int wc, int fr, int fq) const {
;     ...
;                 const f32x4 lb0 = *(const f32x4*)(lbv + dir * 1024 + col), lb1 = *(const f32x4*)(lbv + dir * 1024 + col + 4);
;                 bf16_t* EK = (bf16_t*)(P + (dir ? P_HF1 : P_HF0)); float* EBp = (float*)(ebase);
;                 const int lane_ = fq * 16 + fr;
; #pragma unroll
;                 for (int ai = 0; ai < 2; ++ai)
; #pragma unroll
;                 for (int mp = 0; mp < 2; ++mp) {
;                     const size_t row0 = brow + ai * 128 + wr * 64 + mp * 32 + fr, row1 = row0 + 16;
;                     float fa[8], fb[8], xa[8], xb[8];
; #pragma unroll
;                     for (int j = 0; j < 4; ++j) { fa[j] = lb0[j] + (1.f - lb0[j]) * sigmoid_f(acc[ai][bj][2 * mp][0][j]); fa[4 + j] = lb1[j] + (1.f - lb1[j]) * sigmoid_f(acc[ai][bj][2 * mp][1][j]);
;                                                   fb[j] = lb0[j] + (1.f - lb0[j]) * sigmoid_f(acc[ai][bj][2 * mp + 1][0][j]); fb[4 + j] = lb1[j] + (1.f - lb1[j]) * sigmoid_f(acc[ai][bj][2 * mp + 1][1][j]); }
; #pragma unroll
;                     for (int j = 0; j < 8; ++j) { float x = __builtin_amdgcn_logf(fa[j]) * 0.6931471805599453f, y = __builtin_amdgcn_logf(fb[j]) * 0.6931471805599453f;
;                         if (dir == 0) { x += dpp_f<0x111>(x); x += dpp_f<0x112>(x); x += dpp_f<0x114>(x); x += dpp_f<0x118>(x);
;                                         y += dpp_f<0x111>(y); y += dpp_f<0x112>(y); y += dpp_f<0x114>(y); y += dpp_f<0x118>(y);
;                                         y += __shfl(x, (lane_ & 48) | 15); }
;                         else { x += dpp_f<0x101>(x); x += dpp_f<0x102>(x); x += dpp_f<0x104>(x); x += dpp_f<0x108>(x);
;                                y += dpp_f<0x101>(y); y += dpp_f<0x102>(y); y += dpp_f<0x104>(y); y += dpp_f<0x108>(y);
;                                x += __shfl(y, lane_ & 48); }
;                         xa[j] = x; xb[j] = y; }
.LBB0_2047:
	s_lshl_b64 s[4:5], s[0:1], 2
	v_readlane_b32 s14, v254, 39
	v_readlane_b32 s15, v254, 40
	s_add_u32 s4, s14, s4
	s_addc_u32 s5, s15, s5
	global_load_dwordx4 v[108:111], v152, s[4:5]
	global_load_dwordx4 v[96:99], v152, s[4:5] offset:16
	v_mul_f32_e32 v132, 0xbfb8aa3b, v132
	v_mul_f32_e32 v128, 0xbfb8aa3b, v128
	v_mul_f32_e32 v133, 0xbfb8aa3b, v133
	v_mul_f32_e32 v129, 0xbfb8aa3b, v129
	v_exp_f32_e32 v132, v132
	v_exp_f32_e32 v128, v128
	v_exp_f32_e32 v133, v133
	v_exp_f32_e32 v129, v129
	v_add_f32_e32 v132, 1.0, v132
	v_add_f32_e32 v144, 1.0, v128
	v_add_f32_e32 v133, 1.0, v133
	v_add_f32_e32 v151, 1.0, v129
	v_rcp_f32_e32 v128, v132
	v_rcp_f32_e32 v154, v144
	v_rcp_f32_e32 v129, v133
	v_rcp_f32_e32 v155, v151
	s_mov_b64 s[4:5], -1
	s_and_b64 vcc, exec, s[54:55]
	s_waitcnt vmcnt(0)
	v_pk_add_f32 v[132:133], v[108:109], 1.0 op_sel_hi:[1,0] neg_lo:[1,0] neg_hi:[1,0]
	s_nop 0
	v_pk_fma_f32 v[160:161], v[128:129], v[132:133], v[108:109]
	v_pk_fma_f32 v[156:157], v[154:155], v[132:133], v[108:109]
	v_log_f32_e32 v128, v160
	v_log_f32_e32 v151, v156
	v_mul_f32_e32 v129, 0x3f317218, v128
	v_mul_f32_e32 v128, 0x3f317218, v151
	s_cbranch_vccz .LBB0_2049
	s_nop 0
	v_add_f32_dpp v144, v128, v128 row_shl:1 row_mask:0xf bank_mask:0xf bound_ctrl:1
	v_add_f32_dpp v151, v129, v129 row_shl:1 row_mask:0xf bank_mask:0xf bound_ctrl:1
	s_mov_b64 s[4:5], 0
	v_add_f32_dpp v144, v144, v144 row_shl:2 row_mask:0xf bank_mask:0xf bound_ctrl:1
	v_add_f32_dpp v151, v151, v151 row_shl:2 row_mask:0xf bank_mask:0xf bound_ctrl:1
	s_nop 0
	v_add_f32_dpp v144, v144, v144 row_shl:4 row_mask:0xf bank_mask:0xf bound_ctrl:1
	v_add_f32_dpp v151, v151, v151 row_shl:4 row_mask:0xf bank_mask:0xf bound_ctrl:1
	s_nop 0
	v_add_f32_dpp v182, v144, v144 row_shl:8 row_mask:0xf bank_mask:0xf bound_ctrl:1
	s_nop 0
	s_nop 0
	s_nop 0
	v_add_f32_dpp v151, v151, v151 row_shl:8 row_mask:0xf bank_mask:0xf bound_ctrl:1
	s_waitcnt lgkmcnt(0)
	s_nop 1
	v_add_f32_dpp v144, v182, v151 row_newbcast:0 row_mask:0xf bank_mask:0xf
.LBB0_2049:
	s_andn2_b64 vcc, exec, s[4:5]
	s_cbranch_vccnz .LBB0_2051
	v_add_f32_dpp v129, v129, v129 row_shr:1 row_mask:0xf bank_mask:0xf bound_ctrl:1
	v_add_f32_dpp v128, v128, v128 row_shr:1 row_mask:0xf bank_mask:0xf bound_ctrl:1
	s_nop 0
	v_add_f32_dpp v129, v129, v129 row_shr:2 row_mask:0xf bank_mask:0xf bound_ctrl:1
	v_add_f32_dpp v128, v128, v128 row_shr:2 row_mask:0xf bank_mask:0xf bound_ctrl:1
	s_nop 0
	v_add_f32_dpp v129, v129, v129 row_shr:4 row_mask:0xf bank_mask:0xf bound_ctrl:1
	v_add_f32_dpp v128, v128, v128 row_shr:4 row_mask:0xf bank_mask:0xf bound_ctrl:1
	s_nop 0
	v_add_f32_dpp v144, v129, v129 row_shr:8 row_mask:0xf bank_mask:0xf bound_ctrl:1
	s_nop 0
	s_nop 0
	s_nop 0
	v_add_f32_dpp v128, v128, v128 row_shr:8 row_mask:0xf bank_mask:0xf bound_ctrl:1
	s_waitcnt lgkmcnt(0)
	s_nop 1
	v_add_f32_dpp v182, v144, v128 row_newbcast:15 row_mask:0xf bank_mask:0xf
.LBB0_2051:
	v_log_f32_e32 v128, v161
	v_log_f32_e32 v151, v157
	v_cndmask_b32_e64 v153, 0, 1, s[54:55]
	v_cmp_ne_u32_e64 s[4:5], 1, v153
	v_mul_f32_e32 v129, 0x3f317218, v128
	v_mul_f32_e32 v128, 0x3f317218, v151
	s_andn2_b64 vcc, exec, s[54:55]
	s_mov_b64 s[14:15], -1
	s_cbranch_vccnz .LBB0_2053
	v_add_f32_dpp v151, v128, v128 row_shl:1 row_mask:0xf bank_mask:0xf bound_ctrl:1
	v_add_f32_dpp v153, v129, v129 row_shl:1 row_mask:0xf bank_mask:0xf bound_ctrl:1
	s_mov_b64 s[14:15], 0
	v_add_f32_dpp v151, v151, v151 row_shl:2 row_mask:0xf bank_mask:0xf bound_ctrl:1
	v_add_f32_dpp v153, v153, v153 row_shl:2 row_mask:0xf bank_mask:0xf bound_ctrl:1
	s_nop 0
	v_add_f32_dpp v151, v151, v151 row_shl:4 row_mask:0xf bank_mask:0xf bound_ctrl:1
	v_add_f32_dpp v153, v153, v153 row_shl:4 row_mask:0xf bank_mask:0xf bound_ctrl:1
	s_nop 0
	v_add_f32_dpp v183, v151, v151 row_shl:8 row_mask:0xf bank_mask:0xf bound_ctrl:1
	s_nop 0
	s_nop 0
	s_nop 0
	v_add_f32_dpp v153, v153, v153 row_shl:8 row_mask:0xf bank_mask:0xf bound_ctrl:1
	s_waitcnt lgkmcnt(0)
	s_nop 1
	v_add_f32_dpp v188, v183, v153 row_newbcast:0 row_mask:0xf bank_mask:0xf
.LBB0_2053:
	s_andn2_b64 vcc, exec, s[14:15]
	s_cbranch_vccnz .LBB0_2055
	v_add_f32_dpp v129, v129, v129 row_shr:1 row_mask:0xf bank_mask:0xf bound_ctrl:1
	v_add_f32_dpp v128, v128, v128 row_shr:1 row_mask:0xf bank_mask:0xf bound_ctrl:1
	s_nop 0
	v_add_f32_dpp v129, v129, v129 row_shr:2 row_mask:0xf bank_mask:0xf bound_ctrl:1
	v_add_f32_dpp v128, v128, v128 row_shr:2 row_mask:0xf bank_mask:0xf bound_ctrl:1
	s_nop 0
	v_add_f32_dpp v129, v129, v129 row_shr:4 row_mask:0xf bank_mask:0xf bound_ctrl:1
	v_add_f32_dpp v128, v128, v128 row_shr:4 row_mask:0xf bank_mask:0xf bound_ctrl:1
	s_nop 0
	v_add_f32_dpp v188, v129, v129 row_shr:8 row_mask:0xf bank_mask:0xf bound_ctrl:1
	s_nop 0
	s_nop 0
	s_nop 0
	v_add_f32_dpp v128, v128, v128 row_shr:8 row_mask:0xf bank_mask:0xf bound_ctrl:1
	s_waitcnt lgkmcnt(0)
	s_nop 1
	v_add_f32_dpp v183, v188, v128 row_newbcast:15 row_mask:0xf bank_mask:0xf
; DI float sigmoid_f(float x) { return __builtin_amdgcn_rcpf(1.f + __expf(-x)); }
; template <int CTRL> DI float dpp_f(float x) { return __int_as_float(__builtin_amdgcn_update_dpp(0, __float_as_int(x), CTRL, 0xF, 0xF, true)); }
;     DI void operator()(const AccT& acc, int brow, int bcol, int wr, int wc, int fr, int fq) const {
;     ...
;                     for (int j = 0; j < 4; ++j) { fa[j] = lb0[j] + (1.f - lb0[j]) * sigmoid_f(acc[ai][bj][2 * mp][0][j]); fa[4 + j] = lb1[j] + (1.f - lb1[j]) * sigmoid_f(acc[ai][bj][2 * mp][1][j]);
;                                                   fb[j] = lb0[j] + (1.f - lb0[j]) * sigmoid_f(acc[ai][bj][2 * mp + 1][0][j]); fb[4 + j] = lb1[j] + (1.f - lb1[j]) * sigmoid_f(acc[ai][bj][2 * mp + 1][1][j]); }
; #pragma unroll
;                     for (int j = 0; j < 8; ++j) { float x = __builtin_amdgcn_logf(fa[j]) * 0.6931471805599453f, y = __builtin_amdgcn_logf(fb[j]) * 0.6931471805599453f;
;                         if (dir == 0) { x += dpp_f<0x111>(x); x += dpp_f<0x112>(x); x += dpp_f<0x114>(x); x += dpp_f<0x118>(x);
;                                         y += dpp_f<0x111>(y); y += dpp_f<0x112>(y); y += dpp_f<0x114>(y); y += dpp_f<0x118>(y);
;                                         y += __shfl(x, (lane_ & 48) | 15); }
;                         else { x += dpp_f<0x101>(x); x += dpp_f<0x102>(x); x += dpp_f<0x104>(x); x += dpp_f<0x108>(x);
;                                y += dpp_f<0x101>(y); y += dpp_f<0x102>(y); y += dpp_f<0x104>(y); y += dpp_f<0x108>(y);
;                                x += __shfl(y, lane_ & 48); }
;                         xa[j] = x; xb[j] = y; }
.LBB0_2055:
	v_mul_f32_e32 v129, 0xbfb8aa3b, v130
	v_mul_f32_e32 v128, 0xbfb8aa3b, v134
	v_exp_f32_e32 v129, v129
	v_mul_f32_e32 v130, 0xbfb8aa3b, v135
	v_mul_f32_e32 v131, 0xbfb8aa3b, v131
	v_exp_f32_e32 v128, v128
	v_exp_f32_e32 v130, v130
	v_exp_f32_e32 v131, v131
	v_add_f32_e32 v129, 1.0, v129
	v_add_f32_e32 v128, 1.0, v128
	v_rcp_f32_e32 v134, v129
	v_add_f32_e32 v129, 1.0, v130
	v_add_f32_e32 v130, 1.0, v131
	v_rcp_f32_e32 v128, v128
	v_rcp_f32_e32 v129, v129
	v_rcp_f32_e32 v135, v130
	v_pk_add_f32 v[130:131], v[110:111], 1.0 op_sel_hi:[1,0] neg_lo:[1,0] neg_hi:[1,0]
	s_and_b64 vcc, exec, s[4:5]
	v_pk_fma_f32 v[162:163], v[128:129], v[130:131], v[110:111]
	v_pk_fma_f32 v[158:159], v[134:135], v[130:131], v[110:111]
	v_log_f32_e32 v128, v162
	v_log_f32_e32 v134, v158
	s_mov_b64 s[14:15], -1
	v_mul_f32_e32 v129, 0x3f317218, v128
	v_mul_f32_e32 v128, 0x3f317218, v134
	s_cbranch_vccnz .LBB0_2057
	s_nop 0
	v_add_f32_dpp v134, v128, v128 row_shl:1 row_mask:0xf bank_mask:0xf bound_ctrl:1
	v_add_f32_dpp v135, v129, v129 row_shl:1 row_mask:0xf bank_mask:0xf bound_ctrl:1
	s_mov_b64 s[14:15], 0
	v_add_f32_dpp v134, v134, v134 row_shl:2 row_mask:0xf bank_mask:0xf bound_ctrl:1
	v_add_f32_dpp v135, v135, v135 row_shl:2 row_mask:0xf bank_mask:0xf bound_ctrl:1
	s_nop 0
	v_add_f32_dpp v134, v134, v134 row_shl:4 row_mask:0xf bank_mask:0xf bound_ctrl:1
	v_add_f32_dpp v135, v135, v135 row_shl:4 row_mask:0xf bank_mask:0xf bound_ctrl:1
	s_nop 0
	v_add_f32_dpp v184, v134, v134 row_shl:8 row_mask:0xf bank_mask:0xf bound_ctrl:1
	s_nop 0
	s_nop 0
	s_nop 0
	v_add_f32_dpp v135, v135, v135 row_shl:8 row_mask:0xf bank_mask:0xf bound_ctrl:1
	s_waitcnt lgkmcnt(0)
	s_nop 1
	v_add_f32_dpp v189, v184, v135 row_newbcast:0 row_mask:0xf bank_mask:0xf
.LBB0_2057:
	s_andn2_b64 vcc, exec, s[14:15]
	s_cbranch_vccnz .LBB0_2059
	v_add_f32_dpp v129, v129, v129 row_shr:1 row_mask:0xf bank_mask:0xf bound_ctrl:1
	v_add_f32_dpp v128, v128, v128 row_shr:1 row_mask:0xf bank_mask:0xf bound_ctrl:1
	s_nop 0
	v_add_f32_dpp v129, v129, v129 row_shr:2 row_mask:0xf bank_mask:0xf bound_ctrl:1
	v_add_f32_dpp v128, v128, v128 row_shr:2 row_mask:0xf bank_mask:0xf bound_ctrl:1
	s_nop 0
	v_add_f32_dpp v129, v129, v129 row_shr:4 row_mask:0xf bank_mask:0xf bound_ctrl:1
	v_add_f32_dpp v128, v128, v128 row_shr:4 row_mask:0xf bank_mask:0xf bound_ctrl:1
	s_nop 0
	v_add_f32_dpp v189, v129, v129 row_shr:8 row_mask:0xf bank_mask:0xf bound_ctrl:1
	s_nop 0
	s_nop 0
	s_nop 0
	v_add_f32_dpp v128, v128, v128 row_shr:8 row_mask:0xf bank_mask:0xf bound_ctrl:1
	s_waitcnt lgkmcnt(0)
	s_nop 1
	v_add_f32_dpp v184, v189, v128 row_newbcast:15 row_mask:0xf bank_mask:0xf
.LBB0_2059:
	v_log_f32_e32 v128, v163
	v_log_f32_e32 v134, v159
	s_and_b64 vcc, exec, s[4:5]
	s_mov_b64 s[14:15], -1
	v_mul_f32_e32 v129, 0x3f317218, v128
	v_mul_f32_e32 v128, 0x3f317218, v134
	s_cbranch_vccnz .LBB0_2061
	s_nop 0
	v_add_f32_dpp v134, v128, v128 row_shl:1 row_mask:0xf bank_mask:0xf bound_ctrl:1
	v_add_f32_dpp v135, v129, v129 row_shl:1 row_mask:0xf bank_mask:0xf bound_ctrl:1
	s_mov_b64 s[14:15], 0
	v_add_f32_dpp v134, v134, v134 row_shl:2 row_mask:0xf bank_mask:0xf bound_ctrl:1
	v_add_f32_dpp v135, v135, v135 row_shl:2 row_mask:0xf bank_mask:0xf bound_ctrl:1
	s_nop 0
	v_add_f32_dpp v134, v134, v134 row_shl:4 row_mask:0xf bank_mask:0xf bound_ctrl:1
	v_add_f32_dpp v135, v135, v135 row_shl:4 row_mask:0xf bank_mask:0xf bound_ctrl:1
	s_nop 0
	v_add_f32_dpp v187, v134, v134 row_shl:8 row_mask:0xf bank_mask:0xf bound_ctrl:1
	s_nop 0
	s_nop 0
	s_nop 0
	v_add_f32_dpp v135, v135, v135 row_shl:8 row_mask:0xf bank_mask:0xf bound_ctrl:1
	s_waitcnt lgkmcnt(0)
	s_nop 1
	v_add_f32_dpp v190, v187, v135 row_newbcast:0 row_mask:0xf bank_mask:0xf
.LBB0_2061:
	s_andn2_b64 vcc, exec, s[14:15]
	s_cbranch_vccnz .LBB0_2063
	v_add_f32_dpp v129, v129, v129 row_shr:1 row_mask:0xf bank_mask:0xf bound_ctrl:1
	v_add_f32_dpp v128, v128, v128 row_shr:1 row_mask:0xf bank_mask:0xf bound_ctrl:1
	s_nop 0
	v_add_f32_dpp v129, v129, v129 row_shr:2 row_mask:0xf bank_mask:0xf bound_ctrl:1
	v_add_f32_dpp v128, v128, v128 row_shr:2 row_mask:0xf bank_mask:0xf bound_ctrl:1
	s_nop 0
	v_add_f32_dpp v129, v129, v129 row_shr:4 row_mask:0xf bank_mask:0xf bound_ctrl:1
	v_add_f32_dpp v128, v128, v128 row_shr:4 row_mask:0xf bank_mask:0xf bound_ctrl:1
	s_nop 0
	v_add_f32_dpp v190, v129, v129 row_shr:8 row_mask:0xf bank_mask:0xf bound_ctrl:1
	s_nop 0
	s_nop 0
	s_nop 0
	v_add_f32_dpp v128, v128, v128 row_shr:8 row_mask:0xf bank_mask:0xf bound_ctrl:1
	s_waitcnt lgkmcnt(0)
	s_nop 1
	v_add_f32_dpp v187, v190, v128 row_newbcast:15 row_mask:0xf bank_mask:0xf
.LBB0_2063:
	v_mul_f32_e32 v124, 0xbfb8aa3b, v124
	v_exp_f32_e32 v124, v124
	v_mul_f32_e32 v120, 0xbfb8aa3b, v120
	v_exp_f32_e32 v120, v120
	v_mul_f32_e32 v121, 0xbfb8aa3b, v121
	v_add_f32_e32 v124, 1.0, v124
	v_exp_f32_e32 v129, v121
	v_add_f32_e32 v128, 1.0, v120
	v_rcp_f32_e32 v120, v124
	v_mul_f32_e32 v124, 0xbfb8aa3b, v125
	v_exp_f32_e32 v125, v124
	v_rcp_f32_e32 v124, v128
	v_pk_add_f32 v[134:135], v[96:97], 1.0 op_sel_hi:[1,0] neg_lo:[1,0] neg_hi:[1,0]
	s_and_b64 vcc, exec, s[4:5]
	v_add_f32_e32 v121, 1.0, v125
	v_add_f32_e32 v125, 1.0, v129
	v_rcp_f32_e32 v121, v121
	v_rcp_f32_e32 v125, v125
	s_mov_b64 s[14:15], -1
	v_pk_fma_f32 v[168:169], v[120:121], v[134:135], v[96:97]
	v_pk_fma_f32 v[164:165], v[124:125], v[134:135], v[96:97]
	v_log_f32_e32 v120, v168
	v_log_f32_e32 v121, v164
	v_mul_f32_e32 v124, 0x3f317218, v120
	v_mul_f32_e32 v120, 0x3f317218, v121
	s_cbranch_vccnz .LBB0_2065
	s_nop 0
	v_add_f32_dpp v121, v120, v120 row_shl:1 row_mask:0xf bank_mask:0xf bound_ctrl:1
	v_add_f32_dpp v125, v124, v124 row_shl:1 row_mask:0xf bank_mask:0xf bound_ctrl:1
	s_mov_b64 s[14:15], 0
	v_add_f32_dpp v121, v121, v121 row_shl:2 row_mask:0xf bank_mask:0xf bound_ctrl:1
	v_add_f32_dpp v125, v125, v125 row_shl:2 row_mask:0xf bank_mask:0xf bound_ctrl:1
	s_nop 0
	v_add_f32_dpp v121, v121, v121 row_shl:4 row_mask:0xf bank_mask:0xf bound_ctrl:1
	v_add_f32_dpp v125, v125, v125 row_shl:4 row_mask:0xf bank_mask:0xf bound_ctrl:1
	s_nop 0
	v_add_f32_dpp v191, v121, v121 row_shl:8 row_mask:0xf bank_mask:0xf bound_ctrl:1
	s_nop 0
	s_nop 0
	s_nop 0
	v_add_f32_dpp v125, v125, v125 row_shl:8 row_mask:0xf bank_mask:0xf bound_ctrl:1
	s_waitcnt lgkmcnt(0)
	s_nop 1
	v_add_f32_dpp v121, v191, v125 row_newbcast:0 row_mask:0xf bank_mask:0xf
; template <int CTRL> DI float dpp_f(float x) { return __int_as_float(__builtin_amdgcn_update_dpp(0, __float_as_int(x), CTRL, 0xF, 0xF, true)); }
;     DI void operator()(const AccT& acc, int brow, int bcol, int wr, int wc, int fr, int fq) const {
;     ...
;                     for (int j = 0; j < 8; ++j) { float x = __builtin_amdgcn_logf(fa[j]) * 0.6931471805599453f, y = __builtin_amdgcn_logf(fb[j]) * 0.6931471805599453f;
;                         if (dir == 0) { x += dpp_f<0x111>(x); x += dpp_f<0x112>(x); x += dpp_f<0x114>(x); x += dpp_f<0x118>(x);
;                                         y += dpp_f<0x111>(y); y += dpp_f<0x112>(y); y += dpp_f<0x114>(y); y += dpp_f<0x118>(y);
;                                         y += __shfl(x, (lane_ & 48) | 15); }
;                         else { x += dpp_f<0x101>(x); x += dpp_f<0x102>(x); x += dpp_f<0x104>(x); x += dpp_f<0x108>(x);
;                                y += dpp_f<0x101>(y); y += dpp_f<0x102>(y); y += dpp_f<0x104>(y); y += dpp_f<0x108>(y);
;                                x += __shfl(y, lane_ & 48); }
;                         xa[j] = x; xb[j] = y; }
.LBB0_2065:
	s_andn2_b64 vcc, exec, s[14:15]
	s_cbranch_vccnz .LBB0_2067
	v_add_f32_dpp v121, v124, v124 row_shr:1 row_mask:0xf bank_mask:0xf bound_ctrl:1
	s_nop 0
	s_nop 0
	v_add_f32_dpp v121, v121, v121 row_shr:2 row_mask:0xf bank_mask:0xf bound_ctrl:1
	v_add_f32_dpp v120, v120, v120 row_shr:1 row_mask:0xf bank_mask:0xf bound_ctrl:1
	s_nop 0
	v_add_f32_dpp v121, v121, v121 row_shr:4 row_mask:0xf bank_mask:0xf bound_ctrl:1
	v_add_f32_dpp v120, v120, v120 row_shr:2 row_mask:0xf bank_mask:0xf bound_ctrl:1
	s_nop 0
	v_add_f32_dpp v121, v121, v121 row_shr:8 row_mask:0xf bank_mask:0xf bound_ctrl:1
	s_nop 0
	v_add_f32_dpp v120, v120, v120 row_shr:4 row_mask:0xf bank_mask:0xf bound_ctrl:1
	s_nop 1
	v_add_f32_dpp v120, v120, v120 row_shr:8 row_mask:0xf bank_mask:0xf bound_ctrl:1
	s_waitcnt lgkmcnt(0)
	s_nop 1
	v_add_f32_dpp v191, v121, v120 row_newbcast:15 row_mask:0xf bank_mask:0xf
.LBB0_2067:
	v_log_f32_e32 v120, v169
	v_log_f32_e32 v125, v165
	s_and_b64 vcc, exec, s[4:5]
	s_mov_b64 s[14:15], -1
	v_mul_f32_e32 v124, 0x3f317218, v120
	v_mul_f32_e32 v120, 0x3f317218, v125
	s_cbranch_vccnz .LBB0_2069
	s_nop 0
	v_add_f32_dpp v125, v120, v120 row_shl:1 row_mask:0xf bank_mask:0xf bound_ctrl:1
	v_add_f32_dpp v128, v124, v124 row_shl:1 row_mask:0xf bank_mask:0xf bound_ctrl:1
	s_mov_b64 s[14:15], 0
	v_add_f32_dpp v125, v125, v125 row_shl:2 row_mask:0xf bank_mask:0xf bound_ctrl:1
	v_add_f32_dpp v128, v128, v128 row_shl:2 row_mask:0xf bank_mask:0xf bound_ctrl:1
	s_nop 0
	v_add_f32_dpp v125, v125, v125 row_shl:4 row_mask:0xf bank_mask:0xf bound_ctrl:1
	v_add_f32_dpp v128, v128, v128 row_shl:4 row_mask:0xf bank_mask:0xf bound_ctrl:1
	s_nop 0
	v_add_f32_dpp v192, v125, v125 row_shl:8 row_mask:0xf bank_mask:0xf bound_ctrl:1
	s_nop 0
	s_nop 0
	s_nop 0
	v_add_f32_dpp v128, v128, v128 row_shl:8 row_mask:0xf bank_mask:0xf bound_ctrl:1
	s_waitcnt lgkmcnt(0)
	s_nop 1
	v_add_f32_dpp v125, v192, v128 row_newbcast:0 row_mask:0xf bank_mask:0xf
.LBB0_2069:
	s_andn2_b64 vcc, exec, s[14:15]
	s_cbranch_vccnz .LBB0_2071
	v_add_f32_dpp v124, v124, v124 row_shr:1 row_mask:0xf bank_mask:0xf bound_ctrl:1
	v_add_f32_dpp v120, v120, v120 row_shr:1 row_mask:0xf bank_mask:0xf bound_ctrl:1
	s_nop 0
	v_add_f32_dpp v124, v124, v124 row_shr:2 row_mask:0xf bank_mask:0xf bound_ctrl:1
	v_add_f32_dpp v120, v120, v120 row_shr:2 row_mask:0xf bank_mask:0xf bound_ctrl:1
	s_nop 0
	v_add_f32_dpp v124, v124, v124 row_shr:4 row_mask:0xf bank_mask:0xf bound_ctrl:1
	v_add_f32_dpp v120, v120, v120 row_shr:4 row_mask:0xf bank_mask:0xf bound_ctrl:1
	s_nop 0
	v_add_f32_dpp v125, v124, v124 row_shr:8 row_mask:0xf bank_mask:0xf bound_ctrl:1
	s_nop 0
	s_nop 0
	s_nop 0
	v_add_f32_dpp v120, v120, v120 row_shr:8 row_mask:0xf bank_mask:0xf bound_ctrl:1
	s_waitcnt lgkmcnt(0)
	s_nop 1
	v_add_f32_dpp v192, v125, v120 row_newbcast:15 row_mask:0xf bank_mask:0xf
; DI float sigmoid_f(float x) { return __builtin_amdgcn_rcpf(1.f + __expf(-x)); }
; template <int CTRL> DI float dpp_f(float x) { return __int_as_float(__builtin_amdgcn_update_dpp(0, __float_as_int(x), CTRL, 0xF, 0xF, true)); }
;     DI void operator()(const AccT& acc, int brow, int bcol, int wr, int wc, int fr, int fq) const {
;     ...
;                     for (int j = 0; j < 4; ++j) { fa[j] = lb0[j] + (1.f - lb0[j]) * sigmoid_f(acc[ai][bj][2 * mp][0][j]); fa[4 + j] = lb1[j] + (1.f - lb1[j]) * sigmoid_f(acc[ai][bj][2 * mp][1][j]);
;                                                   fb[j] = lb0[j] + (1.f - lb0[j]) * sigmoid_f(acc[ai][bj][2 * mp + 1][0][j]); fb[4 + j] = lb1[j] + (1.f - lb1[j]) * sigmoid_f(acc[ai][bj][2 * mp + 1][1][j]); }
; #pragma unroll
;                     for (int j = 0; j < 8; ++j) { float x = __builtin_amdgcn_logf(fa[j]) * 0.6931471805599453f, y = __builtin_amdgcn_logf(fb[j]) * 0.6931471805599453f;
;                         if (dir == 0) { x += dpp_f<0x111>(x); x += dpp_f<0x112>(x); x += dpp_f<0x114>(x); x += dpp_f<0x118>(x);
;                                         y += dpp_f<0x111>(y); y += dpp_f<0x112>(y); y += dpp_f<0x114>(y); y += dpp_f<0x118>(y);
;                                         y += __shfl(x, (lane_ & 48) | 15); }
;                         else { x += dpp_f<0x101>(x); x += dpp_f<0x102>(x); x += dpp_f<0x104>(x); x += dpp_f<0x108>(x);
;                                y += dpp_f<0x101>(y); y += dpp_f<0x102>(y); y += dpp_f<0x104>(y); y += dpp_f<0x108>(y);
;                                x += __shfl(y, lane_ & 48); }
;                         xa[j] = x; xb[j] = y; }
.LBB0_2071:
	v_mul_f32_e32 v120, 0xbfb8aa3b, v126
	v_exp_f32_e32 v120, v120
	v_mul_f32_e32 v122, 0xbfb8aa3b, v122
	v_exp_f32_e32 v122, v122
	v_mul_f32_e32 v123, 0xbfb8aa3b, v123
	v_add_f32_e32 v120, 1.0, v120
	v_pk_add_f32 v[154:155], v[98:99], 1.0 op_sel_hi:[1,0] neg_lo:[1,0] neg_hi:[1,0]
	v_add_f32_e32 v124, 1.0, v122
	v_rcp_f32_e32 v122, v120
	v_mul_f32_e32 v120, 0xbfb8aa3b, v127
	v_exp_f32_e32 v120, v120
	v_exp_f32_e32 v127, v123
	v_rcp_f32_e32 v126, v124
	s_and_b64 vcc, exec, s[4:5]
	v_add_f32_e32 v120, 1.0, v120
	v_rcp_f32_e32 v123, v120
	v_add_f32_e32 v120, 1.0, v127
	v_rcp_f32_e32 v127, v120
	s_mov_b64 s[14:15], -1
	v_pk_fma_f32 v[170:171], v[122:123], v[154:155], v[98:99]
	v_pk_fma_f32 v[166:167], v[126:127], v[154:155], v[98:99]
	v_log_f32_e32 v120, v170
	v_log_f32_e32 v123, v166
	v_mul_f32_e32 v122, 0x3f317218, v120
	v_mul_f32_e32 v120, 0x3f317218, v123
	s_cbranch_vccnz .LBB0_2073
	s_nop 0
	v_add_f32_dpp v123, v120, v120 row_shl:1 row_mask:0xf bank_mask:0xf bound_ctrl:1
	v_add_f32_dpp v124, v122, v122 row_shl:1 row_mask:0xf bank_mask:0xf bound_ctrl:1
	s_mov_b64 s[14:15], 0
	v_add_f32_dpp v123, v123, v123 row_shl:2 row_mask:0xf bank_mask:0xf bound_ctrl:1
	v_add_f32_dpp v124, v124, v124 row_shl:2 row_mask:0xf bank_mask:0xf bound_ctrl:1
	s_nop 0
	v_add_f32_dpp v123, v123, v123 row_shl:4 row_mask:0xf bank_mask:0xf bound_ctrl:1
	v_add_f32_dpp v124, v124, v124 row_shl:4 row_mask:0xf bank_mask:0xf bound_ctrl:1
	s_nop 0
	v_add_f32_dpp v193, v123, v123 row_shl:8 row_mask:0xf bank_mask:0xf bound_ctrl:1
	s_nop 0
	s_nop 0
	s_nop 0
	v_add_f32_dpp v124, v124, v124 row_shl:8 row_mask:0xf bank_mask:0xf bound_ctrl:1
	s_waitcnt lgkmcnt(0)
	s_nop 1
	v_add_f32_dpp v123, v193, v124 row_newbcast:0 row_mask:0xf bank_mask:0xf
.LBB0_2073:
	s_andn2_b64 vcc, exec, s[14:15]
	s_cbranch_vccnz .LBB0_2075
	v_add_f32_dpp v122, v122, v122 row_shr:1 row_mask:0xf bank_mask:0xf bound_ctrl:1
	v_add_f32_dpp v120, v120, v120 row_shr:1 row_mask:0xf bank_mask:0xf bound_ctrl:1
	s_nop 0
	v_add_f32_dpp v122, v122, v122 row_shr:2 row_mask:0xf bank_mask:0xf bound_ctrl:1
	v_add_f32_dpp v120, v120, v120 row_shr:2 row_mask:0xf bank_mask:0xf bound_ctrl:1
	s_nop 0
	v_add_f32_dpp v122, v122, v122 row_shr:4 row_mask:0xf bank_mask:0xf bound_ctrl:1
	v_add_f32_dpp v120, v120, v120 row_shr:4 row_mask:0xf bank_mask:0xf bound_ctrl:1
	s_nop 0
	v_add_f32_dpp v123, v122, v122 row_shr:8 row_mask:0xf bank_mask:0xf bound_ctrl:1
	s_nop 0
	s_nop 0
	s_nop 0
	v_add_f32_dpp v120, v120, v120 row_shr:8 row_mask:0xf bank_mask:0xf bound_ctrl:1
	s_waitcnt lgkmcnt(0)
	s_nop 1
	v_add_f32_dpp v193, v123, v120 row_newbcast:15 row_mask:0xf bank_mask:0xf
.LBB0_2075:
	v_log_f32_e32 v120, v171
	v_log_f32_e32 v124, v167
	s_and_b64 vcc, exec, s[4:5]
	s_mov_b64 s[14:15], -1
	v_mul_f32_e32 v122, 0x3f317218, v120
	v_mul_f32_e32 v120, 0x3f317218, v124
	s_cbranch_vccnz .LBB0_2077
	s_nop 0
	v_add_f32_dpp v124, v120, v120 row_shl:1 row_mask:0xf bank_mask:0xf bound_ctrl:1
	v_add_f32_dpp v126, v122, v122 row_shl:1 row_mask:0xf bank_mask:0xf bound_ctrl:1
	s_mov_b64 s[14:15], 0
	v_add_f32_dpp v124, v124, v124 row_shl:2 row_mask:0xf bank_mask:0xf bound_ctrl:1
	v_add_f32_dpp v126, v126, v126 row_shl:2 row_mask:0xf bank_mask:0xf bound_ctrl:1
	s_nop 0
	v_add_f32_dpp v124, v124, v124 row_shl:4 row_mask:0xf bank_mask:0xf bound_ctrl:1
	v_add_f32_dpp v126, v126, v126 row_shl:4 row_mask:0xf bank_mask:0xf bound_ctrl:1
	s_nop 0
	v_add_f32_dpp v194, v124, v124 row_shl:8 row_mask:0xf bank_mask:0xf bound_ctrl:1
	s_nop 0
	s_nop 0
	s_nop 0
	v_add_f32_dpp v126, v126, v126 row_shl:8 row_mask:0xf bank_mask:0xf bound_ctrl:1
	s_waitcnt lgkmcnt(0)
	s_nop 1
	v_add_f32_dpp v127, v194, v126 row_newbcast:0 row_mask:0xf bank_mask:0xf
.LBB0_2077:
	s_andn2_b64 vcc, exec, s[14:15]
	s_cbranch_vccnz .LBB0_2079
	v_add_f32_dpp v122, v122, v122 row_shr:1 row_mask:0xf bank_mask:0xf bound_ctrl:1
	v_add_f32_dpp v120, v120, v120 row_shr:1 row_mask:0xf bank_mask:0xf bound_ctrl:1
	s_nop 0
	v_add_f32_dpp v122, v122, v122 row_shr:2 row_mask:0xf bank_mask:0xf bound_ctrl:1
	v_add_f32_dpp v120, v120, v120 row_shr:2 row_mask:0xf bank_mask:0xf bound_ctrl:1
	s_nop 0
	v_add_f32_dpp v122, v122, v122 row_shr:4 row_mask:0xf bank_mask:0xf bound_ctrl:1
	v_add_f32_dpp v120, v120, v120 row_shr:4 row_mask:0xf bank_mask:0xf bound_ctrl:1
	s_nop 0
	v_add_f32_dpp v127, v122, v122 row_shr:8 row_mask:0xf bank_mask:0xf bound_ctrl:1
	s_nop 0
	s_nop 0
	s_nop 0
	v_add_f32_dpp v120, v120, v120 row_shr:8 row_mask:0xf bank_mask:0xf bound_ctrl:1
	s_waitcnt lgkmcnt(0)
	s_nop 1
	v_add_f32_dpp v194, v127, v120 row_newbcast:15 row_mask:0xf bank_mask:0xf

; DI float sigmoid_f(float x) { return __builtin_amdgcn_rcpf(1.f + __expf(-x)); }
; template <int CTRL> DI float dpp_f(float x) { return __int_as_float(__builtin_amdgcn_update_dpp(0, __float_as_int(x), CTRL, 0xF, 0xF, true)); }
;     DI void operator()(const AccT& acc, int brow, int bcol, int wr, int wc, int fr, int fq) const {
;     ...
;                     for (int j = 0; j < 4; ++j) { fa[j] = lb0[j] + (1.f - lb0[j]) * sigmoid_f(acc[ai][bj][2 * mp][0][j]); fa[4 + j] = lb1[j] + (1.f - lb1[j]) * sigmoid_f(acc[ai][bj][2 * mp][1][j]);
;                                                   fb[j] = lb0[j] + (1.f - lb0[j]) * sigmoid_f(acc[ai][bj][2 * mp + 1][0][j]); fb[4 + j] = lb1[j] + (1.f - lb1[j]) * sigmoid_f(acc[ai][bj][2 * mp + 1][1][j]); }
; #pragma unroll
;                     for (int j = 0; j < 8; ++j) { float x = __builtin_amdgcn_logf(fa[j]) * 0.6931471805599453f, y = __builtin_amdgcn_logf(fb[j]) * 0.6931471805599453f;
;                         if (dir == 0) { x += dpp_f<0x111>(x); x += dpp_f<0x112>(x); x += dpp_f<0x114>(x); x += dpp_f<0x118>(x);
;                                         y += dpp_f<0x111>(y); y += dpp_f<0x112>(y); y += dpp_f<0x114>(y); y += dpp_f<0x118>(y);
;                                         y += __shfl(x, (lane_ & 48) | 15); }
;                         else { x += dpp_f<0x101>(x); x += dpp_f<0x102>(x); x += dpp_f<0x104>(x); x += dpp_f<0x108>(x);
;                                y += dpp_f<0x101>(y); y += dpp_f<0x102>(y); y += dpp_f<0x104>(y); y += dpp_f<0x108>(y);
;                                x += __shfl(y, lane_ & 48); }
;                         xa[j] = x; xb[j] = y; }
.LBB0_2083:
	s_or_b64 exec, exec, s[14:15]
	v_mul_f32_e32 v116, 0xbfb8aa3b, v116
	v_exp_f32_e32 v116, v116
	v_mul_f32_e32 v112, 0xbfb8aa3b, v112
	v_exp_f32_e32 v112, v112
	v_mul_f32_e32 v113, 0xbfb8aa3b, v113
	v_add_f32_e32 v116, 1.0, v116
	s_and_b64 vcc, exec, s[4:5]
	v_add_f32_e32 v120, 1.0, v112
	v_rcp_f32_e32 v112, v116
	v_mul_f32_e32 v116, 0xbfb8aa3b, v117
	v_exp_f32_e32 v116, v116
	v_exp_f32_e32 v117, v113
	v_rcp_f32_e32 v120, v120
	s_mov_b64 s[14:15], -1
	v_add_f32_e32 v113, 1.0, v116
	v_add_f32_e32 v116, 1.0, v117
	v_rcp_f32_e32 v113, v113
	v_rcp_f32_e32 v121, v116
	v_pk_fma_f32 v[116:117], v[112:113], v[132:133], v[108:109]
	v_pk_fma_f32 v[112:113], v[120:121], v[132:133], v[108:109]
	v_log_f32_e32 v120, v116
	v_log_f32_e32 v122, v112
	v_mul_f32_e32 v121, 0x3f317218, v120
	v_mul_f32_e32 v120, 0x3f317218, v122
	s_cbranch_vccnz .LBB0_2085
	s_nop 0
	v_add_f32_dpp v122, v120, v120 row_shl:1 row_mask:0xf bank_mask:0xf bound_ctrl:1
	v_add_f32_dpp v123, v121, v121 row_shl:1 row_mask:0xf bank_mask:0xf bound_ctrl:1
	s_mov_b64 s[14:15], 0
	v_add_f32_dpp v122, v122, v122 row_shl:2 row_mask:0xf bank_mask:0xf bound_ctrl:1
	v_add_f32_dpp v123, v123, v123 row_shl:2 row_mask:0xf bank_mask:0xf bound_ctrl:1
	s_nop 0
	v_add_f32_dpp v122, v122, v122 row_shl:4 row_mask:0xf bank_mask:0xf bound_ctrl:1
	v_add_f32_dpp v123, v123, v123 row_shl:4 row_mask:0xf bank_mask:0xf bound_ctrl:1
	s_nop 0
	v_add_f32_dpp v151, v122, v122 row_shl:8 row_mask:0xf bank_mask:0xf bound_ctrl:1
	s_nop 0
	s_nop 0
	s_nop 0
	v_add_f32_dpp v123, v123, v123 row_shl:8 row_mask:0xf bank_mask:0xf bound_ctrl:1
	s_waitcnt lgkmcnt(0)
	s_nop 1
	v_add_f32_dpp v159, v151, v123 row_newbcast:0 row_mask:0xf bank_mask:0xf
.LBB0_2085:
	s_andn2_b64 vcc, exec, s[14:15]
	s_cbranch_vccnz .LBB0_2087
	v_add_f32_dpp v121, v121, v121 row_shr:1 row_mask:0xf bank_mask:0xf bound_ctrl:1
	v_add_f32_dpp v120, v120, v120 row_shr:1 row_mask:0xf bank_mask:0xf bound_ctrl:1
	s_nop 0
	v_add_f32_dpp v121, v121, v121 row_shr:2 row_mask:0xf bank_mask:0xf bound_ctrl:1
	v_add_f32_dpp v120, v120, v120 row_shr:2 row_mask:0xf bank_mask:0xf bound_ctrl:1
	s_nop 0
	v_add_f32_dpp v121, v121, v121 row_shr:4 row_mask:0xf bank_mask:0xf bound_ctrl:1
	v_add_f32_dpp v120, v120, v120 row_shr:4 row_mask:0xf bank_mask:0xf bound_ctrl:1
	s_nop 0
	v_add_f32_dpp v159, v121, v121 row_shr:8 row_mask:0xf bank_mask:0xf bound_ctrl:1
	s_nop 0
	s_nop 0
	s_nop 0
	v_add_f32_dpp v120, v120, v120 row_shr:8 row_mask:0xf bank_mask:0xf bound_ctrl:1
	s_waitcnt lgkmcnt(0)
	s_nop 1
	v_add_f32_dpp v151, v159, v120 row_newbcast:15 row_mask:0xf bank_mask:0xf
.LBB0_2087:
	v_log_f32_e32 v120, v117
	v_log_f32_e32 v122, v113
	s_and_b64 vcc, exec, s[4:5]
	s_mov_b64 s[14:15], -1
	v_mul_f32_e32 v121, 0x3f317218, v120
	v_mul_f32_e32 v120, 0x3f317218, v122
	s_cbranch_vccnz .LBB0_2089
	s_nop 0
	v_add_f32_dpp v122, v120, v120 row_shl:1 row_mask:0xf bank_mask:0xf bound_ctrl:1
	v_add_f32_dpp v123, v121, v121 row_shl:1 row_mask:0xf bank_mask:0xf bound_ctrl:1
	s_mov_b64 s[14:15], 0
	v_add_f32_dpp v122, v122, v122 row_shl:2 row_mask:0xf bank_mask:0xf bound_ctrl:1
	v_add_f32_dpp v123, v123, v123 row_shl:2 row_mask:0xf bank_mask:0xf bound_ctrl:1
	s_nop 0
	v_add_f32_dpp v122, v122, v122 row_shl:4 row_mask:0xf bank_mask:0xf bound_ctrl:1
	v_add_f32_dpp v123, v123, v123 row_shl:4 row_mask:0xf bank_mask:0xf bound_ctrl:1
	s_nop 0
	v_add_f32_dpp v153, v122, v122 row_shl:8 row_mask:0xf bank_mask:0xf bound_ctrl:1
	s_nop 0
	s_nop 0
	s_nop 0
	v_add_f32_dpp v123, v123, v123 row_shl:8 row_mask:0xf bank_mask:0xf bound_ctrl:1
	s_waitcnt lgkmcnt(0)
	s_nop 1
	v_add_f32_dpp v161, v153, v123 row_newbcast:0 row_mask:0xf bank_mask:0xf
.LBB0_2089:
	s_andn2_b64 vcc, exec, s[14:15]
	s_cbranch_vccnz .LBB0_2091
	v_add_f32_dpp v121, v121, v121 row_shr:1 row_mask:0xf bank_mask:0xf bound_ctrl:1
	v_add_f32_dpp v120, v120, v120 row_shr:1 row_mask:0xf bank_mask:0xf bound_ctrl:1
	s_nop 0
	v_add_f32_dpp v121, v121, v121 row_shr:2 row_mask:0xf bank_mask:0xf bound_ctrl:1
	v_add_f32_dpp v120, v120, v120 row_shr:2 row_mask:0xf bank_mask:0xf bound_ctrl:1
	s_nop 0
	v_add_f32_dpp v121, v121, v121 row_shr:4 row_mask:0xf bank_mask:0xf bound_ctrl:1
	v_add_f32_dpp v120, v120, v120 row_shr:4 row_mask:0xf bank_mask:0xf bound_ctrl:1
	s_nop 0
	v_add_f32_dpp v161, v121, v121 row_shr:8 row_mask:0xf bank_mask:0xf bound_ctrl:1
	s_nop 0
	s_nop 0
	s_nop 0
	v_add_f32_dpp v120, v120, v120 row_shr:8 row_mask:0xf bank_mask:0xf bound_ctrl:1
	s_waitcnt lgkmcnt(0)
	s_nop 1
	v_add_f32_dpp v153, v161, v120 row_newbcast:15 row_mask:0xf bank_mask:0xf
.LBB0_2091:
	v_mul_f32_e32 v118, 0xbfb8aa3b, v118
	v_exp_f32_e32 v118, v118
	v_mul_f32_e32 v114, 0xbfb8aa3b, v114
	v_exp_f32_e32 v114, v114
	v_mul_f32_e32 v115, 0xbfb8aa3b, v115
	v_add_f32_e32 v118, 1.0, v118
	s_and_b64 vcc, exec, s[4:5]
	v_add_f32_e32 v120, 1.0, v114
	v_rcp_f32_e32 v114, v118
	v_mul_f32_e32 v118, 0xbfb8aa3b, v119
	v_exp_f32_e32 v118, v118
	v_exp_f32_e32 v119, v115
	v_rcp_f32_e32 v120, v120
	s_mov_b64 s[14:15], -1
	v_add_f32_e32 v115, 1.0, v118
	v_add_f32_e32 v118, 1.0, v119
	v_rcp_f32_e32 v115, v115
	v_rcp_f32_e32 v121, v118
	v_pk_fma_f32 v[118:119], v[114:115], v[130:131], v[110:111]
	v_pk_fma_f32 v[114:115], v[120:121], v[130:131], v[110:111]
	v_log_f32_e32 v120, v118
	v_log_f32_e32 v122, v114
	v_mul_f32_e32 v121, 0x3f317218, v120
	v_mul_f32_e32 v120, 0x3f317218, v122
	s_cbranch_vccnz .LBB0_2093
	s_nop 0
	v_add_f32_dpp v122, v120, v120 row_shl:1 row_mask:0xf bank_mask:0xf bound_ctrl:1
	v_add_f32_dpp v123, v121, v121 row_shl:1 row_mask:0xf bank_mask:0xf bound_ctrl:1
	s_mov_b64 s[14:15], 0
	v_add_f32_dpp v122, v122, v122 row_shl:2 row_mask:0xf bank_mask:0xf bound_ctrl:1
	v_add_f32_dpp v123, v123, v123 row_shl:2 row_mask:0xf bank_mask:0xf bound_ctrl:1
	s_nop 0
	v_add_f32_dpp v122, v122, v122 row_shl:4 row_mask:0xf bank_mask:0xf bound_ctrl:1
	v_add_f32_dpp v123, v123, v123 row_shl:4 row_mask:0xf bank_mask:0xf bound_ctrl:1
	s_nop 0
	v_add_f32_dpp v158, v122, v122 row_shl:8 row_mask:0xf bank_mask:0xf bound_ctrl:1
	s_nop 0
	s_nop 0
	s_nop 0
	v_add_f32_dpp v123, v123, v123 row_shl:8 row_mask:0xf bank_mask:0xf bound_ctrl:1
	s_waitcnt lgkmcnt(0)
	s_nop 1
	v_add_f32_dpp v162, v158, v123 row_newbcast:0 row_mask:0xf bank_mask:0xf
; DI float sigmoid_f(float x) { return __builtin_amdgcn_rcpf(1.f + __expf(-x)); }
; template <int CTRL> DI float dpp_f(float x) { return __int_as_float(__builtin_amdgcn_update_dpp(0, __float_as_int(x), CTRL, 0xF, 0xF, true)); }
;     DI void operator()(const AccT& acc, int brow, int bcol, int wr, int wc, int fr, int fq) const {
;     ...
;                     for (int j = 0; j < 4; ++j) { fa[j] = lb0[j] + (1.f - lb0[j]) * sigmoid_f(acc[ai][bj][2 * mp][0][j]); fa[4 + j] = lb1[j] + (1.f - lb1[j]) * sigmoid_f(acc[ai][bj][2 * mp][1][j]);
;                                                   fb[j] = lb0[j] + (1.f - lb0[j]) * sigmoid_f(acc[ai][bj][2 * mp + 1][0][j]); fb[4 + j] = lb1[j] + (1.f - lb1[j]) * sigmoid_f(acc[ai][bj][2 * mp + 1][1][j]); }
; #pragma unroll
;                     for (int j = 0; j < 8; ++j) { float x = __builtin_amdgcn_logf(fa[j]) * 0.6931471805599453f, y = __builtin_amdgcn_logf(fb[j]) * 0.6931471805599453f;
;                         if (dir == 0) { x += dpp_f<0x111>(x); x += dpp_f<0x112>(x); x += dpp_f<0x114>(x); x += dpp_f<0x118>(x);
;                                         y += dpp_f<0x111>(y); y += dpp_f<0x112>(y); y += dpp_f<0x114>(y); y += dpp_f<0x118>(y);
;                                         y += __shfl(x, (lane_ & 48) | 15); }
;                         else { x += dpp_f<0x101>(x); x += dpp_f<0x102>(x); x += dpp_f<0x104>(x); x += dpp_f<0x108>(x);
;                                y += dpp_f<0x101>(y); y += dpp_f<0x102>(y); y += dpp_f<0x104>(y); y += dpp_f<0x108>(y);
;                                x += __shfl(y, lane_ & 48); }
;                         xa[j] = x; xb[j] = y; }
.LBB0_2093:
	s_andn2_b64 vcc, exec, s[14:15]
	s_cbranch_vccnz .LBB0_2095
	v_add_f32_dpp v121, v121, v121 row_shr:1 row_mask:0xf bank_mask:0xf bound_ctrl:1
	v_add_f32_dpp v120, v120, v120 row_shr:1 row_mask:0xf bank_mask:0xf bound_ctrl:1
	s_nop 0
	v_add_f32_dpp v121, v121, v121 row_shr:2 row_mask:0xf bank_mask:0xf bound_ctrl:1
	v_add_f32_dpp v120, v120, v120 row_shr:2 row_mask:0xf bank_mask:0xf bound_ctrl:1
	s_nop 0
	v_add_f32_dpp v121, v121, v121 row_shr:4 row_mask:0xf bank_mask:0xf bound_ctrl:1
	v_add_f32_dpp v120, v120, v120 row_shr:4 row_mask:0xf bank_mask:0xf bound_ctrl:1
	s_nop 0
	v_add_f32_dpp v162, v121, v121 row_shr:8 row_mask:0xf bank_mask:0xf bound_ctrl:1
	s_nop 0
	s_nop 0
	s_nop 0
	v_add_f32_dpp v120, v120, v120 row_shr:8 row_mask:0xf bank_mask:0xf bound_ctrl:1
	s_waitcnt lgkmcnt(0)
	s_nop 1
	v_add_f32_dpp v158, v162, v120 row_newbcast:15 row_mask:0xf bank_mask:0xf
.LBB0_2095:
	v_log_f32_e32 v120, v119
	v_log_f32_e32 v122, v115
	s_and_b64 vcc, exec, s[4:5]
	s_mov_b64 s[14:15], -1
	v_mul_f32_e32 v121, 0x3f317218, v120
	v_mul_f32_e32 v120, 0x3f317218, v122
	s_cbranch_vccnz .LBB0_2097
	s_nop 0
	v_add_f32_dpp v122, v120, v120 row_shl:1 row_mask:0xf bank_mask:0xf bound_ctrl:1
	v_add_f32_dpp v123, v121, v121 row_shl:1 row_mask:0xf bank_mask:0xf bound_ctrl:1
	s_mov_b64 s[14:15], 0
	v_add_f32_dpp v122, v122, v122 row_shl:2 row_mask:0xf bank_mask:0xf bound_ctrl:1
	v_add_f32_dpp v123, v123, v123 row_shl:2 row_mask:0xf bank_mask:0xf bound_ctrl:1
	s_nop 0
	v_add_f32_dpp v122, v122, v122 row_shl:4 row_mask:0xf bank_mask:0xf bound_ctrl:1
	v_add_f32_dpp v123, v123, v123 row_shl:4 row_mask:0xf bank_mask:0xf bound_ctrl:1
	s_nop 0
	v_add_f32_dpp v160, v122, v122 row_shl:8 row_mask:0xf bank_mask:0xf bound_ctrl:1
	s_nop 0
	s_nop 0
	s_nop 0
	v_add_f32_dpp v123, v123, v123 row_shl:8 row_mask:0xf bank_mask:0xf bound_ctrl:1
	s_waitcnt lgkmcnt(0)
	s_nop 1
	v_add_f32_dpp v163, v160, v123 row_newbcast:0 row_mask:0xf bank_mask:0xf
.LBB0_2097:
	s_andn2_b64 vcc, exec, s[14:15]
	s_cbranch_vccnz .LBB0_2099
	v_add_f32_dpp v121, v121, v121 row_shr:1 row_mask:0xf bank_mask:0xf bound_ctrl:1
	v_add_f32_dpp v120, v120, v120 row_shr:1 row_mask:0xf bank_mask:0xf bound_ctrl:1
	s_nop 0
	v_add_f32_dpp v121, v121, v121 row_shr:2 row_mask:0xf bank_mask:0xf bound_ctrl:1
	v_add_f32_dpp v120, v120, v120 row_shr:2 row_mask:0xf bank_mask:0xf bound_ctrl:1
	s_nop 0
	v_add_f32_dpp v121, v121, v121 row_shr:4 row_mask:0xf bank_mask:0xf bound_ctrl:1
	v_add_f32_dpp v120, v120, v120 row_shr:4 row_mask:0xf bank_mask:0xf bound_ctrl:1
	s_nop 0
	v_add_f32_dpp v163, v121, v121 row_shr:8 row_mask:0xf bank_mask:0xf bound_ctrl:1
	s_nop 0
	s_nop 0
	s_nop 0
	v_add_f32_dpp v120, v120, v120 row_shr:8 row_mask:0xf bank_mask:0xf bound_ctrl:1
	s_waitcnt lgkmcnt(0)
	s_nop 1
	v_add_f32_dpp v160, v163, v120 row_newbcast:15 row_mask:0xf bank_mask:0xf
.LBB0_2099:
	v_mul_f32_e32 v104, 0xbfb8aa3b, v104
	v_exp_f32_e32 v104, v104
	v_mul_f32_e32 v100, 0xbfb8aa3b, v100
	v_exp_f32_e32 v100, v100
	v_mul_f32_e32 v101, 0xbfb8aa3b, v101
	v_add_f32_e32 v104, 1.0, v104
	v_exp_f32_e32 v121, v101
	v_add_f32_e32 v120, 1.0, v100
	v_rcp_f32_e32 v100, v104
	v_mul_f32_e32 v104, 0xbfb8aa3b, v105
	v_exp_f32_e32 v105, v104
	v_rcp_f32_e32 v104, v120
	s_and_b64 vcc, exec, s[4:5]
	s_mov_b64 s[14:15], -1
	v_add_f32_e32 v101, 1.0, v105
	v_add_f32_e32 v105, 1.0, v121
	v_rcp_f32_e32 v101, v101
	v_rcp_f32_e32 v105, v105
	v_pk_fma_f32 v[124:125], v[100:101], v[134:135], v[96:97]
	v_pk_fma_f32 v[120:121], v[104:105], v[134:135], v[96:97]
	v_log_f32_e32 v100, v124
	v_log_f32_e32 v101, v120
	v_mul_f32_e32 v104, 0x3f317218, v100
	v_mul_f32_e32 v100, 0x3f317218, v101
	s_cbranch_vccnz .LBB0_2101
	s_nop 0
	v_add_f32_dpp v101, v100, v100 row_shl:1 row_mask:0xf bank_mask:0xf bound_ctrl:1
	v_add_f32_dpp v105, v104, v104 row_shl:1 row_mask:0xf bank_mask:0xf bound_ctrl:1
	s_mov_b64 s[14:15], 0
	v_add_f32_dpp v101, v101, v101 row_shl:2 row_mask:0xf bank_mask:0xf bound_ctrl:1
	v_add_f32_dpp v105, v105, v105 row_shl:2 row_mask:0xf bank_mask:0xf bound_ctrl:1
	s_nop 0
	v_add_f32_dpp v101, v101, v101 row_shl:4 row_mask:0xf bank_mask:0xf bound_ctrl:1
	v_add_f32_dpp v105, v105, v105 row_shl:4 row_mask:0xf bank_mask:0xf bound_ctrl:1
	s_nop 0
	v_add_f32_dpp v164, v101, v101 row_shl:8 row_mask:0xf bank_mask:0xf bound_ctrl:1
	s_nop 0
	s_nop 0
	s_nop 0
	v_add_f32_dpp v105, v105, v105 row_shl:8 row_mask:0xf bank_mask:0xf bound_ctrl:1
	s_waitcnt lgkmcnt(0)
	s_nop 1
	v_add_f32_dpp v101, v164, v105 row_newbcast:0 row_mask:0xf bank_mask:0xf
.LBB0_2101:
	s_andn2_b64 vcc, exec, s[14:15]
	s_cbranch_vccnz .LBB0_2103
	v_add_f32_dpp v101, v104, v104 row_shr:1 row_mask:0xf bank_mask:0xf bound_ctrl:1
	s_nop 0
	s_nop 0
	v_add_f32_dpp v101, v101, v101 row_shr:2 row_mask:0xf bank_mask:0xf bound_ctrl:1
	v_add_f32_dpp v100, v100, v100 row_shr:1 row_mask:0xf bank_mask:0xf bound_ctrl:1
	s_nop 0
	v_add_f32_dpp v101, v101, v101 row_shr:4 row_mask:0xf bank_mask:0xf bound_ctrl:1
	v_add_f32_dpp v100, v100, v100 row_shr:2 row_mask:0xf bank_mask:0xf bound_ctrl:1
	s_nop 0
	v_add_f32_dpp v101, v101, v101 row_shr:8 row_mask:0xf bank_mask:0xf bound_ctrl:1
	s_nop 0
	v_add_f32_dpp v100, v100, v100 row_shr:4 row_mask:0xf bank_mask:0xf bound_ctrl:1
	s_nop 1
	v_add_f32_dpp v100, v100, v100 row_shr:8 row_mask:0xf bank_mask:0xf bound_ctrl:1
	s_waitcnt lgkmcnt(0)
	s_nop 1
	v_add_f32_dpp v164, v101, v100 row_newbcast:15 row_mask:0xf bank_mask:0xf
; DI float sigmoid_f(float x) { return __builtin_amdgcn_rcpf(1.f + __expf(-x)); }
; template <int CTRL> DI float dpp_f(float x) { return __int_as_float(__builtin_amdgcn_update_dpp(0, __float_as_int(x), CTRL, 0xF, 0xF, true)); }
;     DI void operator()(const AccT& acc, int brow, int bcol, int wr, int wc, int fr, int fq) const {
;     ...
;                     for (int j = 0; j < 4; ++j) { fa[j] = lb0[j] + (1.f - lb0[j]) * sigmoid_f(acc[ai][bj][2 * mp][0][j]); fa[4 + j] = lb1[j] + (1.f - lb1[j]) * sigmoid_f(acc[ai][bj][2 * mp][1][j]);
;                                                   fb[j] = lb0[j] + (1.f - lb0[j]) * sigmoid_f(acc[ai][bj][2 * mp + 1][0][j]); fb[4 + j] = lb1[j] + (1.f - lb1[j]) * sigmoid_f(acc[ai][bj][2 * mp + 1][1][j]); }
; #pragma unroll
;                     for (int j = 0; j < 8; ++j) { float x = __builtin_amdgcn_logf(fa[j]) * 0.6931471805599453f, y = __builtin_amdgcn_logf(fb[j]) * 0.6931471805599453f;
;                         if (dir == 0) { x += dpp_f<0x111>(x); x += dpp_f<0x112>(x); x += dpp_f<0x114>(x); x += dpp_f<0x118>(x);
;                                         y += dpp_f<0x111>(y); y += dpp_f<0x112>(y); y += dpp_f<0x114>(y); y += dpp_f<0x118>(y);
;                                         y += __shfl(x, (lane_ & 48) | 15); }
;                         else { x += dpp_f<0x101>(x); x += dpp_f<0x102>(x); x += dpp_f<0x104>(x); x += dpp_f<0x108>(x);
;                                y += dpp_f<0x101>(y); y += dpp_f<0x102>(y); y += dpp_f<0x104>(y); y += dpp_f<0x108>(y);
;                                x += __shfl(y, lane_ & 48); }
;                         xa[j] = x; xb[j] = y; }
.LBB0_2103:
	v_log_f32_e32 v100, v125
	v_log_f32_e32 v105, v121
	s_and_b64 vcc, exec, s[4:5]
	s_mov_b64 s[14:15], -1
	v_mul_f32_e32 v104, 0x3f317218, v100
	v_mul_f32_e32 v100, 0x3f317218, v105
	s_cbranch_vccnz .LBB0_2105
	s_nop 0
	v_add_f32_dpp v105, v100, v100 row_shl:1 row_mask:0xf bank_mask:0xf bound_ctrl:1
	v_add_f32_dpp v122, v104, v104 row_shl:1 row_mask:0xf bank_mask:0xf bound_ctrl:1
	s_mov_b64 s[14:15], 0
	v_add_f32_dpp v105, v105, v105 row_shl:2 row_mask:0xf bank_mask:0xf bound_ctrl:1
	v_add_f32_dpp v122, v122, v122 row_shl:2 row_mask:0xf bank_mask:0xf bound_ctrl:1
	s_nop 0
	v_add_f32_dpp v105, v105, v105 row_shl:4 row_mask:0xf bank_mask:0xf bound_ctrl:1
	v_add_f32_dpp v122, v122, v122 row_shl:4 row_mask:0xf bank_mask:0xf bound_ctrl:1
	s_nop 0
	v_add_f32_dpp v165, v105, v105 row_shl:8 row_mask:0xf bank_mask:0xf bound_ctrl:1
	s_nop 0
	s_nop 0
	s_nop 0
	v_add_f32_dpp v122, v122, v122 row_shl:8 row_mask:0xf bank_mask:0xf bound_ctrl:1
	s_waitcnt lgkmcnt(0)
	s_nop 1
	v_add_f32_dpp v105, v165, v122 row_newbcast:0 row_mask:0xf bank_mask:0xf
.LBB0_2105:
	s_andn2_b64 vcc, exec, s[14:15]
	s_cbranch_vccnz .LBB0_2107
	v_add_f32_dpp v104, v104, v104 row_shr:1 row_mask:0xf bank_mask:0xf bound_ctrl:1
	v_add_f32_dpp v100, v100, v100 row_shr:1 row_mask:0xf bank_mask:0xf bound_ctrl:1
	s_nop 0
	v_add_f32_dpp v104, v104, v104 row_shr:2 row_mask:0xf bank_mask:0xf bound_ctrl:1
	v_add_f32_dpp v100, v100, v100 row_shr:2 row_mask:0xf bank_mask:0xf bound_ctrl:1
	s_nop 0
	v_add_f32_dpp v104, v104, v104 row_shr:4 row_mask:0xf bank_mask:0xf bound_ctrl:1
	v_add_f32_dpp v100, v100, v100 row_shr:4 row_mask:0xf bank_mask:0xf bound_ctrl:1
	s_nop 0
	v_add_f32_dpp v105, v104, v104 row_shr:8 row_mask:0xf bank_mask:0xf bound_ctrl:1
	s_nop 0
	s_nop 0
	s_nop 0
	v_add_f32_dpp v100, v100, v100 row_shr:8 row_mask:0xf bank_mask:0xf bound_ctrl:1
	s_waitcnt lgkmcnt(0)
	s_nop 1
	v_add_f32_dpp v165, v105, v100 row_newbcast:15 row_mask:0xf bank_mask:0xf
.LBB0_2107:
	v_mul_f32_e32 v100, 0xbfb8aa3b, v106
	v_exp_f32_e32 v100, v100
	v_mul_f32_e32 v102, 0xbfb8aa3b, v102
	v_exp_f32_e32 v102, v102
	v_mul_f32_e32 v103, 0xbfb8aa3b, v103
	v_add_f32_e32 v100, 1.0, v100
	s_and_b64 vcc, exec, s[4:5]
	v_add_f32_e32 v104, 1.0, v102
	v_rcp_f32_e32 v102, v100
	v_mul_f32_e32 v100, 0xbfb8aa3b, v107
	v_exp_f32_e32 v100, v100
	v_exp_f32_e32 v107, v103
	v_rcp_f32_e32 v106, v104
	s_mov_b64 s[14:15], -1
	v_add_f32_e32 v100, 1.0, v100
	v_rcp_f32_e32 v103, v100
	v_add_f32_e32 v100, 1.0, v107
	v_rcp_f32_e32 v107, v100
	v_pk_fma_f32 v[126:127], v[102:103], v[154:155], v[98:99]
	s_nop 0
	v_log_f32_e32 v100, v126
	v_pk_fma_f32 v[122:123], v[106:107], v[154:155], v[98:99]
	v_mul_f32_e32 v102, 0x3f317218, v100
	v_log_f32_e32 v103, v122
	s_nop 0
	v_mul_f32_e32 v100, 0x3f317218, v103
	s_cbranch_vccnz .LBB0_2109
	s_nop 0
	v_add_f32_dpp v103, v100, v100 row_shl:1 row_mask:0xf bank_mask:0xf bound_ctrl:1
	v_add_f32_dpp v104, v102, v102 row_shl:1 row_mask:0xf bank_mask:0xf bound_ctrl:1
	s_mov_b64 s[14:15], 0
	v_add_f32_dpp v103, v103, v103 row_shl:2 row_mask:0xf bank_mask:0xf bound_ctrl:1
	v_add_f32_dpp v104, v104, v104 row_shl:2 row_mask:0xf bank_mask:0xf bound_ctrl:1
	s_nop 0
	v_add_f32_dpp v103, v103, v103 row_shl:4 row_mask:0xf bank_mask:0xf bound_ctrl:1
	v_add_f32_dpp v104, v104, v104 row_shl:4 row_mask:0xf bank_mask:0xf bound_ctrl:1
	s_nop 0
	v_add_f32_dpp v166, v103, v103 row_shl:8 row_mask:0xf bank_mask:0xf bound_ctrl:1
	s_nop 0
	s_nop 0
	s_nop 0
	v_add_f32_dpp v104, v104, v104 row_shl:8 row_mask:0xf bank_mask:0xf bound_ctrl:1
	s_waitcnt lgkmcnt(0)
	s_nop 1
	v_add_f32_dpp v103, v166, v104 row_newbcast:0 row_mask:0xf bank_mask:0xf
.LBB0_2109:
	s_andn2_b64 vcc, exec, s[14:15]
	s_cbranch_vccnz .LBB0_2111
	v_add_f32_dpp v102, v102, v102 row_shr:1 row_mask:0xf bank_mask:0xf bound_ctrl:1
	v_add_f32_dpp v100, v100, v100 row_shr:1 row_mask:0xf bank_mask:0xf bound_ctrl:1
	s_nop 0
	v_add_f32_dpp v102, v102, v102 row_shr:2 row_mask:0xf bank_mask:0xf bound_ctrl:1
	v_add_f32_dpp v100, v100, v100 row_shr:2 row_mask:0xf bank_mask:0xf bound_ctrl:1
	s_nop 0
	v_add_f32_dpp v102, v102, v102 row_shr:4 row_mask:0xf bank_mask:0xf bound_ctrl:1
	v_add_f32_dpp v100, v100, v100 row_shr:4 row_mask:0xf bank_mask:0xf bound_ctrl:1
	s_nop 0
	v_add_f32_dpp v103, v102, v102 row_shr:8 row_mask:0xf bank_mask:0xf bound_ctrl:1
	s_nop 0
	s_nop 0
	s_nop 0
	v_add_f32_dpp v100, v100, v100 row_shr:8 row_mask:0xf bank_mask:0xf bound_ctrl:1
	s_waitcnt lgkmcnt(0)
	s_nop 1
	v_add_f32_dpp v166, v103, v100 row_newbcast:15 row_mask:0xf bank_mask:0xf
.LBB0_2111:
	v_log_f32_e32 v100, v127
	v_log_f32_e32 v104, v123
	s_and_b64 vcc, exec, s[4:5]
	s_mov_b64 s[14:15], -1
	v_mul_f32_e32 v102, 0x3f317218, v100
	v_mul_f32_e32 v100, 0x3f317218, v104
	s_cbranch_vccnz .LBB0_2113
	s_nop 0
	v_add_f32_dpp v104, v100, v100 row_shl:1 row_mask:0xf bank_mask:0xf bound_ctrl:1
	v_add_f32_dpp v106, v102, v102 row_shl:1 row_mask:0xf bank_mask:0xf bound_ctrl:1
	s_mov_b64 s[14:15], 0
	v_add_f32_dpp v104, v104, v104 row_shl:2 row_mask:0xf bank_mask:0xf bound_ctrl:1
	v_add_f32_dpp v106, v106, v106 row_shl:2 row_mask:0xf bank_mask:0xf bound_ctrl:1
	s_nop 0
	v_add_f32_dpp v104, v104, v104 row_shl:4 row_mask:0xf bank_mask:0xf bound_ctrl:1
	v_add_f32_dpp v106, v106, v106 row_shl:4 row_mask:0xf bank_mask:0xf bound_ctrl:1
	s_nop 0
	v_add_f32_dpp v167, v104, v104 row_shl:8 row_mask:0xf bank_mask:0xf bound_ctrl:1
	s_nop 0
	s_nop 0
	s_nop 0
	v_add_f32_dpp v106, v106, v106 row_shl:8 row_mask:0xf bank_mask:0xf bound_ctrl:1
	s_waitcnt lgkmcnt(0)
	s_nop 1
	v_add_f32_dpp v107, v167, v106 row_newbcast:0 row_mask:0xf bank_mask:0xf
.LBB0_2113:
	s_andn2_b64 vcc, exec, s[14:15]
	s_cbranch_vccnz .LBB0_2115
	v_add_f32_dpp v102, v102, v102 row_shr:1 row_mask:0xf bank_mask:0xf bound_ctrl:1
	v_add_f32_dpp v100, v100, v100 row_shr:1 row_mask:0xf bank_mask:0xf bound_ctrl:1
	s_nop 0
	v_add_f32_dpp v102, v102, v102 row_shr:2 row_mask:0xf bank_mask:0xf bound_ctrl:1
	v_add_f32_dpp v100, v100, v100 row_shr:2 row_mask:0xf bank_mask:0xf bound_ctrl:1
	s_nop 0
	v_add_f32_dpp v102, v102, v102 row_shr:4 row_mask:0xf bank_mask:0xf bound_ctrl:1
	v_add_f32_dpp v100, v100, v100 row_shr:4 row_mask:0xf bank_mask:0xf bound_ctrl:1
	s_nop 0
	v_add_f32_dpp v107, v102, v102 row_shr:8 row_mask:0xf bank_mask:0xf bound_ctrl:1
	s_nop 0
	s_nop 0
	s_nop 0
	v_add_f32_dpp v100, v100, v100 row_shr:8 row_mask:0xf bank_mask:0xf bound_ctrl:1
	s_waitcnt lgkmcnt(0)
	s_nop 1
	v_add_f32_dpp v167, v107, v100 row_newbcast:15 row_mask:0xf bank_mask:0xf

; DI float sigmoid_f(float x) { return __builtin_amdgcn_rcpf(1.f + __expf(-x)); }
; template <int CTRL> DI float dpp_f(float x) { return __int_as_float(__builtin_amdgcn_update_dpp(0, __float_as_int(x), CTRL, 0xF, 0xF, true)); }
;     DI void operator()(const AccT& acc, int brow, int bcol, int wr, int wc, int fr, int fq) const {
;     ...
;                 for (int mp = 0; mp < 2; ++mp) {
;                     const size_t row0 = brow + ai * 128 + wr * 64 + mp * 32 + fr, row1 = row0 + 16;
;                     float fa[8], fb[8], xa[8], xb[8];
; #pragma unroll
;                     for (int j = 0; j < 4; ++j) { fa[j] = lb0[j] + (1.f - lb0[j]) * sigmoid_f(acc[ai][bj][2 * mp][0][j]); fa[4 + j] = lb1[j] + (1.f - lb1[j]) * sigmoid_f(acc[ai][bj][2 * mp][1][j]);
;                                                   fb[j] = lb0[j] + (1.f - lb0[j]) * sigmoid_f(acc[ai][bj][2 * mp + 1][0][j]); fb[4 + j] = lb1[j] + (1.f - lb1[j]) * sigmoid_f(acc[ai][bj][2 * mp + 1][1][j]); }
; #pragma unroll
;                     for (int j = 0; j < 8; ++j) { float x = __builtin_amdgcn_logf(fa[j]) * 0.6931471805599453f, y = __builtin_amdgcn_logf(fb[j]) * 0.6931471805599453f;
;                         if (dir == 0) { x += dpp_f<0x111>(x); x += dpp_f<0x112>(x); x += dpp_f<0x114>(x); x += dpp_f<0x118>(x);
;                                         y += dpp_f<0x111>(y); y += dpp_f<0x112>(y); y += dpp_f<0x114>(y); y += dpp_f<0x118>(y);
;                                         y += __shfl(x, (lane_ & 48) | 15); }
;                         else { x += dpp_f<0x101>(x); x += dpp_f<0x102>(x); x += dpp_f<0x104>(x); x += dpp_f<0x108>(x);
;                                y += dpp_f<0x101>(y); y += dpp_f<0x102>(y); y += dpp_f<0x104>(y); y += dpp_f<0x108>(y);
;                                x += __shfl(y, lane_ & 48); }
;                         xa[j] = x; xb[j] = y; }
.LBB0_2119:
	s_or_b64 exec, exec, s[14:15]
	v_mul_f32_e32 v92, 0xbfb8aa3b, v92
	v_exp_f32_e32 v92, v92
	v_mul_f32_e32 v88, 0xbfb8aa3b, v88
	v_exp_f32_e32 v88, v88
	v_mul_f32_e32 v89, 0xbfb8aa3b, v89
	v_add_f32_e32 v92, 1.0, v92
	s_and_b64 vcc, exec, s[4:5]
	v_add_f32_e32 v100, 1.0, v88
	v_rcp_f32_e32 v88, v92
	v_mul_f32_e32 v92, 0xbfb8aa3b, v93
	v_exp_f32_e32 v92, v92
	v_exp_f32_e32 v93, v89
	v_rcp_f32_e32 v100, v100
	s_mov_b64 s[14:15], -1
	v_add_f32_e32 v89, 1.0, v92
	v_add_f32_e32 v92, 1.0, v93
	v_rcp_f32_e32 v89, v89
	v_rcp_f32_e32 v101, v92
	v_pk_fma_f32 v[92:93], v[88:89], v[132:133], v[108:109]
	v_pk_fma_f32 v[88:89], v[100:101], v[132:133], v[108:109]
	v_log_f32_e32 v100, v92
	v_log_f32_e32 v102, v88
	v_mul_f32_e32 v101, 0x3f317218, v100
	v_mul_f32_e32 v100, 0x3f317218, v102
	s_cbranch_vccnz .LBB0_2121
	s_nop 0
	v_add_f32_dpp v102, v100, v100 row_shl:1 row_mask:0xf bank_mask:0xf bound_ctrl:1
	v_add_f32_dpp v103, v101, v101 row_shl:1 row_mask:0xf bank_mask:0xf bound_ctrl:1
	s_mov_b64 s[14:15], 0
	v_add_f32_dpp v102, v102, v102 row_shl:2 row_mask:0xf bank_mask:0xf bound_ctrl:1
	v_add_f32_dpp v103, v103, v103 row_shl:2 row_mask:0xf bank_mask:0xf bound_ctrl:1
	s_nop 0
	v_add_f32_dpp v102, v102, v102 row_shl:4 row_mask:0xf bank_mask:0xf bound_ctrl:1
	v_add_f32_dpp v103, v103, v103 row_shl:4 row_mask:0xf bank_mask:0xf bound_ctrl:1
	s_nop 0
	v_add_f32_dpp v114, v102, v102 row_shl:8 row_mask:0xf bank_mask:0xf bound_ctrl:1
	s_nop 0
	s_nop 0
	s_nop 0
	v_add_f32_dpp v103, v103, v103 row_shl:8 row_mask:0xf bank_mask:0xf bound_ctrl:1
	s_waitcnt lgkmcnt(0)
	s_nop 1
	v_add_f32_dpp v117, v114, v103 row_newbcast:0 row_mask:0xf bank_mask:0xf
.LBB0_2121:
	s_andn2_b64 vcc, exec, s[14:15]
	s_cbranch_vccnz .LBB0_2123
	v_add_f32_dpp v101, v101, v101 row_shr:1 row_mask:0xf bank_mask:0xf bound_ctrl:1
	v_add_f32_dpp v100, v100, v100 row_shr:1 row_mask:0xf bank_mask:0xf bound_ctrl:1
	s_nop 0
	v_add_f32_dpp v101, v101, v101 row_shr:2 row_mask:0xf bank_mask:0xf bound_ctrl:1
	v_add_f32_dpp v100, v100, v100 row_shr:2 row_mask:0xf bank_mask:0xf bound_ctrl:1
	s_nop 0
	v_add_f32_dpp v101, v101, v101 row_shr:4 row_mask:0xf bank_mask:0xf bound_ctrl:1
	v_add_f32_dpp v100, v100, v100 row_shr:4 row_mask:0xf bank_mask:0xf bound_ctrl:1
	s_nop 0
	v_add_f32_dpp v117, v101, v101 row_shr:8 row_mask:0xf bank_mask:0xf bound_ctrl:1
	s_nop 0
	s_nop 0
	s_nop 0
	v_add_f32_dpp v100, v100, v100 row_shr:8 row_mask:0xf bank_mask:0xf bound_ctrl:1
	s_waitcnt lgkmcnt(0)
	s_nop 1
	v_add_f32_dpp v114, v117, v100 row_newbcast:15 row_mask:0xf bank_mask:0xf
.LBB0_2123:
	v_log_f32_e32 v100, v93
	v_log_f32_e32 v102, v89
	s_and_b64 vcc, exec, s[4:5]
	s_mov_b64 s[14:15], -1
	v_mul_f32_e32 v101, 0x3f317218, v100
	v_mul_f32_e32 v100, 0x3f317218, v102
	s_cbranch_vccnz .LBB0_2125
	s_nop 0
	v_add_f32_dpp v102, v100, v100 row_shl:1 row_mask:0xf bank_mask:0xf bound_ctrl:1
	v_add_f32_dpp v103, v101, v101 row_shl:1 row_mask:0xf bank_mask:0xf bound_ctrl:1
	s_mov_b64 s[14:15], 0
	v_add_f32_dpp v102, v102, v102 row_shl:2 row_mask:0xf bank_mask:0xf bound_ctrl:1
	v_add_f32_dpp v103, v103, v103 row_shl:2 row_mask:0xf bank_mask:0xf bound_ctrl:1
	s_nop 0
	v_add_f32_dpp v102, v102, v102 row_shl:4 row_mask:0xf bank_mask:0xf bound_ctrl:1
	v_add_f32_dpp v103, v103, v103 row_shl:4 row_mask:0xf bank_mask:0xf bound_ctrl:1
	s_nop 0
	v_add_f32_dpp v115, v102, v102 row_shl:8 row_mask:0xf bank_mask:0xf bound_ctrl:1
	s_nop 0
	s_nop 0
	s_nop 0
	v_add_f32_dpp v103, v103, v103 row_shl:8 row_mask:0xf bank_mask:0xf bound_ctrl:1
	s_waitcnt lgkmcnt(0)
	s_nop 1
	v_add_f32_dpp v119, v115, v103 row_newbcast:0 row_mask:0xf bank_mask:0xf
.LBB0_2125:
	s_andn2_b64 vcc, exec, s[14:15]
	s_cbranch_vccnz .LBB0_2127
	v_add_f32_dpp v101, v101, v101 row_shr:1 row_mask:0xf bank_mask:0xf bound_ctrl:1
	v_add_f32_dpp v100, v100, v100 row_shr:1 row_mask:0xf bank_mask:0xf bound_ctrl:1
	s_nop 0
	v_add_f32_dpp v101, v101, v101 row_shr:2 row_mask:0xf bank_mask:0xf bound_ctrl:1
	v_add_f32_dpp v100, v100, v100 row_shr:2 row_mask:0xf bank_mask:0xf bound_ctrl:1
	s_nop 0
	v_add_f32_dpp v101, v101, v101 row_shr:4 row_mask:0xf bank_mask:0xf bound_ctrl:1
	v_add_f32_dpp v100, v100, v100 row_shr:4 row_mask:0xf bank_mask:0xf bound_ctrl:1
	s_nop 0
	v_add_f32_dpp v119, v101, v101 row_shr:8 row_mask:0xf bank_mask:0xf bound_ctrl:1
	s_nop 0
	s_nop 0
	s_nop 0
	v_add_f32_dpp v100, v100, v100 row_shr:8 row_mask:0xf bank_mask:0xf bound_ctrl:1
	s_waitcnt lgkmcnt(0)
	s_nop 1
	v_add_f32_dpp v115, v119, v100 row_newbcast:15 row_mask:0xf bank_mask:0xf
.LBB0_2127:
	v_mul_f32_e32 v94, 0xbfb8aa3b, v94
	v_exp_f32_e32 v94, v94
	v_mul_f32_e32 v90, 0xbfb8aa3b, v90
	v_exp_f32_e32 v90, v90
	v_mul_f32_e32 v91, 0xbfb8aa3b, v91
	v_add_f32_e32 v94, 1.0, v94
	s_and_b64 vcc, exec, s[4:5]
	v_add_f32_e32 v100, 1.0, v90
	v_rcp_f32_e32 v90, v94
	v_mul_f32_e32 v94, 0xbfb8aa3b, v95
	v_exp_f32_e32 v94, v94
	v_exp_f32_e32 v95, v91
	v_rcp_f32_e32 v100, v100
	s_mov_b64 s[14:15], -1
	v_add_f32_e32 v91, 1.0, v94
	v_add_f32_e32 v94, 1.0, v95
	v_rcp_f32_e32 v91, v91
	v_rcp_f32_e32 v101, v94
	v_pk_fma_f32 v[94:95], v[90:91], v[130:131], v[110:111]
	v_pk_fma_f32 v[90:91], v[100:101], v[130:131], v[110:111]
	v_log_f32_e32 v100, v94
	v_log_f32_e32 v102, v90
	v_mul_f32_e32 v101, 0x3f317218, v100
	v_mul_f32_e32 v100, 0x3f317218, v102
	s_cbranch_vccnz .LBB0_2129
	s_nop 0
	v_add_f32_dpp v102, v100, v100 row_shl:1 row_mask:0xf bank_mask:0xf bound_ctrl:1
	v_add_f32_dpp v103, v101, v101 row_shl:1 row_mask:0xf bank_mask:0xf bound_ctrl:1
	s_mov_b64 s[14:15], 0
	v_add_f32_dpp v102, v102, v102 row_shl:2 row_mask:0xf bank_mask:0xf bound_ctrl:1
	v_add_f32_dpp v103, v103, v103 row_shl:2 row_mask:0xf bank_mask:0xf bound_ctrl:1
	s_nop 0
	v_add_f32_dpp v102, v102, v102 row_shl:4 row_mask:0xf bank_mask:0xf bound_ctrl:1
	v_add_f32_dpp v103, v103, v103 row_shl:4 row_mask:0xf bank_mask:0xf bound_ctrl:1
	s_nop 0
	v_add_f32_dpp v116, v102, v102 row_shl:8 row_mask:0xf bank_mask:0xf bound_ctrl:1
	s_nop 0
	s_nop 0
	s_nop 0
	v_add_f32_dpp v103, v103, v103 row_shl:8 row_mask:0xf bank_mask:0xf bound_ctrl:1
	s_waitcnt lgkmcnt(0)
	s_nop 1
	v_add_f32_dpp v120, v116, v103 row_newbcast:0 row_mask:0xf bank_mask:0xf
; DI float sigmoid_f(float x) { return __builtin_amdgcn_rcpf(1.f + __expf(-x)); }
; template <int CTRL> DI float dpp_f(float x) { return __int_as_float(__builtin_amdgcn_update_dpp(0, __float_as_int(x), CTRL, 0xF, 0xF, true)); }
;     DI void operator()(const AccT& acc, int brow, int bcol, int wr, int wc, int fr, int fq) const {
;     ...
;                     for (int j = 0; j < 4; ++j) { fa[j] = lb0[j] + (1.f - lb0[j]) * sigmoid_f(acc[ai][bj][2 * mp][0][j]); fa[4 + j] = lb1[j] + (1.f - lb1[j]) * sigmoid_f(acc[ai][bj][2 * mp][1][j]);
;                                                   fb[j] = lb0[j] + (1.f - lb0[j]) * sigmoid_f(acc[ai][bj][2 * mp + 1][0][j]); fb[4 + j] = lb1[j] + (1.f - lb1[j]) * sigmoid_f(acc[ai][bj][2 * mp + 1][1][j]); }
; #pragma unroll
;                     for (int j = 0; j < 8; ++j) { float x = __builtin_amdgcn_logf(fa[j]) * 0.6931471805599453f, y = __builtin_amdgcn_logf(fb[j]) * 0.6931471805599453f;
;                         if (dir == 0) { x += dpp_f<0x111>(x); x += dpp_f<0x112>(x); x += dpp_f<0x114>(x); x += dpp_f<0x118>(x);
;                                         y += dpp_f<0x111>(y); y += dpp_f<0x112>(y); y += dpp_f<0x114>(y); y += dpp_f<0x118>(y);
;                                         y += __shfl(x, (lane_ & 48) | 15); }
;                         else { x += dpp_f<0x101>(x); x += dpp_f<0x102>(x); x += dpp_f<0x104>(x); x += dpp_f<0x108>(x);
;                                y += dpp_f<0x101>(y); y += dpp_f<0x102>(y); y += dpp_f<0x104>(y); y += dpp_f<0x108>(y);
;                                x += __shfl(y, lane_ & 48); }
;                         xa[j] = x; xb[j] = y; }
.LBB0_2129:
	s_andn2_b64 vcc, exec, s[14:15]
	s_cbranch_vccnz .LBB0_2131
	v_add_f32_dpp v101, v101, v101 row_shr:1 row_mask:0xf bank_mask:0xf bound_ctrl:1
	v_add_f32_dpp v100, v100, v100 row_shr:1 row_mask:0xf bank_mask:0xf bound_ctrl:1
	s_nop 0
	v_add_f32_dpp v101, v101, v101 row_shr:2 row_mask:0xf bank_mask:0xf bound_ctrl:1
	v_add_f32_dpp v100, v100, v100 row_shr:2 row_mask:0xf bank_mask:0xf bound_ctrl:1
	s_nop 0
	v_add_f32_dpp v101, v101, v101 row_shr:4 row_mask:0xf bank_mask:0xf bound_ctrl:1
	v_add_f32_dpp v100, v100, v100 row_shr:4 row_mask:0xf bank_mask:0xf bound_ctrl:1
	s_nop 0
	v_add_f32_dpp v120, v101, v101 row_shr:8 row_mask:0xf bank_mask:0xf bound_ctrl:1
	s_nop 0
	s_nop 0
	s_nop 0
	v_add_f32_dpp v100, v100, v100 row_shr:8 row_mask:0xf bank_mask:0xf bound_ctrl:1
	s_waitcnt lgkmcnt(0)
	s_nop 1
	v_add_f32_dpp v116, v120, v100 row_newbcast:15 row_mask:0xf bank_mask:0xf
.LBB0_2131:
	v_log_f32_e32 v100, v95
	v_log_f32_e32 v102, v91
	s_and_b64 vcc, exec, s[4:5]
	s_mov_b64 s[14:15], -1
	v_mul_f32_e32 v101, 0x3f317218, v100
	v_mul_f32_e32 v100, 0x3f317218, v102
	s_cbranch_vccnz .LBB0_2133
	s_nop 0
	v_add_f32_dpp v102, v100, v100 row_shl:1 row_mask:0xf bank_mask:0xf bound_ctrl:1
	v_add_f32_dpp v103, v101, v101 row_shl:1 row_mask:0xf bank_mask:0xf bound_ctrl:1
	s_mov_b64 s[14:15], 0
	v_add_f32_dpp v102, v102, v102 row_shl:2 row_mask:0xf bank_mask:0xf bound_ctrl:1
	v_add_f32_dpp v103, v103, v103 row_shl:2 row_mask:0xf bank_mask:0xf bound_ctrl:1
	s_nop 0
	v_add_f32_dpp v102, v102, v102 row_shl:4 row_mask:0xf bank_mask:0xf bound_ctrl:1
	v_add_f32_dpp v103, v103, v103 row_shl:4 row_mask:0xf bank_mask:0xf bound_ctrl:1
	s_nop 0
	v_add_f32_dpp v118, v102, v102 row_shl:8 row_mask:0xf bank_mask:0xf bound_ctrl:1
	s_nop 0
	s_nop 0
	s_nop 0
	v_add_f32_dpp v103, v103, v103 row_shl:8 row_mask:0xf bank_mask:0xf bound_ctrl:1
	s_waitcnt lgkmcnt(0)
	s_nop 1
	v_add_f32_dpp v121, v118, v103 row_newbcast:0 row_mask:0xf bank_mask:0xf
.LBB0_2133:
	s_andn2_b64 vcc, exec, s[14:15]
	s_cbranch_vccnz .LBB0_2135
	v_add_f32_dpp v101, v101, v101 row_shr:1 row_mask:0xf bank_mask:0xf bound_ctrl:1
	v_add_f32_dpp v100, v100, v100 row_shr:1 row_mask:0xf bank_mask:0xf bound_ctrl:1
	s_nop 0
	v_add_f32_dpp v101, v101, v101 row_shr:2 row_mask:0xf bank_mask:0xf bound_ctrl:1
	v_add_f32_dpp v100, v100, v100 row_shr:2 row_mask:0xf bank_mask:0xf bound_ctrl:1
	s_nop 0
	v_add_f32_dpp v101, v101, v101 row_shr:4 row_mask:0xf bank_mask:0xf bound_ctrl:1
	v_add_f32_dpp v100, v100, v100 row_shr:4 row_mask:0xf bank_mask:0xf bound_ctrl:1
	s_nop 0
	v_add_f32_dpp v121, v101, v101 row_shr:8 row_mask:0xf bank_mask:0xf bound_ctrl:1
	s_nop 0
	s_nop 0
	s_nop 0
	v_add_f32_dpp v100, v100, v100 row_shr:8 row_mask:0xf bank_mask:0xf bound_ctrl:1
	s_waitcnt lgkmcnt(0)
	s_nop 1
	v_add_f32_dpp v118, v121, v100 row_newbcast:15 row_mask:0xf bank_mask:0xf
.LBB0_2135:
	v_mul_f32_e32 v84, 0xbfb8aa3b, v84
	v_exp_f32_e32 v84, v84
	v_mul_f32_e32 v80, 0xbfb8aa3b, v80
	v_exp_f32_e32 v80, v80
	v_mul_f32_e32 v81, 0xbfb8aa3b, v81
	v_add_f32_e32 v84, 1.0, v84
	v_exp_f32_e32 v101, v81
	v_add_f32_e32 v100, 1.0, v80
	v_rcp_f32_e32 v80, v84
	v_mul_f32_e32 v84, 0xbfb8aa3b, v85
	v_exp_f32_e32 v85, v84
	v_rcp_f32_e32 v84, v100
	s_and_b64 vcc, exec, s[4:5]
	s_mov_b64 s[14:15], -1
	v_add_f32_e32 v81, 1.0, v85
	v_add_f32_e32 v85, 1.0, v101
	v_rcp_f32_e32 v81, v81
	v_rcp_f32_e32 v85, v85
	v_pk_fma_f32 v[104:105], v[80:81], v[134:135], v[96:97]
	v_pk_fma_f32 v[100:101], v[84:85], v[134:135], v[96:97]
	v_log_f32_e32 v80, v104
	v_log_f32_e32 v81, v100
	v_mul_f32_e32 v84, 0x3f317218, v80
	v_mul_f32_e32 v80, 0x3f317218, v81
	s_cbranch_vccnz .LBB0_2137
	s_nop 0
	v_add_f32_dpp v81, v80, v80 row_shl:1 row_mask:0xf bank_mask:0xf bound_ctrl:1
	v_add_f32_dpp v85, v84, v84 row_shl:1 row_mask:0xf bank_mask:0xf bound_ctrl:1
	s_mov_b64 s[14:15], 0
	v_add_f32_dpp v81, v81, v81 row_shl:2 row_mask:0xf bank_mask:0xf bound_ctrl:1
	v_add_f32_dpp v85, v85, v85 row_shl:2 row_mask:0xf bank_mask:0xf bound_ctrl:1
	s_nop 0
	v_add_f32_dpp v81, v81, v81 row_shl:4 row_mask:0xf bank_mask:0xf bound_ctrl:1
	v_add_f32_dpp v85, v85, v85 row_shl:4 row_mask:0xf bank_mask:0xf bound_ctrl:1
	s_nop 0
	v_add_f32_dpp v122, v81, v81 row_shl:8 row_mask:0xf bank_mask:0xf bound_ctrl:1
	s_nop 0
	s_nop 0
	s_nop 0
	v_add_f32_dpp v85, v85, v85 row_shl:8 row_mask:0xf bank_mask:0xf bound_ctrl:1
	s_waitcnt lgkmcnt(0)
	s_nop 1
	v_add_f32_dpp v81, v122, v85 row_newbcast:0 row_mask:0xf bank_mask:0xf
.LBB0_2137:
	s_andn2_b64 vcc, exec, s[14:15]
	s_cbranch_vccnz .LBB0_2139
	v_add_f32_dpp v81, v84, v84 row_shr:1 row_mask:0xf bank_mask:0xf bound_ctrl:1
	s_nop 0
	s_nop 0
	v_add_f32_dpp v81, v81, v81 row_shr:2 row_mask:0xf bank_mask:0xf bound_ctrl:1
	v_add_f32_dpp v80, v80, v80 row_shr:1 row_mask:0xf bank_mask:0xf bound_ctrl:1
	s_nop 0
	v_add_f32_dpp v81, v81, v81 row_shr:4 row_mask:0xf bank_mask:0xf bound_ctrl:1
	v_add_f32_dpp v80, v80, v80 row_shr:2 row_mask:0xf bank_mask:0xf bound_ctrl:1
	s_nop 0
	v_add_f32_dpp v81, v81, v81 row_shr:8 row_mask:0xf bank_mask:0xf bound_ctrl:1
	s_nop 0
	v_add_f32_dpp v80, v80, v80 row_shr:4 row_mask:0xf bank_mask:0xf bound_ctrl:1
	s_nop 1
	v_add_f32_dpp v80, v80, v80 row_shr:8 row_mask:0xf bank_mask:0xf bound_ctrl:1
	s_waitcnt lgkmcnt(0)
	s_nop 1
	v_add_f32_dpp v122, v81, v80 row_newbcast:15 row_mask:0xf bank_mask:0xf
; DI float sigmoid_f(float x) { return __builtin_amdgcn_rcpf(1.f + __expf(-x)); }
; template <int CTRL> DI float dpp_f(float x) { return __int_as_float(__builtin_amdgcn_update_dpp(0, __float_as_int(x), CTRL, 0xF, 0xF, true)); }
;     DI void operator()(const AccT& acc, int brow, int bcol, int wr, int wc, int fr, int fq) const {
;     ...
;                     for (int j = 0; j < 4; ++j) { fa[j] = lb0[j] + (1.f - lb0[j]) * sigmoid_f(acc[ai][bj][2 * mp][0][j]); fa[4 + j] = lb1[j] + (1.f - lb1[j]) * sigmoid_f(acc[ai][bj][2 * mp][1][j]);
;                                                   fb[j] = lb0[j] + (1.f - lb0[j]) * sigmoid_f(acc[ai][bj][2 * mp + 1][0][j]); fb[4 + j] = lb1[j] + (1.f - lb1[j]) * sigmoid_f(acc[ai][bj][2 * mp + 1][1][j]); }
; #pragma unroll
;                     for (int j = 0; j < 8; ++j) { float x = __builtin_amdgcn_logf(fa[j]) * 0.6931471805599453f, y = __builtin_amdgcn_logf(fb[j]) * 0.6931471805599453f;
;                         if (dir == 0) { x += dpp_f<0x111>(x); x += dpp_f<0x112>(x); x += dpp_f<0x114>(x); x += dpp_f<0x118>(x);
;                                         y += dpp_f<0x111>(y); y += dpp_f<0x112>(y); y += dpp_f<0x114>(y); y += dpp_f<0x118>(y);
;                                         y += __shfl(x, (lane_ & 48) | 15); }
;                         else { x += dpp_f<0x101>(x); x += dpp_f<0x102>(x); x += dpp_f<0x104>(x); x += dpp_f<0x108>(x);
;                                y += dpp_f<0x101>(y); y += dpp_f<0x102>(y); y += dpp_f<0x104>(y); y += dpp_f<0x108>(y);
;                                x += __shfl(y, lane_ & 48); }
;                         xa[j] = x; xb[j] = y; }
.LBB0_2139:
	v_log_f32_e32 v80, v105
	v_log_f32_e32 v85, v101
	s_and_b64 vcc, exec, s[4:5]
	s_mov_b64 s[14:15], -1
	v_mul_f32_e32 v84, 0x3f317218, v80
	v_mul_f32_e32 v80, 0x3f317218, v85
	s_cbranch_vccnz .LBB0_2141
	s_nop 0
	v_add_f32_dpp v85, v80, v80 row_shl:1 row_mask:0xf bank_mask:0xf bound_ctrl:1
	v_add_f32_dpp v102, v84, v84 row_shl:1 row_mask:0xf bank_mask:0xf bound_ctrl:1
	s_mov_b64 s[14:15], 0
	v_add_f32_dpp v85, v85, v85 row_shl:2 row_mask:0xf bank_mask:0xf bound_ctrl:1
	v_add_f32_dpp v102, v102, v102 row_shl:2 row_mask:0xf bank_mask:0xf bound_ctrl:1
	s_nop 0
	v_add_f32_dpp v85, v85, v85 row_shl:4 row_mask:0xf bank_mask:0xf bound_ctrl:1
	v_add_f32_dpp v102, v102, v102 row_shl:4 row_mask:0xf bank_mask:0xf bound_ctrl:1
	s_nop 0
	v_add_f32_dpp v123, v85, v85 row_shl:8 row_mask:0xf bank_mask:0xf bound_ctrl:1
	s_nop 0
	s_nop 0
	s_nop 0
	v_add_f32_dpp v102, v102, v102 row_shl:8 row_mask:0xf bank_mask:0xf bound_ctrl:1
	s_waitcnt lgkmcnt(0)
	s_nop 1
	v_add_f32_dpp v85, v123, v102 row_newbcast:0 row_mask:0xf bank_mask:0xf
.LBB0_2141:
	s_andn2_b64 vcc, exec, s[14:15]
	s_cbranch_vccnz .LBB0_2143
	v_add_f32_dpp v84, v84, v84 row_shr:1 row_mask:0xf bank_mask:0xf bound_ctrl:1
	v_add_f32_dpp v80, v80, v80 row_shr:1 row_mask:0xf bank_mask:0xf bound_ctrl:1
	s_nop 0
	v_add_f32_dpp v84, v84, v84 row_shr:2 row_mask:0xf bank_mask:0xf bound_ctrl:1
	v_add_f32_dpp v80, v80, v80 row_shr:2 row_mask:0xf bank_mask:0xf bound_ctrl:1
	s_nop 0
	v_add_f32_dpp v84, v84, v84 row_shr:4 row_mask:0xf bank_mask:0xf bound_ctrl:1
	v_add_f32_dpp v80, v80, v80 row_shr:4 row_mask:0xf bank_mask:0xf bound_ctrl:1
	s_nop 0
	v_add_f32_dpp v85, v84, v84 row_shr:8 row_mask:0xf bank_mask:0xf bound_ctrl:1
	s_nop 0
	s_nop 0
	s_nop 0
	v_add_f32_dpp v80, v80, v80 row_shr:8 row_mask:0xf bank_mask:0xf bound_ctrl:1
	s_waitcnt lgkmcnt(0)
	s_nop 1
	v_add_f32_dpp v123, v85, v80 row_newbcast:15 row_mask:0xf bank_mask:0xf
.LBB0_2143:
	v_mul_f32_e32 v80, 0xbfb8aa3b, v86
	v_exp_f32_e32 v80, v80
	v_mul_f32_e32 v82, 0xbfb8aa3b, v82
	v_exp_f32_e32 v82, v82
	v_mul_f32_e32 v83, 0xbfb8aa3b, v83
	v_add_f32_e32 v80, 1.0, v80
	s_and_b64 vcc, exec, s[4:5]
	v_add_f32_e32 v84, 1.0, v82
	v_rcp_f32_e32 v82, v80
	v_mul_f32_e32 v80, 0xbfb8aa3b, v87
	v_exp_f32_e32 v80, v80
	v_exp_f32_e32 v87, v83
	v_rcp_f32_e32 v86, v84
	s_mov_b64 s[14:15], -1
	v_add_f32_e32 v80, 1.0, v80
	v_rcp_f32_e32 v83, v80
	v_add_f32_e32 v80, 1.0, v87
	v_rcp_f32_e32 v87, v80
	v_pk_fma_f32 v[106:107], v[82:83], v[154:155], v[98:99]
	s_nop 0
	v_log_f32_e32 v80, v106
	v_pk_fma_f32 v[102:103], v[86:87], v[154:155], v[98:99]
	v_mul_f32_e32 v82, 0x3f317218, v80
	v_log_f32_e32 v83, v102
	s_nop 0
	v_mul_f32_e32 v80, 0x3f317218, v83
	s_cbranch_vccnz .LBB0_2145
	s_nop 0
	v_add_f32_dpp v83, v80, v80 row_shl:1 row_mask:0xf bank_mask:0xf bound_ctrl:1
	v_add_f32_dpp v84, v82, v82 row_shl:1 row_mask:0xf bank_mask:0xf bound_ctrl:1
	s_mov_b64 s[14:15], 0
	v_add_f32_dpp v83, v83, v83 row_shl:2 row_mask:0xf bank_mask:0xf bound_ctrl:1
	v_add_f32_dpp v84, v84, v84 row_shl:2 row_mask:0xf bank_mask:0xf bound_ctrl:1
	s_nop 0
	v_add_f32_dpp v83, v83, v83 row_shl:4 row_mask:0xf bank_mask:0xf bound_ctrl:1
	v_add_f32_dpp v84, v84, v84 row_shl:4 row_mask:0xf bank_mask:0xf bound_ctrl:1
	s_nop 0
	v_add_f32_dpp v124, v83, v83 row_shl:8 row_mask:0xf bank_mask:0xf bound_ctrl:1
	s_nop 0
	s_nop 0
	s_nop 0
	v_add_f32_dpp v84, v84, v84 row_shl:8 row_mask:0xf bank_mask:0xf bound_ctrl:1
	s_waitcnt lgkmcnt(0)
	s_nop 1
	v_add_f32_dpp v83, v124, v84 row_newbcast:0 row_mask:0xf bank_mask:0xf
.LBB0_2145:
	s_andn2_b64 vcc, exec, s[14:15]
	s_cbranch_vccnz .LBB0_2147
	v_add_f32_dpp v82, v82, v82 row_shr:1 row_mask:0xf bank_mask:0xf bound_ctrl:1
	v_add_f32_dpp v80, v80, v80 row_shr:1 row_mask:0xf bank_mask:0xf bound_ctrl:1
	s_nop 0
	v_add_f32_dpp v82, v82, v82 row_shr:2 row_mask:0xf bank_mask:0xf bound_ctrl:1
	v_add_f32_dpp v80, v80, v80 row_shr:2 row_mask:0xf bank_mask:0xf bound_ctrl:1
	s_nop 0
	v_add_f32_dpp v82, v82, v82 row_shr:4 row_mask:0xf bank_mask:0xf bound_ctrl:1
	v_add_f32_dpp v80, v80, v80 row_shr:4 row_mask:0xf bank_mask:0xf bound_ctrl:1
	s_nop 0
	v_add_f32_dpp v83, v82, v82 row_shr:8 row_mask:0xf bank_mask:0xf bound_ctrl:1
	s_nop 0
	s_nop 0
	s_nop 0
	v_add_f32_dpp v80, v80, v80 row_shr:8 row_mask:0xf bank_mask:0xf bound_ctrl:1
	s_waitcnt lgkmcnt(0)
	s_nop 1
	v_add_f32_dpp v124, v83, v80 row_newbcast:15 row_mask:0xf bank_mask:0xf
.LBB0_2147:
	v_log_f32_e32 v80, v107
	v_log_f32_e32 v84, v103
	s_and_b64 vcc, exec, s[4:5]
	s_mov_b64 s[14:15], -1
	v_mul_f32_e32 v82, 0x3f317218, v80
	v_mul_f32_e32 v80, 0x3f317218, v84
	s_cbranch_vccnz .LBB0_2149
	s_nop 0
	v_add_f32_dpp v84, v80, v80 row_shl:1 row_mask:0xf bank_mask:0xf bound_ctrl:1
	v_add_f32_dpp v86, v82, v82 row_shl:1 row_mask:0xf bank_mask:0xf bound_ctrl:1
	s_mov_b64 s[14:15], 0
	v_add_f32_dpp v84, v84, v84 row_shl:2 row_mask:0xf bank_mask:0xf bound_ctrl:1
	v_add_f32_dpp v86, v86, v86 row_shl:2 row_mask:0xf bank_mask:0xf bound_ctrl:1
	s_nop 0
	v_add_f32_dpp v84, v84, v84 row_shl:4 row_mask:0xf bank_mask:0xf bound_ctrl:1
	v_add_f32_dpp v86, v86, v86 row_shl:4 row_mask:0xf bank_mask:0xf bound_ctrl:1
	s_nop 0
	v_add_f32_dpp v125, v84, v84 row_shl:8 row_mask:0xf bank_mask:0xf bound_ctrl:1
	s_nop 0
	s_nop 0
	s_nop 0
	v_add_f32_dpp v86, v86, v86 row_shl:8 row_mask:0xf bank_mask:0xf bound_ctrl:1
	s_waitcnt lgkmcnt(0)
	s_nop 1
	v_add_f32_dpp v87, v125, v86 row_newbcast:0 row_mask:0xf bank_mask:0xf
.LBB0_2149:
	s_andn2_b64 vcc, exec, s[14:15]
	s_cbranch_vccnz .LBB0_2151
	v_add_f32_dpp v82, v82, v82 row_shr:1 row_mask:0xf bank_mask:0xf bound_ctrl:1
	v_add_f32_dpp v80, v80, v80 row_shr:1 row_mask:0xf bank_mask:0xf bound_ctrl:1
	s_nop 0
	v_add_f32_dpp v82, v82, v82 row_shr:2 row_mask:0xf bank_mask:0xf bound_ctrl:1
	v_add_f32_dpp v80, v80, v80 row_shr:2 row_mask:0xf bank_mask:0xf bound_ctrl:1
	s_nop 0
	v_add_f32_dpp v82, v82, v82 row_shr:4 row_mask:0xf bank_mask:0xf bound_ctrl:1
	v_add_f32_dpp v80, v80, v80 row_shr:4 row_mask:0xf bank_mask:0xf bound_ctrl:1
	s_nop 0
	v_add_f32_dpp v87, v82, v82 row_shr:8 row_mask:0xf bank_mask:0xf bound_ctrl:1
	s_nop 0
	s_nop 0
	s_nop 0
	v_add_f32_dpp v80, v80, v80 row_shr:8 row_mask:0xf bank_mask:0xf bound_ctrl:1
	s_waitcnt lgkmcnt(0)
	s_nop 1
	v_add_f32_dpp v125, v87, v80 row_newbcast:15 row_mask:0xf bank_mask:0xf

; DI float sigmoid_f(float x) { return __builtin_amdgcn_rcpf(1.f + __expf(-x)); }
; template <int CTRL> DI float dpp_f(float x) { return __int_as_float(__builtin_amdgcn_update_dpp(0, __float_as_int(x), CTRL, 0xF, 0xF, true)); }
;     DI void operator()(const AccT& acc, int brow, int bcol, int wr, int wc, int fr, int fq) const {
;     ...
;                 for (int mp = 0; mp < 2; ++mp) {
;                     const size_t row0 = brow + ai * 128 + wr * 64 + mp * 32 + fr, row1 = row0 + 16;
;                     float fa[8], fb[8], xa[8], xb[8];
; #pragma unroll
;                     for (int j = 0; j < 4; ++j) { fa[j] = lb0[j] + (1.f - lb0[j]) * sigmoid_f(acc[ai][bj][2 * mp][0][j]); fa[4 + j] = lb1[j] + (1.f - lb1[j]) * sigmoid_f(acc[ai][bj][2 * mp][1][j]);
;                                                   fb[j] = lb0[j] + (1.f - lb0[j]) * sigmoid_f(acc[ai][bj][2 * mp + 1][0][j]); fb[4 + j] = lb1[j] + (1.f - lb1[j]) * sigmoid_f(acc[ai][bj][2 * mp + 1][1][j]); }
; #pragma unroll
;                     for (int j = 0; j < 8; ++j) { float x = __builtin_amdgcn_logf(fa[j]) * 0.6931471805599453f, y = __builtin_amdgcn_logf(fb[j]) * 0.6931471805599453f;
;                         if (dir == 0) { x += dpp_f<0x111>(x); x += dpp_f<0x112>(x); x += dpp_f<0x114>(x); x += dpp_f<0x118>(x);
;                                         y += dpp_f<0x111>(y); y += dpp_f<0x112>(y); y += dpp_f<0x114>(y); y += dpp_f<0x118>(y);
;                                         y += __shfl(x, (lane_ & 48) | 15); }
;                         else { x += dpp_f<0x101>(x); x += dpp_f<0x102>(x); x += dpp_f<0x104>(x); x += dpp_f<0x108>(x);
;                                y += dpp_f<0x101>(y); y += dpp_f<0x102>(y); y += dpp_f<0x104>(y); y += dpp_f<0x108>(y);
;                                x += __shfl(y, lane_ & 48); }
;                         xa[j] = x; xb[j] = y; }
.LBB0_2155:
	s_or_b64 exec, exec, s[14:15]
	v_mul_f32_e32 v76, 0xbfb8aa3b, v76
	v_exp_f32_e32 v76, v76
	v_mul_f32_e32 v72, 0xbfb8aa3b, v72
	v_exp_f32_e32 v72, v72
	v_mul_f32_e32 v73, 0xbfb8aa3b, v73
	v_add_f32_e32 v76, 1.0, v76
	s_and_b64 vcc, exec, s[4:5]
	v_add_f32_e32 v80, 1.0, v72
	v_rcp_f32_e32 v72, v76
	v_mul_f32_e32 v76, 0xbfb8aa3b, v77
	v_exp_f32_e32 v76, v76
	v_exp_f32_e32 v77, v73
	v_rcp_f32_e32 v80, v80
	s_mov_b64 s[14:15], -1
	v_add_f32_e32 v73, 1.0, v76
	v_add_f32_e32 v76, 1.0, v77
	v_rcp_f32_e32 v73, v73
	v_rcp_f32_e32 v81, v76
	v_pk_fma_f32 v[76:77], v[72:73], v[132:133], v[108:109]
	v_pk_fma_f32 v[72:73], v[80:81], v[132:133], v[108:109]
	v_log_f32_e32 v80, v76
	v_log_f32_e32 v82, v72
	v_mul_f32_e32 v81, 0x3f317218, v80
	v_mul_f32_e32 v80, 0x3f317218, v82
	s_cbranch_vccnz .LBB0_2157
	s_nop 0
	v_add_f32_dpp v82, v80, v80 row_shl:1 row_mask:0xf bank_mask:0xf bound_ctrl:1
	v_add_f32_dpp v83, v81, v81 row_shl:1 row_mask:0xf bank_mask:0xf bound_ctrl:1
	s_mov_b64 s[14:15], 0
	v_add_f32_dpp v82, v82, v82 row_shl:2 row_mask:0xf bank_mask:0xf bound_ctrl:1
	v_add_f32_dpp v83, v83, v83 row_shl:2 row_mask:0xf bank_mask:0xf bound_ctrl:1
	s_nop 0
	v_add_f32_dpp v82, v82, v82 row_shl:4 row_mask:0xf bank_mask:0xf bound_ctrl:1
	v_add_f32_dpp v83, v83, v83 row_shl:4 row_mask:0xf bank_mask:0xf bound_ctrl:1
	s_nop 0
	v_add_f32_dpp v90, v82, v82 row_shl:8 row_mask:0xf bank_mask:0xf bound_ctrl:1
	s_nop 0
	s_nop 0
	s_nop 0
	v_add_f32_dpp v83, v83, v83 row_shl:8 row_mask:0xf bank_mask:0xf bound_ctrl:1
	s_waitcnt lgkmcnt(0)
	s_nop 1
	v_add_f32_dpp v93, v90, v83 row_newbcast:0 row_mask:0xf bank_mask:0xf
.LBB0_2157:
	s_andn2_b64 vcc, exec, s[14:15]
	s_cbranch_vccnz .LBB0_2159
	v_add_f32_dpp v81, v81, v81 row_shr:1 row_mask:0xf bank_mask:0xf bound_ctrl:1
	v_add_f32_dpp v80, v80, v80 row_shr:1 row_mask:0xf bank_mask:0xf bound_ctrl:1
	s_nop 0
	v_add_f32_dpp v81, v81, v81 row_shr:2 row_mask:0xf bank_mask:0xf bound_ctrl:1
	v_add_f32_dpp v80, v80, v80 row_shr:2 row_mask:0xf bank_mask:0xf bound_ctrl:1
	s_nop 0
	v_add_f32_dpp v81, v81, v81 row_shr:4 row_mask:0xf bank_mask:0xf bound_ctrl:1
	v_add_f32_dpp v80, v80, v80 row_shr:4 row_mask:0xf bank_mask:0xf bound_ctrl:1
	s_nop 0
	v_add_f32_dpp v93, v81, v81 row_shr:8 row_mask:0xf bank_mask:0xf bound_ctrl:1
	s_nop 0
	s_nop 0
	s_nop 0
	v_add_f32_dpp v80, v80, v80 row_shr:8 row_mask:0xf bank_mask:0xf bound_ctrl:1
	s_waitcnt lgkmcnt(0)
	s_nop 1
	v_add_f32_dpp v90, v93, v80 row_newbcast:15 row_mask:0xf bank_mask:0xf
.LBB0_2159:
	v_log_f32_e32 v80, v77
	v_log_f32_e32 v82, v73
	s_and_b64 vcc, exec, s[4:5]
	s_mov_b64 s[14:15], -1
	v_mul_f32_e32 v81, 0x3f317218, v80
	v_mul_f32_e32 v80, 0x3f317218, v82
	s_cbranch_vccnz .LBB0_2161
	s_nop 0
	v_add_f32_dpp v82, v80, v80 row_shl:1 row_mask:0xf bank_mask:0xf bound_ctrl:1
	v_add_f32_dpp v83, v81, v81 row_shl:1 row_mask:0xf bank_mask:0xf bound_ctrl:1
	s_mov_b64 s[14:15], 0
	v_add_f32_dpp v82, v82, v82 row_shl:2 row_mask:0xf bank_mask:0xf bound_ctrl:1
	v_add_f32_dpp v83, v83, v83 row_shl:2 row_mask:0xf bank_mask:0xf bound_ctrl:1
	s_nop 0
	v_add_f32_dpp v82, v82, v82 row_shl:4 row_mask:0xf bank_mask:0xf bound_ctrl:1
	v_add_f32_dpp v83, v83, v83 row_shl:4 row_mask:0xf bank_mask:0xf bound_ctrl:1
	s_nop 0
	v_add_f32_dpp v91, v82, v82 row_shl:8 row_mask:0xf bank_mask:0xf bound_ctrl:1
	s_nop 0
	s_nop 0
	s_nop 0
	v_add_f32_dpp v83, v83, v83 row_shl:8 row_mask:0xf bank_mask:0xf bound_ctrl:1
	s_waitcnt lgkmcnt(0)
	s_nop 1
	v_add_f32_dpp v95, v91, v83 row_newbcast:0 row_mask:0xf bank_mask:0xf
.LBB0_2161:
	s_andn2_b64 vcc, exec, s[14:15]
	s_cbranch_vccnz .LBB0_2163
	v_add_f32_dpp v81, v81, v81 row_shr:1 row_mask:0xf bank_mask:0xf bound_ctrl:1
	v_add_f32_dpp v80, v80, v80 row_shr:1 row_mask:0xf bank_mask:0xf bound_ctrl:1
	s_nop 0
	v_add_f32_dpp v81, v81, v81 row_shr:2 row_mask:0xf bank_mask:0xf bound_ctrl:1
	v_add_f32_dpp v80, v80, v80 row_shr:2 row_mask:0xf bank_mask:0xf bound_ctrl:1
	s_nop 0
	v_add_f32_dpp v81, v81, v81 row_shr:4 row_mask:0xf bank_mask:0xf bound_ctrl:1
	v_add_f32_dpp v80, v80, v80 row_shr:4 row_mask:0xf bank_mask:0xf bound_ctrl:1
	s_nop 0
	v_add_f32_dpp v95, v81, v81 row_shr:8 row_mask:0xf bank_mask:0xf bound_ctrl:1
	s_nop 0
	s_nop 0
	s_nop 0
	v_add_f32_dpp v80, v80, v80 row_shr:8 row_mask:0xf bank_mask:0xf bound_ctrl:1
	s_waitcnt lgkmcnt(0)
	s_nop 1
	v_add_f32_dpp v91, v95, v80 row_newbcast:15 row_mask:0xf bank_mask:0xf
.LBB0_2163:
	v_mul_f32_e32 v78, 0xbfb8aa3b, v78
	v_exp_f32_e32 v78, v78
	v_mul_f32_e32 v74, 0xbfb8aa3b, v74
	v_exp_f32_e32 v74, v74
	v_mul_f32_e32 v75, 0xbfb8aa3b, v75
	v_add_f32_e32 v78, 1.0, v78
	s_and_b64 vcc, exec, s[4:5]
	v_add_f32_e32 v80, 1.0, v74
	v_rcp_f32_e32 v74, v78
	v_mul_f32_e32 v78, 0xbfb8aa3b, v79
	v_exp_f32_e32 v78, v78
	v_exp_f32_e32 v79, v75
	v_rcp_f32_e32 v80, v80
	s_mov_b64 s[14:15], -1
	v_add_f32_e32 v75, 1.0, v78
	v_add_f32_e32 v78, 1.0, v79
	v_rcp_f32_e32 v75, v75
	v_rcp_f32_e32 v81, v78
	v_pk_fma_f32 v[78:79], v[74:75], v[130:131], v[110:111]
	v_pk_fma_f32 v[74:75], v[80:81], v[130:131], v[110:111]
	v_log_f32_e32 v80, v78
	v_log_f32_e32 v82, v74
	v_mul_f32_e32 v81, 0x3f317218, v80
	v_mul_f32_e32 v80, 0x3f317218, v82
	s_cbranch_vccnz .LBB0_2165
	s_nop 0
	v_add_f32_dpp v82, v80, v80 row_shl:1 row_mask:0xf bank_mask:0xf bound_ctrl:1
	v_add_f32_dpp v83, v81, v81 row_shl:1 row_mask:0xf bank_mask:0xf bound_ctrl:1
	s_mov_b64 s[14:15], 0
	v_add_f32_dpp v82, v82, v82 row_shl:2 row_mask:0xf bank_mask:0xf bound_ctrl:1
	v_add_f32_dpp v83, v83, v83 row_shl:2 row_mask:0xf bank_mask:0xf bound_ctrl:1
	s_nop 0
	v_add_f32_dpp v82, v82, v82 row_shl:4 row_mask:0xf bank_mask:0xf bound_ctrl:1
	v_add_f32_dpp v83, v83, v83 row_shl:4 row_mask:0xf bank_mask:0xf bound_ctrl:1
	s_nop 0
	v_add_f32_dpp v92, v82, v82 row_shl:8 row_mask:0xf bank_mask:0xf bound_ctrl:1
	s_nop 0
	s_nop 0
	s_nop 0
	v_add_f32_dpp v83, v83, v83 row_shl:8 row_mask:0xf bank_mask:0xf bound_ctrl:1
	s_waitcnt lgkmcnt(0)
	s_nop 1
	v_add_f32_dpp v100, v92, v83 row_newbcast:0 row_mask:0xf bank_mask:0xf
; DI float sigmoid_f(float x) { return __builtin_amdgcn_rcpf(1.f + __expf(-x)); }
; template <int CTRL> DI float dpp_f(float x) { return __int_as_float(__builtin_amdgcn_update_dpp(0, __float_as_int(x), CTRL, 0xF, 0xF, true)); }
;     DI void operator()(const AccT& acc, int brow, int bcol, int wr, int wc, int fr, int fq) const {
;     ...
;                     for (int j = 0; j < 4; ++j) { fa[j] = lb0[j] + (1.f - lb0[j]) * sigmoid_f(acc[ai][bj][2 * mp][0][j]); fa[4 + j] = lb1[j] + (1.f - lb1[j]) * sigmoid_f(acc[ai][bj][2 * mp][1][j]);
;                                                   fb[j] = lb0[j] + (1.f - lb0[j]) * sigmoid_f(acc[ai][bj][2 * mp + 1][0][j]); fb[4 + j] = lb1[j] + (1.f - lb1[j]) * sigmoid_f(acc[ai][bj][2 * mp + 1][1][j]); }
; #pragma unroll
;                     for (int j = 0; j < 8; ++j) { float x = __builtin_amdgcn_logf(fa[j]) * 0.6931471805599453f, y = __builtin_amdgcn_logf(fb[j]) * 0.6931471805599453f;
;                         if (dir == 0) { x += dpp_f<0x111>(x); x += dpp_f<0x112>(x); x += dpp_f<0x114>(x); x += dpp_f<0x118>(x);
;                                         y += dpp_f<0x111>(y); y += dpp_f<0x112>(y); y += dpp_f<0x114>(y); y += dpp_f<0x118>(y);
;                                         y += __shfl(x, (lane_ & 48) | 15); }
;                         else { x += dpp_f<0x101>(x); x += dpp_f<0x102>(x); x += dpp_f<0x104>(x); x += dpp_f<0x108>(x);
;                                y += dpp_f<0x101>(y); y += dpp_f<0x102>(y); y += dpp_f<0x104>(y); y += dpp_f<0x108>(y);
;                                x += __shfl(y, lane_ & 48); }
;                         xa[j] = x; xb[j] = y; }
.LBB0_2165:
	s_andn2_b64 vcc, exec, s[14:15]
	s_cbranch_vccnz .LBB0_2167
	v_add_f32_dpp v81, v81, v81 row_shr:1 row_mask:0xf bank_mask:0xf bound_ctrl:1
	v_add_f32_dpp v80, v80, v80 row_shr:1 row_mask:0xf bank_mask:0xf bound_ctrl:1
	s_nop 0
	v_add_f32_dpp v81, v81, v81 row_shr:2 row_mask:0xf bank_mask:0xf bound_ctrl:1
	v_add_f32_dpp v80, v80, v80 row_shr:2 row_mask:0xf bank_mask:0xf bound_ctrl:1
	s_nop 0
	v_add_f32_dpp v81, v81, v81 row_shr:4 row_mask:0xf bank_mask:0xf bound_ctrl:1
	v_add_f32_dpp v80, v80, v80 row_shr:4 row_mask:0xf bank_mask:0xf bound_ctrl:1
	s_nop 0
	v_add_f32_dpp v100, v81, v81 row_shr:8 row_mask:0xf bank_mask:0xf bound_ctrl:1
	s_nop 0
	s_nop 0
	s_nop 0
	v_add_f32_dpp v80, v80, v80 row_shr:8 row_mask:0xf bank_mask:0xf bound_ctrl:1
	s_waitcnt lgkmcnt(0)
	s_nop 1
	v_add_f32_dpp v92, v100, v80 row_newbcast:15 row_mask:0xf bank_mask:0xf
.LBB0_2167:
	v_log_f32_e32 v80, v79
	v_log_f32_e32 v82, v75
	s_and_b64 vcc, exec, s[4:5]
	s_mov_b64 s[14:15], -1
	v_mul_f32_e32 v81, 0x3f317218, v80
	v_mul_f32_e32 v80, 0x3f317218, v82
	s_cbranch_vccnz .LBB0_2169
	s_nop 0
	v_add_f32_dpp v82, v80, v80 row_shl:1 row_mask:0xf bank_mask:0xf bound_ctrl:1
	v_add_f32_dpp v83, v81, v81 row_shl:1 row_mask:0xf bank_mask:0xf bound_ctrl:1
	s_mov_b64 s[14:15], 0
	v_add_f32_dpp v82, v82, v82 row_shl:2 row_mask:0xf bank_mask:0xf bound_ctrl:1
	v_add_f32_dpp v83, v83, v83 row_shl:2 row_mask:0xf bank_mask:0xf bound_ctrl:1
	s_nop 0
	v_add_f32_dpp v82, v82, v82 row_shl:4 row_mask:0xf bank_mask:0xf bound_ctrl:1
	v_add_f32_dpp v83, v83, v83 row_shl:4 row_mask:0xf bank_mask:0xf bound_ctrl:1
	s_nop 0
	v_add_f32_dpp v94, v82, v82 row_shl:8 row_mask:0xf bank_mask:0xf bound_ctrl:1
	s_nop 0
	s_nop 0
	s_nop 0
	v_add_f32_dpp v83, v83, v83 row_shl:8 row_mask:0xf bank_mask:0xf bound_ctrl:1
	s_waitcnt lgkmcnt(0)
	s_nop 1
	v_add_f32_dpp v101, v94, v83 row_newbcast:0 row_mask:0xf bank_mask:0xf
.LBB0_2169:
	s_andn2_b64 vcc, exec, s[14:15]
	s_cbranch_vccnz .LBB0_2171
	v_add_f32_dpp v81, v81, v81 row_shr:1 row_mask:0xf bank_mask:0xf bound_ctrl:1
	v_add_f32_dpp v80, v80, v80 row_shr:1 row_mask:0xf bank_mask:0xf bound_ctrl:1
	s_nop 0
	v_add_f32_dpp v81, v81, v81 row_shr:2 row_mask:0xf bank_mask:0xf bound_ctrl:1
	v_add_f32_dpp v80, v80, v80 row_shr:2 row_mask:0xf bank_mask:0xf bound_ctrl:1
	s_nop 0
	v_add_f32_dpp v81, v81, v81 row_shr:4 row_mask:0xf bank_mask:0xf bound_ctrl:1
	v_add_f32_dpp v80, v80, v80 row_shr:4 row_mask:0xf bank_mask:0xf bound_ctrl:1
	s_nop 0
	v_add_f32_dpp v101, v81, v81 row_shr:8 row_mask:0xf bank_mask:0xf bound_ctrl:1
	s_nop 0
	s_nop 0
	s_nop 0
	v_add_f32_dpp v80, v80, v80 row_shr:8 row_mask:0xf bank_mask:0xf bound_ctrl:1
	s_waitcnt lgkmcnt(0)
	s_nop 1
	v_add_f32_dpp v94, v101, v80 row_newbcast:15 row_mask:0xf bank_mask:0xf
.LBB0_2171:
	v_mul_f32_e32 v68, 0xbfb8aa3b, v68
	v_exp_f32_e32 v68, v68
	v_mul_f32_e32 v64, 0xbfb8aa3b, v64
	v_exp_f32_e32 v64, v64
	v_mul_f32_e32 v65, 0xbfb8aa3b, v65
	v_add_f32_e32 v68, 1.0, v68
	v_exp_f32_e32 v81, v65
	v_add_f32_e32 v80, 1.0, v64
	v_rcp_f32_e32 v64, v68
	v_mul_f32_e32 v68, 0xbfb8aa3b, v69
	v_exp_f32_e32 v69, v68
	v_rcp_f32_e32 v68, v80
	s_and_b64 vcc, exec, s[4:5]
	s_mov_b64 s[14:15], -1
	v_add_f32_e32 v65, 1.0, v69
	v_add_f32_e32 v69, 1.0, v81
	v_rcp_f32_e32 v65, v65
	v_rcp_f32_e32 v69, v69
	v_pk_fma_f32 v[84:85], v[64:65], v[134:135], v[96:97]
	v_pk_fma_f32 v[80:81], v[68:69], v[134:135], v[96:97]
	v_log_f32_e32 v64, v84
	v_log_f32_e32 v65, v80
	v_mul_f32_e32 v68, 0x3f317218, v64
	v_mul_f32_e32 v64, 0x3f317218, v65
	s_cbranch_vccnz .LBB0_2173
	s_nop 0
	v_add_f32_dpp v65, v64, v64 row_shl:1 row_mask:0xf bank_mask:0xf bound_ctrl:1
	v_add_f32_dpp v69, v68, v68 row_shl:1 row_mask:0xf bank_mask:0xf bound_ctrl:1
	s_mov_b64 s[14:15], 0
	v_add_f32_dpp v65, v65, v65 row_shl:2 row_mask:0xf bank_mask:0xf bound_ctrl:1
	v_add_f32_dpp v69, v69, v69 row_shl:2 row_mask:0xf bank_mask:0xf bound_ctrl:1
	s_nop 0
	v_add_f32_dpp v65, v65, v65 row_shl:4 row_mask:0xf bank_mask:0xf bound_ctrl:1
	v_add_f32_dpp v69, v69, v69 row_shl:4 row_mask:0xf bank_mask:0xf bound_ctrl:1
	s_nop 0
	v_add_f32_dpp v96, v65, v65 row_shl:8 row_mask:0xf bank_mask:0xf bound_ctrl:1
	s_nop 0
	s_nop 0
	s_nop 0
	v_add_f32_dpp v69, v69, v69 row_shl:8 row_mask:0xf bank_mask:0xf bound_ctrl:1
	s_waitcnt lgkmcnt(0)
	s_nop 1
	v_add_f32_dpp v65, v96, v69 row_newbcast:0 row_mask:0xf bank_mask:0xf
.LBB0_2173:
	s_andn2_b64 vcc, exec, s[14:15]
	s_cbranch_vccnz .LBB0_2175
	v_add_f32_dpp v65, v68, v68 row_shr:1 row_mask:0xf bank_mask:0xf bound_ctrl:1
	s_nop 0
	s_nop 0
	v_add_f32_dpp v65, v65, v65 row_shr:2 row_mask:0xf bank_mask:0xf bound_ctrl:1
	v_add_f32_dpp v64, v64, v64 row_shr:1 row_mask:0xf bank_mask:0xf bound_ctrl:1
	s_nop 0
	v_add_f32_dpp v65, v65, v65 row_shr:4 row_mask:0xf bank_mask:0xf bound_ctrl:1
	v_add_f32_dpp v64, v64, v64 row_shr:2 row_mask:0xf bank_mask:0xf bound_ctrl:1
	s_nop 0
	v_add_f32_dpp v65, v65, v65 row_shr:8 row_mask:0xf bank_mask:0xf bound_ctrl:1
	s_nop 0
	v_add_f32_dpp v64, v64, v64 row_shr:4 row_mask:0xf bank_mask:0xf bound_ctrl:1
	s_nop 1
	v_add_f32_dpp v64, v64, v64 row_shr:8 row_mask:0xf bank_mask:0xf bound_ctrl:1
	s_waitcnt lgkmcnt(0)
	s_nop 1
	v_add_f32_dpp v96, v65, v64 row_newbcast:15 row_mask:0xf bank_mask:0xf
; DI float sigmoid_f(float x) { return __builtin_amdgcn_rcpf(1.f + __expf(-x)); }
; template <int CTRL> DI float dpp_f(float x) { return __int_as_float(__builtin_amdgcn_update_dpp(0, __float_as_int(x), CTRL, 0xF, 0xF, true)); }
;     DI void operator()(const AccT& acc, int brow, int bcol, int wr, int wc, int fr, int fq) const {
;     ...
;                     for (int j = 0; j < 4; ++j) { fa[j] = lb0[j] + (1.f - lb0[j]) * sigmoid_f(acc[ai][bj][2 * mp][0][j]); fa[4 + j] = lb1[j] + (1.f - lb1[j]) * sigmoid_f(acc[ai][bj][2 * mp][1][j]);
;                                                   fb[j] = lb0[j] + (1.f - lb0[j]) * sigmoid_f(acc[ai][bj][2 * mp + 1][0][j]); fb[4 + j] = lb1[j] + (1.f - lb1[j]) * sigmoid_f(acc[ai][bj][2 * mp + 1][1][j]); }
; #pragma unroll
;                     for (int j = 0; j < 8; ++j) { float x = __builtin_amdgcn_logf(fa[j]) * 0.6931471805599453f, y = __builtin_amdgcn_logf(fb[j]) * 0.6931471805599453f;
;                         if (dir == 0) { x += dpp_f<0x111>(x); x += dpp_f<0x112>(x); x += dpp_f<0x114>(x); x += dpp_f<0x118>(x);
;                                         y += dpp_f<0x111>(y); y += dpp_f<0x112>(y); y += dpp_f<0x114>(y); y += dpp_f<0x118>(y);
;                                         y += __shfl(x, (lane_ & 48) | 15); }
;                         else { x += dpp_f<0x101>(x); x += dpp_f<0x102>(x); x += dpp_f<0x104>(x); x += dpp_f<0x108>(x);
;                                y += dpp_f<0x101>(y); y += dpp_f<0x102>(y); y += dpp_f<0x104>(y); y += dpp_f<0x108>(y);
;                                x += __shfl(y, lane_ & 48); }
;                         xa[j] = x; xb[j] = y; }
.LBB0_2175:
	v_log_f32_e32 v64, v85
	v_log_f32_e32 v69, v81
	s_and_b64 vcc, exec, s[4:5]
	s_mov_b64 s[14:15], -1
	v_mul_f32_e32 v68, 0x3f317218, v64
	v_mul_f32_e32 v64, 0x3f317218, v69
	s_cbranch_vccnz .LBB0_2177
	s_nop 0
	v_add_f32_dpp v69, v64, v64 row_shl:1 row_mask:0xf bank_mask:0xf bound_ctrl:1
	v_add_f32_dpp v82, v68, v68 row_shl:1 row_mask:0xf bank_mask:0xf bound_ctrl:1
	s_mov_b64 s[14:15], 0
	v_add_f32_dpp v69, v69, v69 row_shl:2 row_mask:0xf bank_mask:0xf bound_ctrl:1
	v_add_f32_dpp v82, v82, v82 row_shl:2 row_mask:0xf bank_mask:0xf bound_ctrl:1
	s_nop 0
	v_add_f32_dpp v69, v69, v69 row_shl:4 row_mask:0xf bank_mask:0xf bound_ctrl:1
	v_add_f32_dpp v82, v82, v82 row_shl:4 row_mask:0xf bank_mask:0xf bound_ctrl:1
	s_nop 0
	v_add_f32_dpp v97, v69, v69 row_shl:8 row_mask:0xf bank_mask:0xf bound_ctrl:1
	s_nop 0
	s_nop 0
	s_nop 0
	v_add_f32_dpp v82, v82, v82 row_shl:8 row_mask:0xf bank_mask:0xf bound_ctrl:1
	s_waitcnt lgkmcnt(0)
	s_nop 1
	v_add_f32_dpp v69, v97, v82 row_newbcast:0 row_mask:0xf bank_mask:0xf
.LBB0_2177:
	s_andn2_b64 vcc, exec, s[14:15]
	s_cbranch_vccnz .LBB0_2179
	v_add_f32_dpp v68, v68, v68 row_shr:1 row_mask:0xf bank_mask:0xf bound_ctrl:1
	v_add_f32_dpp v64, v64, v64 row_shr:1 row_mask:0xf bank_mask:0xf bound_ctrl:1
	s_nop 0
	v_add_f32_dpp v68, v68, v68 row_shr:2 row_mask:0xf bank_mask:0xf bound_ctrl:1
	v_add_f32_dpp v64, v64, v64 row_shr:2 row_mask:0xf bank_mask:0xf bound_ctrl:1
	s_nop 0
	v_add_f32_dpp v68, v68, v68 row_shr:4 row_mask:0xf bank_mask:0xf bound_ctrl:1
	v_add_f32_dpp v64, v64, v64 row_shr:4 row_mask:0xf bank_mask:0xf bound_ctrl:1
	s_nop 0
	v_add_f32_dpp v69, v68, v68 row_shr:8 row_mask:0xf bank_mask:0xf bound_ctrl:1
	s_nop 0
	s_nop 0
	s_nop 0
	v_add_f32_dpp v64, v64, v64 row_shr:8 row_mask:0xf bank_mask:0xf bound_ctrl:1
	s_waitcnt lgkmcnt(0)
	s_nop 1
	v_add_f32_dpp v97, v69, v64 row_newbcast:15 row_mask:0xf bank_mask:0xf
.LBB0_2179:
	v_mul_f32_e32 v64, 0xbfb8aa3b, v70
	v_exp_f32_e32 v64, v64
	v_mul_f32_e32 v66, 0xbfb8aa3b, v66
	v_exp_f32_e32 v66, v66
	v_mul_f32_e32 v67, 0xbfb8aa3b, v67
	v_add_f32_e32 v64, 1.0, v64
	s_and_b64 vcc, exec, s[4:5]
	v_add_f32_e32 v68, 1.0, v66
	v_rcp_f32_e32 v66, v64
	v_mul_f32_e32 v64, 0xbfb8aa3b, v71
	v_exp_f32_e32 v64, v64
	v_exp_f32_e32 v71, v67
	v_rcp_f32_e32 v70, v68
	s_mov_b64 s[14:15], -1
	v_add_f32_e32 v64, 1.0, v64
	v_rcp_f32_e32 v67, v64
	v_add_f32_e32 v64, 1.0, v71
	v_rcp_f32_e32 v71, v64
	v_pk_fma_f32 v[86:87], v[66:67], v[154:155], v[98:99]
	s_nop 0
	v_log_f32_e32 v64, v86
	v_pk_fma_f32 v[82:83], v[70:71], v[154:155], v[98:99]
	v_mul_f32_e32 v66, 0x3f317218, v64
	v_log_f32_e32 v67, v82
	s_nop 0
	v_mul_f32_e32 v64, 0x3f317218, v67
	s_cbranch_vccnz .LBB0_2181
	s_nop 0
	v_add_f32_dpp v67, v64, v64 row_shl:1 row_mask:0xf bank_mask:0xf bound_ctrl:1
	v_add_f32_dpp v68, v66, v66 row_shl:1 row_mask:0xf bank_mask:0xf bound_ctrl:1
	s_mov_b64 s[14:15], 0
	v_add_f32_dpp v67, v67, v67 row_shl:2 row_mask:0xf bank_mask:0xf bound_ctrl:1
	v_add_f32_dpp v68, v68, v68 row_shl:2 row_mask:0xf bank_mask:0xf bound_ctrl:1
	s_nop 0
	v_add_f32_dpp v67, v67, v67 row_shl:4 row_mask:0xf bank_mask:0xf bound_ctrl:1
	v_add_f32_dpp v68, v68, v68 row_shl:4 row_mask:0xf bank_mask:0xf bound_ctrl:1
	s_nop 0
	v_add_f32_dpp v98, v67, v67 row_shl:8 row_mask:0xf bank_mask:0xf bound_ctrl:1
	s_nop 0
	s_nop 0
	s_nop 0
	v_add_f32_dpp v68, v68, v68 row_shl:8 row_mask:0xf bank_mask:0xf bound_ctrl:1
	s_waitcnt lgkmcnt(0)
	s_nop 1
	v_add_f32_dpp v67, v98, v68 row_newbcast:0 row_mask:0xf bank_mask:0xf
.LBB0_2181:
	s_andn2_b64 vcc, exec, s[14:15]
	s_cbranch_vccnz .LBB0_2183
	v_add_f32_dpp v66, v66, v66 row_shr:1 row_mask:0xf bank_mask:0xf bound_ctrl:1
	v_add_f32_dpp v64, v64, v64 row_shr:1 row_mask:0xf bank_mask:0xf bound_ctrl:1
	s_nop 0
	v_add_f32_dpp v66, v66, v66 row_shr:2 row_mask:0xf bank_mask:0xf bound_ctrl:1
	v_add_f32_dpp v64, v64, v64 row_shr:2 row_mask:0xf bank_mask:0xf bound_ctrl:1
	s_nop 0
	v_add_f32_dpp v66, v66, v66 row_shr:4 row_mask:0xf bank_mask:0xf bound_ctrl:1
	v_add_f32_dpp v64, v64, v64 row_shr:4 row_mask:0xf bank_mask:0xf bound_ctrl:1
	s_nop 0
	v_add_f32_dpp v67, v66, v66 row_shr:8 row_mask:0xf bank_mask:0xf bound_ctrl:1
	s_nop 0
	s_nop 0
	s_nop 0
	v_add_f32_dpp v64, v64, v64 row_shr:8 row_mask:0xf bank_mask:0xf bound_ctrl:1
	s_waitcnt lgkmcnt(0)
	s_nop 1
	v_add_f32_dpp v98, v67, v64 row_newbcast:15 row_mask:0xf bank_mask:0xf
.LBB0_2183:
	v_log_f32_e32 v64, v87
	v_log_f32_e32 v68, v83
	s_and_b64 vcc, exec, s[4:5]
	s_mov_b64 s[4:5], -1
	v_mul_f32_e32 v66, 0x3f317218, v64
	v_mul_f32_e32 v64, 0x3f317218, v68
	s_cbranch_vccnz .LBB0_2185
	s_nop 0
	v_add_f32_dpp v68, v64, v64 row_shl:1 row_mask:0xf bank_mask:0xf bound_ctrl:1
	v_add_f32_dpp v70, v66, v66 row_shl:1 row_mask:0xf bank_mask:0xf bound_ctrl:1
	s_mov_b64 s[4:5], 0
	v_add_f32_dpp v68, v68, v68 row_shl:2 row_mask:0xf bank_mask:0xf bound_ctrl:1
	v_add_f32_dpp v70, v70, v70 row_shl:2 row_mask:0xf bank_mask:0xf bound_ctrl:1
	s_nop 0
	v_add_f32_dpp v68, v68, v68 row_shl:4 row_mask:0xf bank_mask:0xf bound_ctrl:1
	v_add_f32_dpp v70, v70, v70 row_shl:4 row_mask:0xf bank_mask:0xf bound_ctrl:1
	s_nop 0
	v_add_f32_dpp v99, v68, v68 row_shl:8 row_mask:0xf bank_mask:0xf bound_ctrl:1
	s_nop 0
	s_nop 0
	s_nop 0
	v_add_f32_dpp v70, v70, v70 row_shl:8 row_mask:0xf bank_mask:0xf bound_ctrl:1
	s_waitcnt lgkmcnt(0)
	s_nop 1
	v_add_f32_dpp v71, v99, v70 row_newbcast:0 row_mask:0xf bank_mask:0xf
.LBB0_2185:
	s_andn2_b64 vcc, exec, s[4:5]
	s_cbranch_vccnz .LBB0_2187
	v_add_f32_dpp v66, v66, v66 row_shr:1 row_mask:0xf bank_mask:0xf bound_ctrl:1
	v_add_f32_dpp v64, v64, v64 row_shr:1 row_mask:0xf bank_mask:0xf bound_ctrl:1
	s_nop 0
	v_add_f32_dpp v66, v66, v66 row_shr:2 row_mask:0xf bank_mask:0xf bound_ctrl:1
	v_add_f32_dpp v64, v64, v64 row_shr:2 row_mask:0xf bank_mask:0xf bound_ctrl:1
	s_nop 0
	v_add_f32_dpp v66, v66, v66 row_shr:4 row_mask:0xf bank_mask:0xf bound_ctrl:1
	v_add_f32_dpp v64, v64, v64 row_shr:4 row_mask:0xf bank_mask:0xf bound_ctrl:1
	s_nop 0
	v_add_f32_dpp v71, v66, v66 row_shr:8 row_mask:0xf bank_mask:0xf bound_ctrl:1
	s_nop 0
	s_nop 0
	s_nop 0
	v_add_f32_dpp v64, v64, v64 row_shr:8 row_mask:0xf bank_mask:0xf bound_ctrl:1
	s_waitcnt lgkmcnt(0)
	s_nop 1
	v_add_f32_dpp v99, v71, v64 row_newbcast:15 row_mask:0xf bank_mask:0xf

; DI float sigmoid_f(float x) { return __builtin_amdgcn_rcpf(1.f + __expf(-x)); }
; #define EPI_LOOP_BJ _Pragma("unroll") for (int bj = 0; bj < 2; ++bj)
;     DI void operator()(const AccT& acc, int brow, int bcol, int wr, int wc, int fr, int fq) const {
;     ...
;         EPI_LOOP_BJ { const int col = cb + bj * 128 + wc * 32 + fq * 8;
;             if (seg == 1 || seg == 2) {
;                 const int dir = seg - 1;
;                 const f32x4 lb0 = *(const f32x4*)(lbv + dir * 1024 + col), lb1 = *(const f32x4*)(lbv + dir * 1024 + col + 4);
;                 bf16_t* EK = (bf16_t*)(P + (dir ? P_HF1 : P_HF0)); float* EBp = (float*)(ebase);
;                 const int lane_ = fq * 16 + fr;
; #pragma unroll
;                 for (int ai = 0; ai < 2; ++ai)
; #pragma unroll
;                 for (int mp = 0; mp < 2; ++mp) {
;                     const size_t row0 = brow + ai * 128 + wr * 64 + mp * 32 + fr, row1 = row0 + 16;
;                     float fa[8], fb[8], xa[8], xb[8];
; #pragma unroll
;                     for (int j = 0; j < 4; ++j) { fa[j] = lb0[j] + (1.f - lb0[j]) * sigmoid_f(acc[ai][bj][2 * mp][0][j]); fa[4 + j] = lb1[j] + (1.f - lb1[j]) * sigmoid_f(acc[ai][bj][2 * mp][1][j]);
;                                                   fb[j] = lb0[j] + (1.f - lb0[j]) * sigmoid_f(acc[ai][bj][2 * mp + 1][0][j]); fb[4 + j] = lb1[j] + (1.f - lb1[j]) * sigmoid_f(acc[ai][bj][2 * mp + 1][1][j]); }
; #pragma unroll
;                     for (int j = 0; j < 8; ++j) { float x = __builtin_amdgcn_logf(fa[j]) * 0.6931471805599453f, y = __builtin_amdgcn_logf(fb[j]) * 0.6931471805599453f;
;                         if (dir == 0) { x += dpp_f<0x111>(x); x += dpp_f<0x112>(x); x += dpp_f<0x114>(x); x += dpp_f<0x118>(x);
;                                         y += dpp_f<0x111>(y); y += dpp_f<0x112>(y); y += dpp_f<0x114>(y); y += dpp_f<0x118>(y);
;                                         y += __shfl(x, (lane_ & 48) | 15); }
;                         else { x += dpp_f<0x101>(x); x += dpp_f<0x102>(x); x += dpp_f<0x104>(x); x += dpp_f<0x108>(x);
;                                y += dpp_f<0x101>(y); y += dpp_f<0x102>(y); y += dpp_f<0x104>(y); y += dpp_f<0x108>(y);
;                                x += __shfl(y, lane_ & 48); }
;                         xa[j] = x; xb[j] = y; }
.LBB0_2209:
	s_lshl_b64 s[2:3], s[0:1], 2
	v_readlane_b32 s4, v254, 39
	v_readlane_b32 s5, v254, 40
	s_add_u32 s2, s4, s2
	s_addc_u32 s3, s5, s3
	global_load_dwordx4 v[68:71], v152, s[2:3] offset:512
	global_load_dwordx4 v[64:67], v152, s[2:3] offset:528
	v_mul_f32_e32 v60, 0xbfb8aa3b, v60
	v_mul_f32_e32 v56, 0xbfb8aa3b, v56
	v_mul_f32_e32 v61, 0xbfb8aa3b, v61
	v_mul_f32_e32 v57, 0xbfb8aa3b, v57
	v_exp_f32_e32 v60, v60
	v_exp_f32_e32 v56, v56
	v_exp_f32_e32 v61, v61
	v_exp_f32_e32 v57, v57
	v_add_f32_e32 v60, 1.0, v60
	v_add_f32_e32 v72, 1.0, v56
	v_add_f32_e32 v61, 1.0, v61
	v_add_f32_e32 v73, 1.0, v57
	v_rcp_f32_e32 v56, v60
	v_rcp_f32_e32 v72, v72
	v_rcp_f32_e32 v57, v61
	v_rcp_f32_e32 v73, v73
	v_cndmask_b32_e64 v76, 0, 1, s[54:55]
	v_cmp_ne_u32_e64 s[2:3], 1, v76
	s_andn2_b64 vcc, exec, s[54:55]
	s_mov_b64 s[4:5], -1
	s_waitcnt vmcnt(0)
	v_pk_add_f32 v[60:61], v[68:69], 1.0 op_sel_hi:[1,0] neg_lo:[1,0] neg_hi:[1,0]
	s_nop 0
	v_pk_fma_f32 v[56:57], v[56:57], v[60:61], v[68:69]
	v_pk_fma_f32 v[74:75], v[72:73], v[60:61], v[68:69]
	v_log_f32_e32 v72, v56
	v_log_f32_e32 v77, v74
	v_mul_f32_e32 v73, 0x3f317218, v72
	v_mul_f32_e32 v72, 0x3f317218, v77
	s_cbranch_vccnz .LBB0_2211
	s_nop 0
	v_add_f32_dpp v76, v72, v72 row_shl:1 row_mask:0xf bank_mask:0xf bound_ctrl:1
	v_add_f32_dpp v77, v73, v73 row_shl:1 row_mask:0xf bank_mask:0xf bound_ctrl:1
	s_mov_b64 s[4:5], 0
	v_add_f32_dpp v76, v76, v76 row_shl:2 row_mask:0xf bank_mask:0xf bound_ctrl:1
	v_add_f32_dpp v77, v77, v77 row_shl:2 row_mask:0xf bank_mask:0xf bound_ctrl:1
	s_nop 0
	v_add_f32_dpp v76, v76, v76 row_shl:4 row_mask:0xf bank_mask:0xf bound_ctrl:1
	v_add_f32_dpp v77, v77, v77 row_shl:4 row_mask:0xf bank_mask:0xf bound_ctrl:1
	s_nop 0
	v_add_f32_dpp v88, v76, v76 row_shl:8 row_mask:0xf bank_mask:0xf bound_ctrl:1
	s_nop 0
	s_nop 0
	s_nop 0
	v_add_f32_dpp v77, v77, v77 row_shl:8 row_mask:0xf bank_mask:0xf bound_ctrl:1
	s_waitcnt lgkmcnt(0)
	s_nop 1
	v_add_f32_dpp v91, v88, v77 row_newbcast:0 row_mask:0xf bank_mask:0xf
.LBB0_2211:
	s_andn2_b64 vcc, exec, s[4:5]
	s_cbranch_vccnz .LBB0_2213
	v_add_f32_dpp v73, v73, v73 row_shr:1 row_mask:0xf bank_mask:0xf bound_ctrl:1
	v_add_f32_dpp v72, v72, v72 row_shr:1 row_mask:0xf bank_mask:0xf bound_ctrl:1
	s_nop 0
	v_add_f32_dpp v73, v73, v73 row_shr:2 row_mask:0xf bank_mask:0xf bound_ctrl:1
	v_add_f32_dpp v72, v72, v72 row_shr:2 row_mask:0xf bank_mask:0xf bound_ctrl:1
	s_nop 0
	v_add_f32_dpp v73, v73, v73 row_shr:4 row_mask:0xf bank_mask:0xf bound_ctrl:1
	v_add_f32_dpp v72, v72, v72 row_shr:4 row_mask:0xf bank_mask:0xf bound_ctrl:1
	s_nop 0
	v_add_f32_dpp v91, v73, v73 row_shr:8 row_mask:0xf bank_mask:0xf bound_ctrl:1
	s_nop 0
	s_nop 0
	s_nop 0
	v_add_f32_dpp v72, v72, v72 row_shr:8 row_mask:0xf bank_mask:0xf bound_ctrl:1
	s_waitcnt lgkmcnt(0)
	s_nop 1
	v_add_f32_dpp v88, v91, v72 row_newbcast:15 row_mask:0xf bank_mask:0xf
.LBB0_2213:
	v_log_f32_e32 v72, v57
	v_log_f32_e32 v76, v75
	s_and_b64 vcc, exec, s[2:3]
	s_mov_b64 s[4:5], -1
	v_mul_f32_e32 v73, 0x3f317218, v72
	v_mul_f32_e32 v72, 0x3f317218, v76
	s_cbranch_vccnz .LBB0_2215
	s_nop 0
	v_add_f32_dpp v76, v72, v72 row_shl:1 row_mask:0xf bank_mask:0xf bound_ctrl:1
	v_add_f32_dpp v77, v73, v73 row_shl:1 row_mask:0xf bank_mask:0xf bound_ctrl:1
	s_mov_b64 s[4:5], 0
	v_add_f32_dpp v76, v76, v76 row_shl:2 row_mask:0xf bank_mask:0xf bound_ctrl:1
	v_add_f32_dpp v77, v77, v77 row_shl:2 row_mask:0xf bank_mask:0xf bound_ctrl:1
	s_nop 0
	v_add_f32_dpp v76, v76, v76 row_shl:4 row_mask:0xf bank_mask:0xf bound_ctrl:1
	v_add_f32_dpp v77, v77, v77 row_shl:4 row_mask:0xf bank_mask:0xf bound_ctrl:1
	s_nop 0
	v_add_f32_dpp v89, v76, v76 row_shl:8 row_mask:0xf bank_mask:0xf bound_ctrl:1
	s_nop 0
	s_nop 0
	s_nop 0
	v_add_f32_dpp v77, v77, v77 row_shl:8 row_mask:0xf bank_mask:0xf bound_ctrl:1
	s_waitcnt lgkmcnt(0)
	s_nop 1
	v_add_f32_dpp v93, v89, v77 row_newbcast:0 row_mask:0xf bank_mask:0xf
.LBB0_2215:
	s_andn2_b64 vcc, exec, s[4:5]
	s_cbranch_vccnz .LBB0_2217
	v_add_f32_dpp v73, v73, v73 row_shr:1 row_mask:0xf bank_mask:0xf bound_ctrl:1
	v_add_f32_dpp v72, v72, v72 row_shr:1 row_mask:0xf bank_mask:0xf bound_ctrl:1
	s_nop 0
	v_add_f32_dpp v73, v73, v73 row_shr:2 row_mask:0xf bank_mask:0xf bound_ctrl:1
	v_add_f32_dpp v72, v72, v72 row_shr:2 row_mask:0xf bank_mask:0xf bound_ctrl:1
	s_nop 0
	v_add_f32_dpp v73, v73, v73 row_shr:4 row_mask:0xf bank_mask:0xf bound_ctrl:1
	v_add_f32_dpp v72, v72, v72 row_shr:4 row_mask:0xf bank_mask:0xf bound_ctrl:1
	s_nop 0
	v_add_f32_dpp v93, v73, v73 row_shr:8 row_mask:0xf bank_mask:0xf bound_ctrl:1
	s_nop 0
	s_nop 0
	s_nop 0
	v_add_f32_dpp v72, v72, v72 row_shr:8 row_mask:0xf bank_mask:0xf bound_ctrl:1
	s_waitcnt lgkmcnt(0)
	s_nop 1
	v_add_f32_dpp v89, v93, v72 row_newbcast:15 row_mask:0xf bank_mask:0xf
.LBB0_2217:
	v_mul_f32_e32 v58, 0xbfb8aa3b, v58
	v_exp_f32_e32 v58, v58
	v_mul_f32_e32 v63, 0xbfb8aa3b, v63
	v_mul_f32_e32 v62, 0xbfb8aa3b, v62
	v_exp_f32_e32 v63, v63
	v_mul_f32_e32 v59, 0xbfb8aa3b, v59
	v_exp_f32_e32 v62, v62
	v_exp_f32_e32 v59, v59
	v_add_f32_e32 v58, 1.0, v58
	v_rcp_f32_e32 v72, v58
	v_add_f32_e32 v58, 1.0, v63
	v_add_f32_e32 v62, 1.0, v62
	v_rcp_f32_e32 v63, v58
	v_add_f32_e32 v58, 1.0, v59
	v_rcp_f32_e32 v62, v62
	v_rcp_f32_e32 v73, v58
	v_pk_add_f32 v[58:59], v[70:71], 1.0 op_sel_hi:[1,0] neg_lo:[1,0] neg_hi:[1,0]
	s_and_b64 vcc, exec, s[2:3]
	v_pk_fma_f32 v[78:79], v[62:63], v[58:59], v[70:71]
	v_pk_fma_f32 v[76:77], v[72:73], v[58:59], v[70:71]
	v_log_f32_e32 v62, v78
	v_log_f32_e32 v72, v76
	s_mov_b64 s[4:5], -1
	v_mul_f32_e32 v63, 0x3f317218, v62
	v_mul_f32_e32 v62, 0x3f317218, v72
	s_cbranch_vccnz .LBB0_2219
	s_nop 0
	v_add_f32_dpp v72, v62, v62 row_shl:1 row_mask:0xf bank_mask:0xf bound_ctrl:1
	v_add_f32_dpp v73, v63, v63 row_shl:1 row_mask:0xf bank_mask:0xf bound_ctrl:1
	s_mov_b64 s[4:5], 0
	v_add_f32_dpp v72, v72, v72 row_shl:2 row_mask:0xf bank_mask:0xf bound_ctrl:1
	v_add_f32_dpp v73, v73, v73 row_shl:2 row_mask:0xf bank_mask:0xf bound_ctrl:1
	s_nop 0
	v_add_f32_dpp v72, v72, v72 row_shl:4 row_mask:0xf bank_mask:0xf bound_ctrl:1
	v_add_f32_dpp v73, v73, v73 row_shl:4 row_mask:0xf bank_mask:0xf bound_ctrl:1
	s_nop 0
	v_add_f32_dpp v90, v72, v72 row_shl:8 row_mask:0xf bank_mask:0xf bound_ctrl:1
	s_nop 0
	s_nop 0
	s_nop 0
	v_add_f32_dpp v73, v73, v73 row_shl:8 row_mask:0xf bank_mask:0xf bound_ctrl:1
	s_waitcnt lgkmcnt(0)
	s_nop 1
	v_add_f32_dpp v94, v90, v73 row_newbcast:0 row_mask:0xf bank_mask:0xf
; DI float sigmoid_f(float x) { return __builtin_amdgcn_rcpf(1.f + __expf(-x)); }
; template <int CTRL> DI float dpp_f(float x) { return __int_as_float(__builtin_amdgcn_update_dpp(0, __float_as_int(x), CTRL, 0xF, 0xF, true)); }
;     DI void operator()(const AccT& acc, int brow, int bcol, int wr, int wc, int fr, int fq) const {
;     ...
;                     for (int j = 0; j < 4; ++j) { fa[j] = lb0[j] + (1.f - lb0[j]) * sigmoid_f(acc[ai][bj][2 * mp][0][j]); fa[4 + j] = lb1[j] + (1.f - lb1[j]) * sigmoid_f(acc[ai][bj][2 * mp][1][j]);
;                                                   fb[j] = lb0[j] + (1.f - lb0[j]) * sigmoid_f(acc[ai][bj][2 * mp + 1][0][j]); fb[4 + j] = lb1[j] + (1.f - lb1[j]) * sigmoid_f(acc[ai][bj][2 * mp + 1][1][j]); }
; #pragma unroll
;                     for (int j = 0; j < 8; ++j) { float x = __builtin_amdgcn_logf(fa[j]) * 0.6931471805599453f, y = __builtin_amdgcn_logf(fb[j]) * 0.6931471805599453f;
;                         if (dir == 0) { x += dpp_f<0x111>(x); x += dpp_f<0x112>(x); x += dpp_f<0x114>(x); x += dpp_f<0x118>(x);
;                                         y += dpp_f<0x111>(y); y += dpp_f<0x112>(y); y += dpp_f<0x114>(y); y += dpp_f<0x118>(y);
;                                         y += __shfl(x, (lane_ & 48) | 15); }
;                         else { x += dpp_f<0x101>(x); x += dpp_f<0x102>(x); x += dpp_f<0x104>(x); x += dpp_f<0x108>(x);
;                                y += dpp_f<0x101>(y); y += dpp_f<0x102>(y); y += dpp_f<0x104>(y); y += dpp_f<0x108>(y);
;                                x += __shfl(y, lane_ & 48); }
;                         xa[j] = x; xb[j] = y; }
.LBB0_2219:
	s_andn2_b64 vcc, exec, s[4:5]
	s_cbranch_vccnz .LBB0_2221
	v_add_f32_dpp v63, v63, v63 row_shr:1 row_mask:0xf bank_mask:0xf bound_ctrl:1
	v_add_f32_dpp v62, v62, v62 row_shr:1 row_mask:0xf bank_mask:0xf bound_ctrl:1
	s_nop 0
	v_add_f32_dpp v63, v63, v63 row_shr:2 row_mask:0xf bank_mask:0xf bound_ctrl:1
	v_add_f32_dpp v62, v62, v62 row_shr:2 row_mask:0xf bank_mask:0xf bound_ctrl:1
	s_nop 0
	v_add_f32_dpp v63, v63, v63 row_shr:4 row_mask:0xf bank_mask:0xf bound_ctrl:1
	v_add_f32_dpp v62, v62, v62 row_shr:4 row_mask:0xf bank_mask:0xf bound_ctrl:1
	s_nop 0
	v_add_f32_dpp v94, v63, v63 row_shr:8 row_mask:0xf bank_mask:0xf bound_ctrl:1
	s_nop 0
	s_nop 0
	s_nop 0
	v_add_f32_dpp v62, v62, v62 row_shr:8 row_mask:0xf bank_mask:0xf bound_ctrl:1
	s_waitcnt lgkmcnt(0)
	s_nop 1
	v_add_f32_dpp v90, v94, v62 row_newbcast:15 row_mask:0xf bank_mask:0xf
.LBB0_2221:
	v_log_f32_e32 v62, v79
	v_log_f32_e32 v72, v77
	s_and_b64 vcc, exec, s[2:3]
	s_mov_b64 s[4:5], -1
	v_mul_f32_e32 v63, 0x3f317218, v62
	v_mul_f32_e32 v62, 0x3f317218, v72
	s_cbranch_vccnz .LBB0_2223
	s_nop 0
	v_add_f32_dpp v72, v62, v62 row_shl:1 row_mask:0xf bank_mask:0xf bound_ctrl:1
	v_add_f32_dpp v73, v63, v63 row_shl:1 row_mask:0xf bank_mask:0xf bound_ctrl:1
	s_mov_b64 s[4:5], 0
	v_add_f32_dpp v72, v72, v72 row_shl:2 row_mask:0xf bank_mask:0xf bound_ctrl:1
	v_add_f32_dpp v73, v73, v73 row_shl:2 row_mask:0xf bank_mask:0xf bound_ctrl:1
	s_nop 0
	v_add_f32_dpp v72, v72, v72 row_shl:4 row_mask:0xf bank_mask:0xf bound_ctrl:1
	v_add_f32_dpp v73, v73, v73 row_shl:4 row_mask:0xf bank_mask:0xf bound_ctrl:1
	s_nop 0
	v_add_f32_dpp v92, v72, v72 row_shl:8 row_mask:0xf bank_mask:0xf bound_ctrl:1
	s_nop 0
	s_nop 0
	s_nop 0
	v_add_f32_dpp v73, v73, v73 row_shl:8 row_mask:0xf bank_mask:0xf bound_ctrl:1
	s_waitcnt lgkmcnt(0)
	s_nop 1
	v_add_f32_dpp v95, v92, v73 row_newbcast:0 row_mask:0xf bank_mask:0xf
.LBB0_2223:
	s_andn2_b64 vcc, exec, s[4:5]
	s_cbranch_vccnz .LBB0_2225
	v_add_f32_dpp v63, v63, v63 row_shr:1 row_mask:0xf bank_mask:0xf bound_ctrl:1
	v_add_f32_dpp v62, v62, v62 row_shr:1 row_mask:0xf bank_mask:0xf bound_ctrl:1
	s_nop 0
	v_add_f32_dpp v63, v63, v63 row_shr:2 row_mask:0xf bank_mask:0xf bound_ctrl:1
	v_add_f32_dpp v62, v62, v62 row_shr:2 row_mask:0xf bank_mask:0xf bound_ctrl:1
	s_nop 0
	v_add_f32_dpp v63, v63, v63 row_shr:4 row_mask:0xf bank_mask:0xf bound_ctrl:1
	v_add_f32_dpp v62, v62, v62 row_shr:4 row_mask:0xf bank_mask:0xf bound_ctrl:1
	s_nop 0
	v_add_f32_dpp v95, v63, v63 row_shr:8 row_mask:0xf bank_mask:0xf bound_ctrl:1
	s_nop 0
	s_nop 0
	s_nop 0
	v_add_f32_dpp v62, v62, v62 row_shr:8 row_mask:0xf bank_mask:0xf bound_ctrl:1
	s_waitcnt lgkmcnt(0)
	s_nop 1
	v_add_f32_dpp v92, v95, v62 row_newbcast:15 row_mask:0xf bank_mask:0xf
.LBB0_2225:
	v_mul_f32_e32 v52, 0xbfb8aa3b, v52
	v_exp_f32_e32 v52, v52
	v_mul_f32_e32 v48, 0xbfb8aa3b, v48
	v_exp_f32_e32 v48, v48
	v_mul_f32_e32 v49, 0xbfb8aa3b, v49
	v_add_f32_e32 v52, 1.0, v52
	v_exp_f32_e32 v63, v49
	v_add_f32_e32 v62, 1.0, v48
	v_rcp_f32_e32 v48, v52
	v_mul_f32_e32 v52, 0xbfb8aa3b, v53
	v_exp_f32_e32 v53, v52
	v_rcp_f32_e32 v52, v62
	s_and_b64 vcc, exec, s[2:3]
	s_mov_b64 s[4:5], -1
	v_add_f32_e32 v49, 1.0, v53
	v_add_f32_e32 v53, 1.0, v63
	v_rcp_f32_e32 v49, v49
	v_rcp_f32_e32 v53, v53
	v_pk_add_f32 v[62:63], v[64:65], 1.0 op_sel_hi:[1,0] neg_lo:[1,0] neg_hi:[1,0]
	s_nop 0
	v_pk_fma_f32 v[84:85], v[48:49], v[62:63], v[64:65]
	v_pk_fma_f32 v[80:81], v[52:53], v[62:63], v[64:65]
	v_log_f32_e32 v48, v84
	v_log_f32_e32 v49, v80
	v_mul_f32_e32 v52, 0x3f317218, v48
	v_mul_f32_e32 v48, 0x3f317218, v49
	s_cbranch_vccnz .LBB0_2227
	s_nop 0
	v_add_f32_dpp v49, v48, v48 row_shl:1 row_mask:0xf bank_mask:0xf bound_ctrl:1
	v_add_f32_dpp v53, v52, v52 row_shl:1 row_mask:0xf bank_mask:0xf bound_ctrl:1
	s_mov_b64 s[4:5], 0
	v_add_f32_dpp v49, v49, v49 row_shl:2 row_mask:0xf bank_mask:0xf bound_ctrl:1
	v_add_f32_dpp v53, v53, v53 row_shl:2 row_mask:0xf bank_mask:0xf bound_ctrl:1
	s_nop 0
	v_add_f32_dpp v49, v49, v49 row_shl:4 row_mask:0xf bank_mask:0xf bound_ctrl:1
	v_add_f32_dpp v53, v53, v53 row_shl:4 row_mask:0xf bank_mask:0xf bound_ctrl:1
	s_nop 0
	v_add_f32_dpp v96, v49, v49 row_shl:8 row_mask:0xf bank_mask:0xf bound_ctrl:1
	s_nop 0
	s_nop 0
	s_nop 0
	v_add_f32_dpp v53, v53, v53 row_shl:8 row_mask:0xf bank_mask:0xf bound_ctrl:1
	s_waitcnt lgkmcnt(0)
	s_nop 1
	v_add_f32_dpp v49, v96, v53 row_newbcast:0 row_mask:0xf bank_mask:0xf
.LBB0_2227:
	s_andn2_b64 vcc, exec, s[4:5]
	s_cbranch_vccnz .LBB0_2229
	v_add_f32_dpp v49, v52, v52 row_shr:1 row_mask:0xf bank_mask:0xf bound_ctrl:1
	s_nop 0
	s_nop 0
	v_add_f32_dpp v49, v49, v49 row_shr:2 row_mask:0xf bank_mask:0xf bound_ctrl:1
	v_add_f32_dpp v48, v48, v48 row_shr:1 row_mask:0xf bank_mask:0xf bound_ctrl:1
	s_nop 0
	v_add_f32_dpp v49, v49, v49 row_shr:4 row_mask:0xf bank_mask:0xf bound_ctrl:1
	v_add_f32_dpp v48, v48, v48 row_shr:2 row_mask:0xf bank_mask:0xf bound_ctrl:1
	s_nop 0
	v_add_f32_dpp v49, v49, v49 row_shr:8 row_mask:0xf bank_mask:0xf bound_ctrl:1
	s_nop 0
	v_add_f32_dpp v48, v48, v48 row_shr:4 row_mask:0xf bank_mask:0xf bound_ctrl:1
	s_nop 1
	v_add_f32_dpp v48, v48, v48 row_shr:8 row_mask:0xf bank_mask:0xf bound_ctrl:1
	s_waitcnt lgkmcnt(0)
	s_nop 1
	v_add_f32_dpp v96, v49, v48 row_newbcast:15 row_mask:0xf bank_mask:0xf
; DI float sigmoid_f(float x) { return __builtin_amdgcn_rcpf(1.f + __expf(-x)); }
; template <int CTRL> DI float dpp_f(float x) { return __int_as_float(__builtin_amdgcn_update_dpp(0, __float_as_int(x), CTRL, 0xF, 0xF, true)); }
;     DI void operator()(const AccT& acc, int brow, int bcol, int wr, int wc, int fr, int fq) const {
;     ...
;                     for (int j = 0; j < 4; ++j) { fa[j] = lb0[j] + (1.f - lb0[j]) * sigmoid_f(acc[ai][bj][2 * mp][0][j]); fa[4 + j] = lb1[j] + (1.f - lb1[j]) * sigmoid_f(acc[ai][bj][2 * mp][1][j]);
;                                                   fb[j] = lb0[j] + (1.f - lb0[j]) * sigmoid_f(acc[ai][bj][2 * mp + 1][0][j]); fb[4 + j] = lb1[j] + (1.f - lb1[j]) * sigmoid_f(acc[ai][bj][2 * mp + 1][1][j]); }
; #pragma unroll
;                     for (int j = 0; j < 8; ++j) { float x = __builtin_amdgcn_logf(fa[j]) * 0.6931471805599453f, y = __builtin_amdgcn_logf(fb[j]) * 0.6931471805599453f;
;                         if (dir == 0) { x += dpp_f<0x111>(x); x += dpp_f<0x112>(x); x += dpp_f<0x114>(x); x += dpp_f<0x118>(x);
;                                         y += dpp_f<0x111>(y); y += dpp_f<0x112>(y); y += dpp_f<0x114>(y); y += dpp_f<0x118>(y);
;                                         y += __shfl(x, (lane_ & 48) | 15); }
;                         else { x += dpp_f<0x101>(x); x += dpp_f<0x102>(x); x += dpp_f<0x104>(x); x += dpp_f<0x108>(x);
;                                y += dpp_f<0x101>(y); y += dpp_f<0x102>(y); y += dpp_f<0x104>(y); y += dpp_f<0x108>(y);
;                                x += __shfl(y, lane_ & 48); }
;                         xa[j] = x; xb[j] = y; }
.LBB0_2229:
	v_log_f32_e32 v48, v85
	v_log_f32_e32 v53, v81
	s_and_b64 vcc, exec, s[2:3]
	s_mov_b64 s[4:5], -1
	v_mul_f32_e32 v52, 0x3f317218, v48
	v_mul_f32_e32 v48, 0x3f317218, v53
	s_cbranch_vccnz .LBB0_2231
	s_nop 0
	v_add_f32_dpp v53, v48, v48 row_shl:1 row_mask:0xf bank_mask:0xf bound_ctrl:1
	v_add_f32_dpp v72, v52, v52 row_shl:1 row_mask:0xf bank_mask:0xf bound_ctrl:1
	s_mov_b64 s[4:5], 0
	v_add_f32_dpp v53, v53, v53 row_shl:2 row_mask:0xf bank_mask:0xf bound_ctrl:1
	v_add_f32_dpp v72, v72, v72 row_shl:2 row_mask:0xf bank_mask:0xf bound_ctrl:1
	s_nop 0
	v_add_f32_dpp v53, v53, v53 row_shl:4 row_mask:0xf bank_mask:0xf bound_ctrl:1
	v_add_f32_dpp v72, v72, v72 row_shl:4 row_mask:0xf bank_mask:0xf bound_ctrl:1
	s_nop 0
	v_add_f32_dpp v97, v53, v53 row_shl:8 row_mask:0xf bank_mask:0xf bound_ctrl:1
	s_nop 0
	s_nop 0
	s_nop 0
	v_add_f32_dpp v72, v72, v72 row_shl:8 row_mask:0xf bank_mask:0xf bound_ctrl:1
	s_waitcnt lgkmcnt(0)
	s_nop 1
	v_add_f32_dpp v53, v97, v72 row_newbcast:0 row_mask:0xf bank_mask:0xf
.LBB0_2231:
	s_andn2_b64 vcc, exec, s[4:5]
	s_cbranch_vccnz .LBB0_2233
	v_add_f32_dpp v52, v52, v52 row_shr:1 row_mask:0xf bank_mask:0xf bound_ctrl:1
	v_add_f32_dpp v48, v48, v48 row_shr:1 row_mask:0xf bank_mask:0xf bound_ctrl:1
	s_nop 0
	v_add_f32_dpp v52, v52, v52 row_shr:2 row_mask:0xf bank_mask:0xf bound_ctrl:1
	v_add_f32_dpp v48, v48, v48 row_shr:2 row_mask:0xf bank_mask:0xf bound_ctrl:1
	s_nop 0
	v_add_f32_dpp v52, v52, v52 row_shr:4 row_mask:0xf bank_mask:0xf bound_ctrl:1
	v_add_f32_dpp v48, v48, v48 row_shr:4 row_mask:0xf bank_mask:0xf bound_ctrl:1
	s_nop 0
	v_add_f32_dpp v53, v52, v52 row_shr:8 row_mask:0xf bank_mask:0xf bound_ctrl:1
	s_nop 0
	s_nop 0
	s_nop 0
	v_add_f32_dpp v48, v48, v48 row_shr:8 row_mask:0xf bank_mask:0xf bound_ctrl:1
	s_waitcnt lgkmcnt(0)
	s_nop 1
	v_add_f32_dpp v97, v53, v48 row_newbcast:15 row_mask:0xf bank_mask:0xf
.LBB0_2233:
	v_mul_f32_e32 v48, 0xbfb8aa3b, v54
	v_exp_f32_e32 v48, v48
	v_mul_f32_e32 v50, 0xbfb8aa3b, v50
	v_exp_f32_e32 v50, v50
	v_mul_f32_e32 v51, 0xbfb8aa3b, v51
	v_add_f32_e32 v48, 1.0, v48
	v_pk_add_f32 v[72:73], v[66:67], 1.0 op_sel_hi:[1,0] neg_lo:[1,0] neg_hi:[1,0]
	v_add_f32_e32 v52, 1.0, v50
	v_rcp_f32_e32 v50, v48
	v_mul_f32_e32 v48, 0xbfb8aa3b, v55
	v_exp_f32_e32 v48, v48
	v_exp_f32_e32 v55, v51
	v_rcp_f32_e32 v54, v52
	s_and_b64 vcc, exec, s[2:3]
	v_add_f32_e32 v48, 1.0, v48
	v_rcp_f32_e32 v51, v48
	v_add_f32_e32 v48, 1.0, v55
	v_rcp_f32_e32 v55, v48
	s_mov_b64 s[4:5], -1
	v_pk_fma_f32 v[86:87], v[50:51], v[72:73], v[66:67]
	v_pk_fma_f32 v[82:83], v[54:55], v[72:73], v[66:67]
	v_log_f32_e32 v48, v86
	v_log_f32_e32 v51, v82
	v_mul_f32_e32 v50, 0x3f317218, v48
	v_mul_f32_e32 v48, 0x3f317218, v51
	s_cbranch_vccnz .LBB0_2235
	s_nop 0
	v_add_f32_dpp v51, v48, v48 row_shl:1 row_mask:0xf bank_mask:0xf bound_ctrl:1
	v_add_f32_dpp v52, v50, v50 row_shl:1 row_mask:0xf bank_mask:0xf bound_ctrl:1
	s_mov_b64 s[4:5], 0
	v_add_f32_dpp v51, v51, v51 row_shl:2 row_mask:0xf bank_mask:0xf bound_ctrl:1
	v_add_f32_dpp v52, v52, v52 row_shl:2 row_mask:0xf bank_mask:0xf bound_ctrl:1
	s_nop 0
	v_add_f32_dpp v51, v51, v51 row_shl:4 row_mask:0xf bank_mask:0xf bound_ctrl:1
	v_add_f32_dpp v52, v52, v52 row_shl:4 row_mask:0xf bank_mask:0xf bound_ctrl:1
	s_nop 0
	v_add_f32_dpp v98, v51, v51 row_shl:8 row_mask:0xf bank_mask:0xf bound_ctrl:1
	s_nop 0
	s_nop 0
	s_nop 0
	v_add_f32_dpp v52, v52, v52 row_shl:8 row_mask:0xf bank_mask:0xf bound_ctrl:1
	s_waitcnt lgkmcnt(0)
	s_nop 1
	v_add_f32_dpp v51, v98, v52 row_newbcast:0 row_mask:0xf bank_mask:0xf
.LBB0_2235:
	s_andn2_b64 vcc, exec, s[4:5]
	s_cbranch_vccnz .LBB0_2237
	v_add_f32_dpp v50, v50, v50 row_shr:1 row_mask:0xf bank_mask:0xf bound_ctrl:1
	v_add_f32_dpp v48, v48, v48 row_shr:1 row_mask:0xf bank_mask:0xf bound_ctrl:1
	s_nop 0
	v_add_f32_dpp v50, v50, v50 row_shr:2 row_mask:0xf bank_mask:0xf bound_ctrl:1
	v_add_f32_dpp v48, v48, v48 row_shr:2 row_mask:0xf bank_mask:0xf bound_ctrl:1
	s_nop 0
	v_add_f32_dpp v50, v50, v50 row_shr:4 row_mask:0xf bank_mask:0xf bound_ctrl:1
	v_add_f32_dpp v48, v48, v48 row_shr:4 row_mask:0xf bank_mask:0xf bound_ctrl:1
	s_nop 0
	v_add_f32_dpp v51, v50, v50 row_shr:8 row_mask:0xf bank_mask:0xf bound_ctrl:1
	s_nop 0
	s_nop 0
	s_nop 0
	v_add_f32_dpp v48, v48, v48 row_shr:8 row_mask:0xf bank_mask:0xf bound_ctrl:1
	s_waitcnt lgkmcnt(0)
	s_nop 1
	v_add_f32_dpp v98, v51, v48 row_newbcast:15 row_mask:0xf bank_mask:0xf
.LBB0_2237:
	v_log_f32_e32 v48, v87
	v_log_f32_e32 v52, v83
	s_and_b64 vcc, exec, s[2:3]
	s_mov_b64 s[4:5], -1
	v_mul_f32_e32 v50, 0x3f317218, v48
	v_mul_f32_e32 v48, 0x3f317218, v52
	s_cbranch_vccnz .LBB0_2239
	s_nop 0
	v_add_f32_dpp v52, v48, v48 row_shl:1 row_mask:0xf bank_mask:0xf bound_ctrl:1
	v_add_f32_dpp v54, v50, v50 row_shl:1 row_mask:0xf bank_mask:0xf bound_ctrl:1
	s_mov_b64 s[4:5], 0
	v_add_f32_dpp v52, v52, v52 row_shl:2 row_mask:0xf bank_mask:0xf bound_ctrl:1
	v_add_f32_dpp v54, v54, v54 row_shl:2 row_mask:0xf bank_mask:0xf bound_ctrl:1
	s_nop 0
	v_add_f32_dpp v52, v52, v52 row_shl:4 row_mask:0xf bank_mask:0xf bound_ctrl:1
	v_add_f32_dpp v54, v54, v54 row_shl:4 row_mask:0xf bank_mask:0xf bound_ctrl:1
	s_nop 0
	v_add_f32_dpp v99, v52, v52 row_shl:8 row_mask:0xf bank_mask:0xf bound_ctrl:1
	s_nop 0
	s_nop 0
	s_nop 0
	v_add_f32_dpp v54, v54, v54 row_shl:8 row_mask:0xf bank_mask:0xf bound_ctrl:1
	s_waitcnt lgkmcnt(0)
	s_nop 1
	v_add_f32_dpp v55, v99, v54 row_newbcast:0 row_mask:0xf bank_mask:0xf
.LBB0_2239:
	s_andn2_b64 vcc, exec, s[4:5]
	s_cbranch_vccnz .LBB0_2241
	v_add_f32_dpp v50, v50, v50 row_shr:1 row_mask:0xf bank_mask:0xf bound_ctrl:1
	v_add_f32_dpp v48, v48, v48 row_shr:1 row_mask:0xf bank_mask:0xf bound_ctrl:1
	s_nop 0
	v_add_f32_dpp v50, v50, v50 row_shr:2 row_mask:0xf bank_mask:0xf bound_ctrl:1
	v_add_f32_dpp v48, v48, v48 row_shr:2 row_mask:0xf bank_mask:0xf bound_ctrl:1
	s_nop 0
	v_add_f32_dpp v50, v50, v50 row_shr:4 row_mask:0xf bank_mask:0xf bound_ctrl:1
	v_add_f32_dpp v48, v48, v48 row_shr:4 row_mask:0xf bank_mask:0xf bound_ctrl:1
	s_nop 0
	v_add_f32_dpp v55, v50, v50 row_shr:8 row_mask:0xf bank_mask:0xf bound_ctrl:1
	s_nop 0
	s_nop 0
	s_nop 0
	v_add_f32_dpp v48, v48, v48 row_shr:8 row_mask:0xf bank_mask:0xf bound_ctrl:1
	s_waitcnt lgkmcnt(0)
	s_nop 1
	v_add_f32_dpp v99, v55, v48 row_newbcast:15 row_mask:0xf bank_mask:0xf

; DI float sigmoid_f(float x) { return __builtin_amdgcn_rcpf(1.f + __expf(-x)); }
; template <int CTRL> DI float dpp_f(float x) { return __int_as_float(__builtin_amdgcn_update_dpp(0, __float_as_int(x), CTRL, 0xF, 0xF, true)); }
;     DI void operator()(const AccT& acc, int brow, int bcol, int wr, int wc, int fr, int fq) const {
;     ...
;                 for (int mp = 0; mp < 2; ++mp) {
;                     const size_t row0 = brow + ai * 128 + wr * 64 + mp * 32 + fr, row1 = row0 + 16;
;                     float fa[8], fb[8], xa[8], xb[8];
; #pragma unroll
;                     for (int j = 0; j < 4; ++j) { fa[j] = lb0[j] + (1.f - lb0[j]) * sigmoid_f(acc[ai][bj][2 * mp][0][j]); fa[4 + j] = lb1[j] + (1.f - lb1[j]) * sigmoid_f(acc[ai][bj][2 * mp][1][j]);
;                                                   fb[j] = lb0[j] + (1.f - lb0[j]) * sigmoid_f(acc[ai][bj][2 * mp + 1][0][j]); fb[4 + j] = lb1[j] + (1.f - lb1[j]) * sigmoid_f(acc[ai][bj][2 * mp + 1][1][j]); }
; #pragma unroll
;                     for (int j = 0; j < 8; ++j) { float x = __builtin_amdgcn_logf(fa[j]) * 0.6931471805599453f, y = __builtin_amdgcn_logf(fb[j]) * 0.6931471805599453f;
;                         if (dir == 0) { x += dpp_f<0x111>(x); x += dpp_f<0x112>(x); x += dpp_f<0x114>(x); x += dpp_f<0x118>(x);
;                                         y += dpp_f<0x111>(y); y += dpp_f<0x112>(y); y += dpp_f<0x114>(y); y += dpp_f<0x118>(y);
;                                         y += __shfl(x, (lane_ & 48) | 15); }
;                         else { x += dpp_f<0x101>(x); x += dpp_f<0x102>(x); x += dpp_f<0x104>(x); x += dpp_f<0x108>(x);
;                                y += dpp_f<0x101>(y); y += dpp_f<0x102>(y); y += dpp_f<0x104>(y); y += dpp_f<0x108>(y);
;                                x += __shfl(y, lane_ & 48); }
;                         xa[j] = x; xb[j] = y; }
.LBB0_2245:
	s_or_b64 exec, exec, s[14:15]
	v_mul_f32_e32 v44, 0xbfb8aa3b, v44
	v_exp_f32_e32 v44, v44
	v_mul_f32_e32 v40, 0xbfb8aa3b, v40
	v_exp_f32_e32 v40, v40
	v_mul_f32_e32 v41, 0xbfb8aa3b, v41
	v_add_f32_e32 v44, 1.0, v44
	s_and_b64 vcc, exec, s[2:3]
	v_add_f32_e32 v48, 1.0, v40
	v_rcp_f32_e32 v40, v44
	v_mul_f32_e32 v44, 0xbfb8aa3b, v45
	v_exp_f32_e32 v44, v44
	v_exp_f32_e32 v45, v41
	v_rcp_f32_e32 v48, v48
	s_mov_b64 s[14:15], -1
	v_add_f32_e32 v41, 1.0, v44
	v_add_f32_e32 v44, 1.0, v45
	v_rcp_f32_e32 v41, v41
	v_rcp_f32_e32 v49, v44
	v_pk_fma_f32 v[44:45], v[40:41], v[60:61], v[68:69]
	v_pk_fma_f32 v[40:41], v[48:49], v[60:61], v[68:69]
	v_log_f32_e32 v48, v44
	v_log_f32_e32 v50, v40
	v_mul_f32_e32 v49, 0x3f317218, v48
	v_mul_f32_e32 v48, 0x3f317218, v50
	s_cbranch_vccnz .LBB0_2247
	s_nop 0
	v_add_f32_dpp v50, v48, v48 row_shl:1 row_mask:0xf bank_mask:0xf bound_ctrl:1
	v_add_f32_dpp v51, v49, v49 row_shl:1 row_mask:0xf bank_mask:0xf bound_ctrl:1
	s_mov_b64 s[14:15], 0
	v_add_f32_dpp v50, v50, v50 row_shl:2 row_mask:0xf bank_mask:0xf bound_ctrl:1
	v_add_f32_dpp v51, v51, v51 row_shl:2 row_mask:0xf bank_mask:0xf bound_ctrl:1
	s_nop 0
	v_add_f32_dpp v50, v50, v50 row_shl:4 row_mask:0xf bank_mask:0xf bound_ctrl:1
	v_add_f32_dpp v51, v51, v51 row_shl:4 row_mask:0xf bank_mask:0xf bound_ctrl:1
	s_nop 0
	v_add_f32_dpp v76, v50, v50 row_shl:8 row_mask:0xf bank_mask:0xf bound_ctrl:1
	s_nop 0
	s_nop 0
	s_nop 0
	v_add_f32_dpp v51, v51, v51 row_shl:8 row_mask:0xf bank_mask:0xf bound_ctrl:1
	s_waitcnt lgkmcnt(0)
	s_nop 1
	v_add_f32_dpp v57, v76, v51 row_newbcast:0 row_mask:0xf bank_mask:0xf
.LBB0_2247:
	s_andn2_b64 vcc, exec, s[14:15]
	s_cbranch_vccnz .LBB0_2249
	v_add_f32_dpp v49, v49, v49 row_shr:1 row_mask:0xf bank_mask:0xf bound_ctrl:1
	v_add_f32_dpp v48, v48, v48 row_shr:1 row_mask:0xf bank_mask:0xf bound_ctrl:1
	s_nop 0
	v_add_f32_dpp v49, v49, v49 row_shr:2 row_mask:0xf bank_mask:0xf bound_ctrl:1
	v_add_f32_dpp v48, v48, v48 row_shr:2 row_mask:0xf bank_mask:0xf bound_ctrl:1
	s_nop 0
	v_add_f32_dpp v49, v49, v49 row_shr:4 row_mask:0xf bank_mask:0xf bound_ctrl:1
	v_add_f32_dpp v48, v48, v48 row_shr:4 row_mask:0xf bank_mask:0xf bound_ctrl:1
	s_nop 0
	v_add_f32_dpp v57, v49, v49 row_shr:8 row_mask:0xf bank_mask:0xf bound_ctrl:1
	s_nop 0
	s_nop 0
	s_nop 0
	v_add_f32_dpp v48, v48, v48 row_shr:8 row_mask:0xf bank_mask:0xf bound_ctrl:1
	s_waitcnt lgkmcnt(0)
	s_nop 1
	v_add_f32_dpp v76, v57, v48 row_newbcast:15 row_mask:0xf bank_mask:0xf
.LBB0_2249:
	v_log_f32_e32 v48, v45
	v_log_f32_e32 v50, v41
	s_and_b64 vcc, exec, s[2:3]
	s_mov_b64 s[14:15], -1
	v_mul_f32_e32 v49, 0x3f317218, v48
	v_mul_f32_e32 v48, 0x3f317218, v50
	s_cbranch_vccnz .LBB0_2251
	s_nop 0
	v_add_f32_dpp v50, v48, v48 row_shl:1 row_mask:0xf bank_mask:0xf bound_ctrl:1
	v_add_f32_dpp v51, v49, v49 row_shl:1 row_mask:0xf bank_mask:0xf bound_ctrl:1
	s_mov_b64 s[14:15], 0
	v_add_f32_dpp v50, v50, v50 row_shl:2 row_mask:0xf bank_mask:0xf bound_ctrl:1
	v_add_f32_dpp v51, v51, v51 row_shl:2 row_mask:0xf bank_mask:0xf bound_ctrl:1
	s_nop 0
	v_add_f32_dpp v50, v50, v50 row_shl:4 row_mask:0xf bank_mask:0xf bound_ctrl:1
	v_add_f32_dpp v51, v51, v51 row_shl:4 row_mask:0xf bank_mask:0xf bound_ctrl:1
	s_nop 0
	v_add_f32_dpp v77, v50, v50 row_shl:8 row_mask:0xf bank_mask:0xf bound_ctrl:1
	s_nop 0
	s_nop 0
	s_nop 0
	v_add_f32_dpp v51, v51, v51 row_shl:8 row_mask:0xf bank_mask:0xf bound_ctrl:1
	s_waitcnt lgkmcnt(0)
	s_nop 1
	v_add_f32_dpp v80, v77, v51 row_newbcast:0 row_mask:0xf bank_mask:0xf
.LBB0_2251:
	s_andn2_b64 vcc, exec, s[14:15]
	s_cbranch_vccnz .LBB0_2253
	v_add_f32_dpp v49, v49, v49 row_shr:1 row_mask:0xf bank_mask:0xf bound_ctrl:1
	v_add_f32_dpp v48, v48, v48 row_shr:1 row_mask:0xf bank_mask:0xf bound_ctrl:1
	s_nop 0
	v_add_f32_dpp v49, v49, v49 row_shr:2 row_mask:0xf bank_mask:0xf bound_ctrl:1
	v_add_f32_dpp v48, v48, v48 row_shr:2 row_mask:0xf bank_mask:0xf bound_ctrl:1
	s_nop 0
	v_add_f32_dpp v49, v49, v49 row_shr:4 row_mask:0xf bank_mask:0xf bound_ctrl:1
	v_add_f32_dpp v48, v48, v48 row_shr:4 row_mask:0xf bank_mask:0xf bound_ctrl:1
	s_nop 0
	v_add_f32_dpp v80, v49, v49 row_shr:8 row_mask:0xf bank_mask:0xf bound_ctrl:1
	s_nop 0
	s_nop 0
	s_nop 0
	v_add_f32_dpp v48, v48, v48 row_shr:8 row_mask:0xf bank_mask:0xf bound_ctrl:1
	s_waitcnt lgkmcnt(0)
	s_nop 1
	v_add_f32_dpp v77, v80, v48 row_newbcast:15 row_mask:0xf bank_mask:0xf
.LBB0_2253:
	v_mul_f32_e32 v46, 0xbfb8aa3b, v46
	v_exp_f32_e32 v46, v46
	v_mul_f32_e32 v42, 0xbfb8aa3b, v42
	v_exp_f32_e32 v42, v42
	v_mul_f32_e32 v43, 0xbfb8aa3b, v43
	v_add_f32_e32 v46, 1.0, v46
	s_and_b64 vcc, exec, s[2:3]
	v_add_f32_e32 v48, 1.0, v42
	v_rcp_f32_e32 v42, v46
	v_mul_f32_e32 v46, 0xbfb8aa3b, v47
	v_exp_f32_e32 v46, v46
	v_exp_f32_e32 v47, v43
	v_rcp_f32_e32 v48, v48
	s_mov_b64 s[14:15], -1
	v_add_f32_e32 v43, 1.0, v46
	v_add_f32_e32 v46, 1.0, v47
	v_rcp_f32_e32 v43, v43
	v_rcp_f32_e32 v49, v46
	v_pk_fma_f32 v[46:47], v[42:43], v[58:59], v[70:71]
	v_pk_fma_f32 v[42:43], v[48:49], v[58:59], v[70:71]
	v_log_f32_e32 v48, v46
	v_log_f32_e32 v50, v42
	v_mul_f32_e32 v49, 0x3f317218, v48
	v_mul_f32_e32 v48, 0x3f317218, v50
	s_cbranch_vccnz .LBB0_2255
	s_nop 0
	v_add_f32_dpp v50, v48, v48 row_shl:1 row_mask:0xf bank_mask:0xf bound_ctrl:1
	v_add_f32_dpp v51, v49, v49 row_shl:1 row_mask:0xf bank_mask:0xf bound_ctrl:1
	s_mov_b64 s[14:15], 0
	v_add_f32_dpp v50, v50, v50 row_shl:2 row_mask:0xf bank_mask:0xf bound_ctrl:1
	v_add_f32_dpp v51, v51, v51 row_shl:2 row_mask:0xf bank_mask:0xf bound_ctrl:1
	s_nop 0
	v_add_f32_dpp v50, v50, v50 row_shl:4 row_mask:0xf bank_mask:0xf bound_ctrl:1
	v_add_f32_dpp v51, v51, v51 row_shl:4 row_mask:0xf bank_mask:0xf bound_ctrl:1
	s_nop 0
	v_add_f32_dpp v78, v50, v50 row_shl:8 row_mask:0xf bank_mask:0xf bound_ctrl:1
	s_nop 0
	s_nop 0
	s_nop 0
	v_add_f32_dpp v51, v51, v51 row_shl:8 row_mask:0xf bank_mask:0xf bound_ctrl:1
	s_waitcnt lgkmcnt(0)
	s_nop 1
	v_add_f32_dpp v81, v78, v51 row_newbcast:0 row_mask:0xf bank_mask:0xf
; DI float sigmoid_f(float x) { return __builtin_amdgcn_rcpf(1.f + __expf(-x)); }
; template <int CTRL> DI float dpp_f(float x) { return __int_as_float(__builtin_amdgcn_update_dpp(0, __float_as_int(x), CTRL, 0xF, 0xF, true)); }
;     DI void operator()(const AccT& acc, int brow, int bcol, int wr, int wc, int fr, int fq) const {
;     ...
;                     for (int j = 0; j < 4; ++j) { fa[j] = lb0[j] + (1.f - lb0[j]) * sigmoid_f(acc[ai][bj][2 * mp][0][j]); fa[4 + j] = lb1[j] + (1.f - lb1[j]) * sigmoid_f(acc[ai][bj][2 * mp][1][j]);
;                                                   fb[j] = lb0[j] + (1.f - lb0[j]) * sigmoid_f(acc[ai][bj][2 * mp + 1][0][j]); fb[4 + j] = lb1[j] + (1.f - lb1[j]) * sigmoid_f(acc[ai][bj][2 * mp + 1][1][j]); }
; #pragma unroll
;                     for (int j = 0; j < 8; ++j) { float x = __builtin_amdgcn_logf(fa[j]) * 0.6931471805599453f, y = __builtin_amdgcn_logf(fb[j]) * 0.6931471805599453f;
;                         if (dir == 0) { x += dpp_f<0x111>(x); x += dpp_f<0x112>(x); x += dpp_f<0x114>(x); x += dpp_f<0x118>(x);
;                                         y += dpp_f<0x111>(y); y += dpp_f<0x112>(y); y += dpp_f<0x114>(y); y += dpp_f<0x118>(y);
;                                         y += __shfl(x, (lane_ & 48) | 15); }
;                         else { x += dpp_f<0x101>(x); x += dpp_f<0x102>(x); x += dpp_f<0x104>(x); x += dpp_f<0x108>(x);
;                                y += dpp_f<0x101>(y); y += dpp_f<0x102>(y); y += dpp_f<0x104>(y); y += dpp_f<0x108>(y);
;                                x += __shfl(y, lane_ & 48); }
;                         xa[j] = x; xb[j] = y; }
.LBB0_2255:
	s_andn2_b64 vcc, exec, s[14:15]
	s_cbranch_vccnz .LBB0_2257
	v_add_f32_dpp v49, v49, v49 row_shr:1 row_mask:0xf bank_mask:0xf bound_ctrl:1
	v_add_f32_dpp v48, v48, v48 row_shr:1 row_mask:0xf bank_mask:0xf bound_ctrl:1
	s_nop 0
	v_add_f32_dpp v49, v49, v49 row_shr:2 row_mask:0xf bank_mask:0xf bound_ctrl:1
	v_add_f32_dpp v48, v48, v48 row_shr:2 row_mask:0xf bank_mask:0xf bound_ctrl:1
	s_nop 0
	v_add_f32_dpp v49, v49, v49 row_shr:4 row_mask:0xf bank_mask:0xf bound_ctrl:1
	v_add_f32_dpp v48, v48, v48 row_shr:4 row_mask:0xf bank_mask:0xf bound_ctrl:1
	s_nop 0
	v_add_f32_dpp v81, v49, v49 row_shr:8 row_mask:0xf bank_mask:0xf bound_ctrl:1
	s_nop 0
	s_nop 0
	s_nop 0
	v_add_f32_dpp v48, v48, v48 row_shr:8 row_mask:0xf bank_mask:0xf bound_ctrl:1
	s_waitcnt lgkmcnt(0)
	s_nop 1
	v_add_f32_dpp v78, v81, v48 row_newbcast:15 row_mask:0xf bank_mask:0xf
.LBB0_2257:
	v_log_f32_e32 v48, v47
	v_log_f32_e32 v50, v43
	s_and_b64 vcc, exec, s[2:3]
	s_mov_b64 s[14:15], -1
	v_mul_f32_e32 v49, 0x3f317218, v48
	v_mul_f32_e32 v48, 0x3f317218, v50
	s_cbranch_vccnz .LBB0_2259
	s_nop 0
	v_add_f32_dpp v50, v48, v48 row_shl:1 row_mask:0xf bank_mask:0xf bound_ctrl:1
	v_add_f32_dpp v51, v49, v49 row_shl:1 row_mask:0xf bank_mask:0xf bound_ctrl:1
	s_mov_b64 s[14:15], 0
	v_add_f32_dpp v50, v50, v50 row_shl:2 row_mask:0xf bank_mask:0xf bound_ctrl:1
	v_add_f32_dpp v51, v51, v51 row_shl:2 row_mask:0xf bank_mask:0xf bound_ctrl:1
	s_nop 0
	v_add_f32_dpp v50, v50, v50 row_shl:4 row_mask:0xf bank_mask:0xf bound_ctrl:1
	v_add_f32_dpp v51, v51, v51 row_shl:4 row_mask:0xf bank_mask:0xf bound_ctrl:1
	s_nop 0
	v_add_f32_dpp v79, v50, v50 row_shl:8 row_mask:0xf bank_mask:0xf bound_ctrl:1
	s_nop 0
	s_nop 0
	s_nop 0
	v_add_f32_dpp v51, v51, v51 row_shl:8 row_mask:0xf bank_mask:0xf bound_ctrl:1
	s_waitcnt lgkmcnt(0)
	s_nop 1
	v_add_f32_dpp v83, v79, v51 row_newbcast:0 row_mask:0xf bank_mask:0xf
.LBB0_2259:
	s_andn2_b64 vcc, exec, s[14:15]
	s_cbranch_vccnz .LBB0_2261
	v_add_f32_dpp v49, v49, v49 row_shr:1 row_mask:0xf bank_mask:0xf bound_ctrl:1
	v_add_f32_dpp v48, v48, v48 row_shr:1 row_mask:0xf bank_mask:0xf bound_ctrl:1
	s_nop 0
	v_add_f32_dpp v49, v49, v49 row_shr:2 row_mask:0xf bank_mask:0xf bound_ctrl:1
	v_add_f32_dpp v48, v48, v48 row_shr:2 row_mask:0xf bank_mask:0xf bound_ctrl:1
	s_nop 0
	v_add_f32_dpp v49, v49, v49 row_shr:4 row_mask:0xf bank_mask:0xf bound_ctrl:1
	v_add_f32_dpp v48, v48, v48 row_shr:4 row_mask:0xf bank_mask:0xf bound_ctrl:1
	s_nop 0
	v_add_f32_dpp v83, v49, v49 row_shr:8 row_mask:0xf bank_mask:0xf bound_ctrl:1
	s_nop 0
	s_nop 0
	s_nop 0
	v_add_f32_dpp v48, v48, v48 row_shr:8 row_mask:0xf bank_mask:0xf bound_ctrl:1
	s_waitcnt lgkmcnt(0)
	s_nop 1
	v_add_f32_dpp v79, v83, v48 row_newbcast:15 row_mask:0xf bank_mask:0xf
.LBB0_2261:
	v_mul_f32_e32 v36, 0xbfb8aa3b, v36
	v_exp_f32_e32 v36, v36
	v_mul_f32_e32 v32, 0xbfb8aa3b, v32
	v_exp_f32_e32 v32, v32
	v_mul_f32_e32 v33, 0xbfb8aa3b, v33
	v_add_f32_e32 v36, 1.0, v36
	v_exp_f32_e32 v49, v33
	v_add_f32_e32 v48, 1.0, v32
	v_rcp_f32_e32 v32, v36
	v_mul_f32_e32 v36, 0xbfb8aa3b, v37
	v_exp_f32_e32 v37, v36
	v_rcp_f32_e32 v36, v48
	s_and_b64 vcc, exec, s[2:3]
	s_mov_b64 s[14:15], -1
	v_add_f32_e32 v33, 1.0, v37
	v_add_f32_e32 v37, 1.0, v49
	v_rcp_f32_e32 v33, v33
	v_rcp_f32_e32 v37, v37
	v_pk_fma_f32 v[52:53], v[32:33], v[62:63], v[64:65]
	v_pk_fma_f32 v[48:49], v[36:37], v[62:63], v[64:65]
	v_log_f32_e32 v32, v52
	v_log_f32_e32 v33, v48
	v_mul_f32_e32 v36, 0x3f317218, v32
	v_mul_f32_e32 v32, 0x3f317218, v33
	s_cbranch_vccnz .LBB0_2263
	s_nop 0
	v_add_f32_dpp v33, v32, v32 row_shl:1 row_mask:0xf bank_mask:0xf bound_ctrl:1
	v_add_f32_dpp v37, v36, v36 row_shl:1 row_mask:0xf bank_mask:0xf bound_ctrl:1
	s_mov_b64 s[14:15], 0
	v_add_f32_dpp v33, v33, v33 row_shl:2 row_mask:0xf bank_mask:0xf bound_ctrl:1
	v_add_f32_dpp v37, v37, v37 row_shl:2 row_mask:0xf bank_mask:0xf bound_ctrl:1
	s_nop 0
	v_add_f32_dpp v33, v33, v33 row_shl:4 row_mask:0xf bank_mask:0xf bound_ctrl:1
	v_add_f32_dpp v37, v37, v37 row_shl:4 row_mask:0xf bank_mask:0xf bound_ctrl:1
	s_nop 0
	v_add_f32_dpp v82, v33, v33 row_shl:8 row_mask:0xf bank_mask:0xf bound_ctrl:1
	s_nop 0
	s_nop 0
	s_nop 0
	v_add_f32_dpp v37, v37, v37 row_shl:8 row_mask:0xf bank_mask:0xf bound_ctrl:1
	s_waitcnt lgkmcnt(0)
	s_nop 1
	v_add_f32_dpp v33, v82, v37 row_newbcast:0 row_mask:0xf bank_mask:0xf
.LBB0_2263:
	s_andn2_b64 vcc, exec, s[14:15]
	s_cbranch_vccnz .LBB0_2265
	v_add_f32_dpp v33, v36, v36 row_shr:1 row_mask:0xf bank_mask:0xf bound_ctrl:1
	s_nop 0
	s_nop 0
	v_add_f32_dpp v33, v33, v33 row_shr:2 row_mask:0xf bank_mask:0xf bound_ctrl:1
	v_add_f32_dpp v32, v32, v32 row_shr:1 row_mask:0xf bank_mask:0xf bound_ctrl:1
	s_nop 0
	v_add_f32_dpp v33, v33, v33 row_shr:4 row_mask:0xf bank_mask:0xf bound_ctrl:1
	v_add_f32_dpp v32, v32, v32 row_shr:2 row_mask:0xf bank_mask:0xf bound_ctrl:1
	s_nop 0
	v_add_f32_dpp v33, v33, v33 row_shr:8 row_mask:0xf bank_mask:0xf bound_ctrl:1
	s_nop 0
	v_add_f32_dpp v32, v32, v32 row_shr:4 row_mask:0xf bank_mask:0xf bound_ctrl:1
	s_nop 1
	v_add_f32_dpp v32, v32, v32 row_shr:8 row_mask:0xf bank_mask:0xf bound_ctrl:1
	s_waitcnt lgkmcnt(0)
	s_nop 1
	v_add_f32_dpp v82, v33, v32 row_newbcast:15 row_mask:0xf bank_mask:0xf
; DI float sigmoid_f(float x) { return __builtin_amdgcn_rcpf(1.f + __expf(-x)); }
; template <int CTRL> DI float dpp_f(float x) { return __int_as_float(__builtin_amdgcn_update_dpp(0, __float_as_int(x), CTRL, 0xF, 0xF, true)); }
;     DI void operator()(const AccT& acc, int brow, int bcol, int wr, int wc, int fr, int fq) const {
;     ...
;                     for (int j = 0; j < 4; ++j) { fa[j] = lb0[j] + (1.f - lb0[j]) * sigmoid_f(acc[ai][bj][2 * mp][0][j]); fa[4 + j] = lb1[j] + (1.f - lb1[j]) * sigmoid_f(acc[ai][bj][2 * mp][1][j]);
;                                                   fb[j] = lb0[j] + (1.f - lb0[j]) * sigmoid_f(acc[ai][bj][2 * mp + 1][0][j]); fb[4 + j] = lb1[j] + (1.f - lb1[j]) * sigmoid_f(acc[ai][bj][2 * mp + 1][1][j]); }
; #pragma unroll
;                     for (int j = 0; j < 8; ++j) { float x = __builtin_amdgcn_logf(fa[j]) * 0.6931471805599453f, y = __builtin_amdgcn_logf(fb[j]) * 0.6931471805599453f;
;                         if (dir == 0) { x += dpp_f<0x111>(x); x += dpp_f<0x112>(x); x += dpp_f<0x114>(x); x += dpp_f<0x118>(x);
;                                         y += dpp_f<0x111>(y); y += dpp_f<0x112>(y); y += dpp_f<0x114>(y); y += dpp_f<0x118>(y);
;                                         y += __shfl(x, (lane_ & 48) | 15); }
;                         else { x += dpp_f<0x101>(x); x += dpp_f<0x102>(x); x += dpp_f<0x104>(x); x += dpp_f<0x108>(x);
;                                y += dpp_f<0x101>(y); y += dpp_f<0x102>(y); y += dpp_f<0x104>(y); y += dpp_f<0x108>(y);
;                                x += __shfl(y, lane_ & 48); }
;                         xa[j] = x; xb[j] = y; }
.LBB0_2265:
	v_log_f32_e32 v32, v53
	v_log_f32_e32 v37, v49
	s_and_b64 vcc, exec, s[2:3]
	s_mov_b64 s[14:15], -1
	v_mul_f32_e32 v36, 0x3f317218, v32
	v_mul_f32_e32 v32, 0x3f317218, v37
	s_cbranch_vccnz .LBB0_2267
	s_nop 0
	v_add_f32_dpp v37, v32, v32 row_shl:1 row_mask:0xf bank_mask:0xf bound_ctrl:1
	v_add_f32_dpp v50, v36, v36 row_shl:1 row_mask:0xf bank_mask:0xf bound_ctrl:1
	s_mov_b64 s[14:15], 0
	v_add_f32_dpp v37, v37, v37 row_shl:2 row_mask:0xf bank_mask:0xf bound_ctrl:1
	v_add_f32_dpp v50, v50, v50 row_shl:2 row_mask:0xf bank_mask:0xf bound_ctrl:1
	s_nop 0
	v_add_f32_dpp v37, v37, v37 row_shl:4 row_mask:0xf bank_mask:0xf bound_ctrl:1
	v_add_f32_dpp v50, v50, v50 row_shl:4 row_mask:0xf bank_mask:0xf bound_ctrl:1
	s_nop 0
	v_add_f32_dpp v84, v37, v37 row_shl:8 row_mask:0xf bank_mask:0xf bound_ctrl:1
	s_nop 0
	s_nop 0
	s_nop 0
	v_add_f32_dpp v50, v50, v50 row_shl:8 row_mask:0xf bank_mask:0xf bound_ctrl:1
	s_waitcnt lgkmcnt(0)
	s_nop 1
	v_add_f32_dpp v37, v84, v50 row_newbcast:0 row_mask:0xf bank_mask:0xf
.LBB0_2267:
	s_andn2_b64 vcc, exec, s[14:15]
	s_cbranch_vccnz .LBB0_2269
	v_add_f32_dpp v36, v36, v36 row_shr:1 row_mask:0xf bank_mask:0xf bound_ctrl:1
	v_add_f32_dpp v32, v32, v32 row_shr:1 row_mask:0xf bank_mask:0xf bound_ctrl:1
	s_nop 0
	v_add_f32_dpp v36, v36, v36 row_shr:2 row_mask:0xf bank_mask:0xf bound_ctrl:1
	v_add_f32_dpp v32, v32, v32 row_shr:2 row_mask:0xf bank_mask:0xf bound_ctrl:1
	s_nop 0
	v_add_f32_dpp v36, v36, v36 row_shr:4 row_mask:0xf bank_mask:0xf bound_ctrl:1
	v_add_f32_dpp v32, v32, v32 row_shr:4 row_mask:0xf bank_mask:0xf bound_ctrl:1
	s_nop 0
	v_add_f32_dpp v37, v36, v36 row_shr:8 row_mask:0xf bank_mask:0xf bound_ctrl:1
	s_nop 0
	s_nop 0
	s_nop 0
	v_add_f32_dpp v32, v32, v32 row_shr:8 row_mask:0xf bank_mask:0xf bound_ctrl:1
	s_waitcnt lgkmcnt(0)
	s_nop 1
	v_add_f32_dpp v84, v37, v32 row_newbcast:15 row_mask:0xf bank_mask:0xf
.LBB0_2269:
	v_mul_f32_e32 v32, 0xbfb8aa3b, v38
	v_exp_f32_e32 v32, v32
	v_mul_f32_e32 v34, 0xbfb8aa3b, v34
	v_exp_f32_e32 v34, v34
	v_mul_f32_e32 v35, 0xbfb8aa3b, v35
	v_add_f32_e32 v32, 1.0, v32
	s_and_b64 vcc, exec, s[2:3]
	v_add_f32_e32 v36, 1.0, v34
	v_rcp_f32_e32 v34, v32
	v_mul_f32_e32 v32, 0xbfb8aa3b, v39
	v_exp_f32_e32 v32, v32
	v_exp_f32_e32 v39, v35
	v_rcp_f32_e32 v38, v36
	s_mov_b64 s[14:15], -1
	v_add_f32_e32 v32, 1.0, v32
	v_rcp_f32_e32 v35, v32
	v_add_f32_e32 v32, 1.0, v39
	v_rcp_f32_e32 v39, v32
	v_pk_fma_f32 v[54:55], v[34:35], v[72:73], v[66:67]
	s_nop 0
	v_log_f32_e32 v32, v54
	v_pk_fma_f32 v[50:51], v[38:39], v[72:73], v[66:67]
	v_mul_f32_e32 v34, 0x3f317218, v32
	v_log_f32_e32 v35, v50
	s_nop 0
	v_mul_f32_e32 v32, 0x3f317218, v35
	s_cbranch_vccnz .LBB0_2271
	s_nop 0
	v_add_f32_dpp v35, v32, v32 row_shl:1 row_mask:0xf bank_mask:0xf bound_ctrl:1
	v_add_f32_dpp v36, v34, v34 row_shl:1 row_mask:0xf bank_mask:0xf bound_ctrl:1
	s_mov_b64 s[14:15], 0
	v_add_f32_dpp v35, v35, v35 row_shl:2 row_mask:0xf bank_mask:0xf bound_ctrl:1
	v_add_f32_dpp v36, v36, v36 row_shl:2 row_mask:0xf bank_mask:0xf bound_ctrl:1
	s_nop 0
	v_add_f32_dpp v35, v35, v35 row_shl:4 row_mask:0xf bank_mask:0xf bound_ctrl:1
	v_add_f32_dpp v36, v36, v36 row_shl:4 row_mask:0xf bank_mask:0xf bound_ctrl:1
	s_nop 0
	v_add_f32_dpp v85, v35, v35 row_shl:8 row_mask:0xf bank_mask:0xf bound_ctrl:1
	s_nop 0
	s_nop 0
	s_nop 0
	v_add_f32_dpp v36, v36, v36 row_shl:8 row_mask:0xf bank_mask:0xf bound_ctrl:1
	s_waitcnt lgkmcnt(0)
	s_nop 1
	v_add_f32_dpp v35, v85, v36 row_newbcast:0 row_mask:0xf bank_mask:0xf
.LBB0_2271:
	s_andn2_b64 vcc, exec, s[14:15]
	s_cbranch_vccnz .LBB0_2273
	v_add_f32_dpp v34, v34, v34 row_shr:1 row_mask:0xf bank_mask:0xf bound_ctrl:1
	v_add_f32_dpp v32, v32, v32 row_shr:1 row_mask:0xf bank_mask:0xf bound_ctrl:1
	s_nop 0
	v_add_f32_dpp v34, v34, v34 row_shr:2 row_mask:0xf bank_mask:0xf bound_ctrl:1
	v_add_f32_dpp v32, v32, v32 row_shr:2 row_mask:0xf bank_mask:0xf bound_ctrl:1
	s_nop 0
	v_add_f32_dpp v34, v34, v34 row_shr:4 row_mask:0xf bank_mask:0xf bound_ctrl:1
	v_add_f32_dpp v32, v32, v32 row_shr:4 row_mask:0xf bank_mask:0xf bound_ctrl:1
	s_nop 0
	v_add_f32_dpp v35, v34, v34 row_shr:8 row_mask:0xf bank_mask:0xf bound_ctrl:1
	s_nop 0
	s_nop 0
	s_nop 0
	v_add_f32_dpp v32, v32, v32 row_shr:8 row_mask:0xf bank_mask:0xf bound_ctrl:1
	s_waitcnt lgkmcnt(0)
	s_nop 1
	v_add_f32_dpp v85, v35, v32 row_newbcast:15 row_mask:0xf bank_mask:0xf
.LBB0_2273:
	v_log_f32_e32 v32, v55
	v_log_f32_e32 v36, v51
	s_and_b64 vcc, exec, s[2:3]
	s_mov_b64 s[14:15], -1
	v_mul_f32_e32 v34, 0x3f317218, v32
	v_mul_f32_e32 v32, 0x3f317218, v36
	s_cbranch_vccnz .LBB0_2275
	s_nop 0
	v_add_f32_dpp v36, v32, v32 row_shl:1 row_mask:0xf bank_mask:0xf bound_ctrl:1
	v_add_f32_dpp v38, v34, v34 row_shl:1 row_mask:0xf bank_mask:0xf bound_ctrl:1
	s_mov_b64 s[14:15], 0
	v_add_f32_dpp v36, v36, v36 row_shl:2 row_mask:0xf bank_mask:0xf bound_ctrl:1
	v_add_f32_dpp v38, v38, v38 row_shl:2 row_mask:0xf bank_mask:0xf bound_ctrl:1
	s_nop 0
	v_add_f32_dpp v36, v36, v36 row_shl:4 row_mask:0xf bank_mask:0xf bound_ctrl:1
	v_add_f32_dpp v38, v38, v38 row_shl:4 row_mask:0xf bank_mask:0xf bound_ctrl:1
	s_nop 0
	v_add_f32_dpp v86, v36, v36 row_shl:8 row_mask:0xf bank_mask:0xf bound_ctrl:1
	s_nop 0
	s_nop 0
	s_nop 0
	v_add_f32_dpp v38, v38, v38 row_shl:8 row_mask:0xf bank_mask:0xf bound_ctrl:1
	s_waitcnt lgkmcnt(0)
	s_nop 1
	v_add_f32_dpp v39, v86, v38 row_newbcast:0 row_mask:0xf bank_mask:0xf
.LBB0_2275:
	s_andn2_b64 vcc, exec, s[14:15]
	s_cbranch_vccnz .LBB0_2277
	v_add_f32_dpp v34, v34, v34 row_shr:1 row_mask:0xf bank_mask:0xf bound_ctrl:1
	v_add_f32_dpp v32, v32, v32 row_shr:1 row_mask:0xf bank_mask:0xf bound_ctrl:1
	s_nop 0
	v_add_f32_dpp v34, v34, v34 row_shr:2 row_mask:0xf bank_mask:0xf bound_ctrl:1
	v_add_f32_dpp v32, v32, v32 row_shr:2 row_mask:0xf bank_mask:0xf bound_ctrl:1
	s_nop 0
	v_add_f32_dpp v34, v34, v34 row_shr:4 row_mask:0xf bank_mask:0xf bound_ctrl:1
	v_add_f32_dpp v32, v32, v32 row_shr:4 row_mask:0xf bank_mask:0xf bound_ctrl:1
	s_nop 0
	v_add_f32_dpp v39, v34, v34 row_shr:8 row_mask:0xf bank_mask:0xf bound_ctrl:1
	s_nop 0
	s_nop 0
	s_nop 0
	v_add_f32_dpp v32, v32, v32 row_shr:8 row_mask:0xf bank_mask:0xf bound_ctrl:1
	s_waitcnt lgkmcnt(0)
	s_nop 1
	v_add_f32_dpp v86, v39, v32 row_newbcast:15 row_mask:0xf bank_mask:0xf

; DI float sigmoid_f(float x) { return __builtin_amdgcn_rcpf(1.f + __expf(-x)); }
; template <int CTRL> DI float dpp_f(float x) { return __int_as_float(__builtin_amdgcn_update_dpp(0, __float_as_int(x), CTRL, 0xF, 0xF, true)); }
;     DI void operator()(const AccT& acc, int brow, int bcol, int wr, int wc, int fr, int fq) const {
;     ...
;                 for (int mp = 0; mp < 2; ++mp) {
;                     const size_t row0 = brow + ai * 128 + wr * 64 + mp * 32 + fr, row1 = row0 + 16;
;                     float fa[8], fb[8], xa[8], xb[8];
; #pragma unroll
;                     for (int j = 0; j < 4; ++j) { fa[j] = lb0[j] + (1.f - lb0[j]) * sigmoid_f(acc[ai][bj][2 * mp][0][j]); fa[4 + j] = lb1[j] + (1.f - lb1[j]) * sigmoid_f(acc[ai][bj][2 * mp][1][j]);
;                                                   fb[j] = lb0[j] + (1.f - lb0[j]) * sigmoid_f(acc[ai][bj][2 * mp + 1][0][j]); fb[4 + j] = lb1[j] + (1.f - lb1[j]) * sigmoid_f(acc[ai][bj][2 * mp + 1][1][j]); }
; #pragma unroll
;                     for (int j = 0; j < 8; ++j) { float x = __builtin_amdgcn_logf(fa[j]) * 0.6931471805599453f, y = __builtin_amdgcn_logf(fb[j]) * 0.6931471805599453f;
;                         if (dir == 0) { x += dpp_f<0x111>(x); x += dpp_f<0x112>(x); x += dpp_f<0x114>(x); x += dpp_f<0x118>(x);
;                                         y += dpp_f<0x111>(y); y += dpp_f<0x112>(y); y += dpp_f<0x114>(y); y += dpp_f<0x118>(y);
;                                         y += __shfl(x, (lane_ & 48) | 15); }
;                         else { x += dpp_f<0x101>(x); x += dpp_f<0x102>(x); x += dpp_f<0x104>(x); x += dpp_f<0x108>(x);
;                                y += dpp_f<0x101>(y); y += dpp_f<0x102>(y); y += dpp_f<0x104>(y); y += dpp_f<0x108>(y);
;                                x += __shfl(y, lane_ & 48); }
;                         xa[j] = x; xb[j] = y; }
.LBB0_2281:
	s_or_b64 exec, exec, s[14:15]
	v_mul_f32_e32 v28, 0xbfb8aa3b, v28
	v_exp_f32_e32 v28, v28
	v_mul_f32_e32 v24, 0xbfb8aa3b, v24
	v_exp_f32_e32 v24, v24
	v_mul_f32_e32 v25, 0xbfb8aa3b, v25
	v_add_f32_e32 v28, 1.0, v28
	s_and_b64 vcc, exec, s[2:3]
	v_add_f32_e32 v32, 1.0, v24
	v_rcp_f32_e32 v24, v28
	v_mul_f32_e32 v28, 0xbfb8aa3b, v29
	v_exp_f32_e32 v28, v28
	v_exp_f32_e32 v29, v25
	v_rcp_f32_e32 v32, v32
	s_mov_b64 s[14:15], -1
	v_add_f32_e32 v25, 1.0, v28
	v_add_f32_e32 v28, 1.0, v29
	v_rcp_f32_e32 v25, v25
	v_rcp_f32_e32 v33, v28
	v_pk_fma_f32 v[28:29], v[24:25], v[60:61], v[68:69]
	v_pk_fma_f32 v[24:25], v[32:33], v[60:61], v[68:69]
	v_log_f32_e32 v32, v28
	v_log_f32_e32 v34, v24
	v_mul_f32_e32 v33, 0x3f317218, v32
	v_mul_f32_e32 v32, 0x3f317218, v34
	s_cbranch_vccnz .LBB0_2283
	s_nop 0
	v_add_f32_dpp v34, v32, v32 row_shl:1 row_mask:0xf bank_mask:0xf bound_ctrl:1
	v_add_f32_dpp v35, v33, v33 row_shl:1 row_mask:0xf bank_mask:0xf bound_ctrl:1
	s_mov_b64 s[14:15], 0
	v_add_f32_dpp v34, v34, v34 row_shl:2 row_mask:0xf bank_mask:0xf bound_ctrl:1
	v_add_f32_dpp v35, v35, v35 row_shl:2 row_mask:0xf bank_mask:0xf bound_ctrl:1
	s_nop 0
	v_add_f32_dpp v34, v34, v34 row_shl:4 row_mask:0xf bank_mask:0xf bound_ctrl:1
	v_add_f32_dpp v35, v35, v35 row_shl:4 row_mask:0xf bank_mask:0xf bound_ctrl:1
	s_nop 0
	v_add_f32_dpp v42, v34, v34 row_shl:8 row_mask:0xf bank_mask:0xf bound_ctrl:1
	s_nop 0
	s_nop 0
	s_nop 0
	v_add_f32_dpp v35, v35, v35 row_shl:8 row_mask:0xf bank_mask:0xf bound_ctrl:1
	s_waitcnt lgkmcnt(0)
	s_nop 1
	v_add_f32_dpp v45, v42, v35 row_newbcast:0 row_mask:0xf bank_mask:0xf
.LBB0_2283:
	s_andn2_b64 vcc, exec, s[14:15]
	s_cbranch_vccnz .LBB0_2285
	v_add_f32_dpp v33, v33, v33 row_shr:1 row_mask:0xf bank_mask:0xf bound_ctrl:1
	v_add_f32_dpp v32, v32, v32 row_shr:1 row_mask:0xf bank_mask:0xf bound_ctrl:1
	s_nop 0
	v_add_f32_dpp v33, v33, v33 row_shr:2 row_mask:0xf bank_mask:0xf bound_ctrl:1
	v_add_f32_dpp v32, v32, v32 row_shr:2 row_mask:0xf bank_mask:0xf bound_ctrl:1
	s_nop 0
	v_add_f32_dpp v33, v33, v33 row_shr:4 row_mask:0xf bank_mask:0xf bound_ctrl:1
	v_add_f32_dpp v32, v32, v32 row_shr:4 row_mask:0xf bank_mask:0xf bound_ctrl:1
	s_nop 0
	v_add_f32_dpp v45, v33, v33 row_shr:8 row_mask:0xf bank_mask:0xf bound_ctrl:1
	s_nop 0
	s_nop 0
	s_nop 0
	v_add_f32_dpp v32, v32, v32 row_shr:8 row_mask:0xf bank_mask:0xf bound_ctrl:1
	s_waitcnt lgkmcnt(0)
	s_nop 1
	v_add_f32_dpp v42, v45, v32 row_newbcast:15 row_mask:0xf bank_mask:0xf
.LBB0_2285:
	v_log_f32_e32 v32, v29
	v_log_f32_e32 v34, v25
	s_and_b64 vcc, exec, s[2:3]
	s_mov_b64 s[14:15], -1
	v_mul_f32_e32 v33, 0x3f317218, v32
	v_mul_f32_e32 v32, 0x3f317218, v34
	s_cbranch_vccnz .LBB0_2287
	s_nop 0
	v_add_f32_dpp v34, v32, v32 row_shl:1 row_mask:0xf bank_mask:0xf bound_ctrl:1
	v_add_f32_dpp v35, v33, v33 row_shl:1 row_mask:0xf bank_mask:0xf bound_ctrl:1
	s_mov_b64 s[14:15], 0
	v_add_f32_dpp v34, v34, v34 row_shl:2 row_mask:0xf bank_mask:0xf bound_ctrl:1
	v_add_f32_dpp v35, v35, v35 row_shl:2 row_mask:0xf bank_mask:0xf bound_ctrl:1
	s_nop 0
	v_add_f32_dpp v34, v34, v34 row_shl:4 row_mask:0xf bank_mask:0xf bound_ctrl:1
	v_add_f32_dpp v35, v35, v35 row_shl:4 row_mask:0xf bank_mask:0xf bound_ctrl:1
	s_nop 0
	v_add_f32_dpp v43, v34, v34 row_shl:8 row_mask:0xf bank_mask:0xf bound_ctrl:1
	s_nop 0
	s_nop 0
	s_nop 0
	v_add_f32_dpp v35, v35, v35 row_shl:8 row_mask:0xf bank_mask:0xf bound_ctrl:1
	s_waitcnt lgkmcnt(0)
	s_nop 1
	v_add_f32_dpp v47, v43, v35 row_newbcast:0 row_mask:0xf bank_mask:0xf
.LBB0_2287:
	s_andn2_b64 vcc, exec, s[14:15]
	s_cbranch_vccnz .LBB0_2289
	v_add_f32_dpp v33, v33, v33 row_shr:1 row_mask:0xf bank_mask:0xf bound_ctrl:1
	v_add_f32_dpp v32, v32, v32 row_shr:1 row_mask:0xf bank_mask:0xf bound_ctrl:1
	s_nop 0
	v_add_f32_dpp v33, v33, v33 row_shr:2 row_mask:0xf bank_mask:0xf bound_ctrl:1
	v_add_f32_dpp v32, v32, v32 row_shr:2 row_mask:0xf bank_mask:0xf bound_ctrl:1
	s_nop 0
	v_add_f32_dpp v33, v33, v33 row_shr:4 row_mask:0xf bank_mask:0xf bound_ctrl:1
	v_add_f32_dpp v32, v32, v32 row_shr:4 row_mask:0xf bank_mask:0xf bound_ctrl:1
	s_nop 0
	v_add_f32_dpp v47, v33, v33 row_shr:8 row_mask:0xf bank_mask:0xf bound_ctrl:1
	s_nop 0
	s_nop 0
	s_nop 0
	v_add_f32_dpp v32, v32, v32 row_shr:8 row_mask:0xf bank_mask:0xf bound_ctrl:1
	s_waitcnt lgkmcnt(0)
	s_nop 1
	v_add_f32_dpp v43, v47, v32 row_newbcast:15 row_mask:0xf bank_mask:0xf
.LBB0_2289:
	v_mul_f32_e32 v30, 0xbfb8aa3b, v30
	v_exp_f32_e32 v30, v30
	v_mul_f32_e32 v26, 0xbfb8aa3b, v26
	v_exp_f32_e32 v26, v26
	v_mul_f32_e32 v27, 0xbfb8aa3b, v27
	v_add_f32_e32 v30, 1.0, v30
	s_and_b64 vcc, exec, s[2:3]
	v_add_f32_e32 v32, 1.0, v26
	v_rcp_f32_e32 v26, v30
	v_mul_f32_e32 v30, 0xbfb8aa3b, v31
	v_exp_f32_e32 v30, v30
	v_exp_f32_e32 v31, v27
	v_rcp_f32_e32 v32, v32
	s_mov_b64 s[14:15], -1
	v_add_f32_e32 v27, 1.0, v30
	v_add_f32_e32 v30, 1.0, v31
	v_rcp_f32_e32 v27, v27
	v_rcp_f32_e32 v33, v30
	v_pk_fma_f32 v[30:31], v[26:27], v[58:59], v[70:71]
	v_pk_fma_f32 v[26:27], v[32:33], v[58:59], v[70:71]
	v_log_f32_e32 v32, v30
	v_log_f32_e32 v34, v26
	v_mul_f32_e32 v33, 0x3f317218, v32
	v_mul_f32_e32 v32, 0x3f317218, v34
	s_cbranch_vccnz .LBB0_2291
	s_nop 0
	v_add_f32_dpp v34, v32, v32 row_shl:1 row_mask:0xf bank_mask:0xf bound_ctrl:1
	v_add_f32_dpp v35, v33, v33 row_shl:1 row_mask:0xf bank_mask:0xf bound_ctrl:1
	s_mov_b64 s[14:15], 0
	v_add_f32_dpp v34, v34, v34 row_shl:2 row_mask:0xf bank_mask:0xf bound_ctrl:1
	v_add_f32_dpp v35, v35, v35 row_shl:2 row_mask:0xf bank_mask:0xf bound_ctrl:1
	s_nop 0
	v_add_f32_dpp v34, v34, v34 row_shl:4 row_mask:0xf bank_mask:0xf bound_ctrl:1
	v_add_f32_dpp v35, v35, v35 row_shl:4 row_mask:0xf bank_mask:0xf bound_ctrl:1
	s_nop 0
	v_add_f32_dpp v44, v34, v34 row_shl:8 row_mask:0xf bank_mask:0xf bound_ctrl:1
	s_nop 0
	s_nop 0
	s_nop 0
	v_add_f32_dpp v35, v35, v35 row_shl:8 row_mask:0xf bank_mask:0xf bound_ctrl:1
	s_waitcnt lgkmcnt(0)
	s_nop 1
	v_add_f32_dpp v48, v44, v35 row_newbcast:0 row_mask:0xf bank_mask:0xf
; DI float sigmoid_f(float x) { return __builtin_amdgcn_rcpf(1.f + __expf(-x)); }
; template <int CTRL> DI float dpp_f(float x) { return __int_as_float(__builtin_amdgcn_update_dpp(0, __float_as_int(x), CTRL, 0xF, 0xF, true)); }
;     DI void operator()(const AccT& acc, int brow, int bcol, int wr, int wc, int fr, int fq) const {
;     ...
;                     for (int j = 0; j < 4; ++j) { fa[j] = lb0[j] + (1.f - lb0[j]) * sigmoid_f(acc[ai][bj][2 * mp][0][j]); fa[4 + j] = lb1[j] + (1.f - lb1[j]) * sigmoid_f(acc[ai][bj][2 * mp][1][j]);
;                                                   fb[j] = lb0[j] + (1.f - lb0[j]) * sigmoid_f(acc[ai][bj][2 * mp + 1][0][j]); fb[4 + j] = lb1[j] + (1.f - lb1[j]) * sigmoid_f(acc[ai][bj][2 * mp + 1][1][j]); }
; #pragma unroll
;                     for (int j = 0; j < 8; ++j) { float x = __builtin_amdgcn_logf(fa[j]) * 0.6931471805599453f, y = __builtin_amdgcn_logf(fb[j]) * 0.6931471805599453f;
;                         if (dir == 0) { x += dpp_f<0x111>(x); x += dpp_f<0x112>(x); x += dpp_f<0x114>(x); x += dpp_f<0x118>(x);
;                                         y += dpp_f<0x111>(y); y += dpp_f<0x112>(y); y += dpp_f<0x114>(y); y += dpp_f<0x118>(y);
;                                         y += __shfl(x, (lane_ & 48) | 15); }
;                         else { x += dpp_f<0x101>(x); x += dpp_f<0x102>(x); x += dpp_f<0x104>(x); x += dpp_f<0x108>(x);
;                                y += dpp_f<0x101>(y); y += dpp_f<0x102>(y); y += dpp_f<0x104>(y); y += dpp_f<0x108>(y);
;                                x += __shfl(y, lane_ & 48); }
;                         xa[j] = x; xb[j] = y; }
.LBB0_2291:
	s_andn2_b64 vcc, exec, s[14:15]
	s_cbranch_vccnz .LBB0_2293
	v_add_f32_dpp v33, v33, v33 row_shr:1 row_mask:0xf bank_mask:0xf bound_ctrl:1
	v_add_f32_dpp v32, v32, v32 row_shr:1 row_mask:0xf bank_mask:0xf bound_ctrl:1
	s_nop 0
	v_add_f32_dpp v33, v33, v33 row_shr:2 row_mask:0xf bank_mask:0xf bound_ctrl:1
	v_add_f32_dpp v32, v32, v32 row_shr:2 row_mask:0xf bank_mask:0xf bound_ctrl:1
	s_nop 0
	v_add_f32_dpp v33, v33, v33 row_shr:4 row_mask:0xf bank_mask:0xf bound_ctrl:1
	v_add_f32_dpp v32, v32, v32 row_shr:4 row_mask:0xf bank_mask:0xf bound_ctrl:1
	s_nop 0
	v_add_f32_dpp v48, v33, v33 row_shr:8 row_mask:0xf bank_mask:0xf bound_ctrl:1
	s_nop 0
	s_nop 0
	s_nop 0
	v_add_f32_dpp v32, v32, v32 row_shr:8 row_mask:0xf bank_mask:0xf bound_ctrl:1
	s_waitcnt lgkmcnt(0)
	s_nop 1
	v_add_f32_dpp v44, v48, v32 row_newbcast:15 row_mask:0xf bank_mask:0xf
.LBB0_2293:
	v_log_f32_e32 v32, v31
	v_log_f32_e32 v34, v27
	s_and_b64 vcc, exec, s[2:3]
	s_mov_b64 s[14:15], -1
	v_mul_f32_e32 v33, 0x3f317218, v32
	v_mul_f32_e32 v32, 0x3f317218, v34
	s_cbranch_vccnz .LBB0_2295
	s_nop 0
	v_add_f32_dpp v34, v32, v32 row_shl:1 row_mask:0xf bank_mask:0xf bound_ctrl:1
	v_add_f32_dpp v35, v33, v33 row_shl:1 row_mask:0xf bank_mask:0xf bound_ctrl:1
	s_mov_b64 s[14:15], 0
	v_add_f32_dpp v34, v34, v34 row_shl:2 row_mask:0xf bank_mask:0xf bound_ctrl:1
	v_add_f32_dpp v35, v35, v35 row_shl:2 row_mask:0xf bank_mask:0xf bound_ctrl:1
	s_nop 0
	v_add_f32_dpp v34, v34, v34 row_shl:4 row_mask:0xf bank_mask:0xf bound_ctrl:1
	v_add_f32_dpp v35, v35, v35 row_shl:4 row_mask:0xf bank_mask:0xf bound_ctrl:1
	s_nop 0
	v_add_f32_dpp v46, v34, v34 row_shl:8 row_mask:0xf bank_mask:0xf bound_ctrl:1
	s_nop 0
	s_nop 0
	s_nop 0
	v_add_f32_dpp v35, v35, v35 row_shl:8 row_mask:0xf bank_mask:0xf bound_ctrl:1
	s_waitcnt lgkmcnt(0)
	s_nop 1
	v_add_f32_dpp v50, v46, v35 row_newbcast:0 row_mask:0xf bank_mask:0xf
.LBB0_2295:
	s_andn2_b64 vcc, exec, s[14:15]
	s_cbranch_vccnz .LBB0_2297
	v_add_f32_dpp v33, v33, v33 row_shr:1 row_mask:0xf bank_mask:0xf bound_ctrl:1
	v_add_f32_dpp v32, v32, v32 row_shr:1 row_mask:0xf bank_mask:0xf bound_ctrl:1
	s_nop 0
	v_add_f32_dpp v33, v33, v33 row_shr:2 row_mask:0xf bank_mask:0xf bound_ctrl:1
	v_add_f32_dpp v32, v32, v32 row_shr:2 row_mask:0xf bank_mask:0xf bound_ctrl:1
	s_nop 0
	v_add_f32_dpp v33, v33, v33 row_shr:4 row_mask:0xf bank_mask:0xf bound_ctrl:1
	v_add_f32_dpp v32, v32, v32 row_shr:4 row_mask:0xf bank_mask:0xf bound_ctrl:1
	s_nop 0
	v_add_f32_dpp v50, v33, v33 row_shr:8 row_mask:0xf bank_mask:0xf bound_ctrl:1
	s_nop 0
	s_nop 0
	s_nop 0
	v_add_f32_dpp v32, v32, v32 row_shr:8 row_mask:0xf bank_mask:0xf bound_ctrl:1
	s_waitcnt lgkmcnt(0)
	s_nop 1
	v_add_f32_dpp v46, v50, v32 row_newbcast:15 row_mask:0xf bank_mask:0xf
.LBB0_2297:
	v_mul_f32_e32 v20, 0xbfb8aa3b, v20
	v_exp_f32_e32 v20, v20
	v_mul_f32_e32 v16, 0xbfb8aa3b, v16
	v_exp_f32_e32 v16, v16
	v_mul_f32_e32 v17, 0xbfb8aa3b, v17
	v_add_f32_e32 v20, 1.0, v20
	v_exp_f32_e32 v33, v17
	v_add_f32_e32 v32, 1.0, v16
	v_rcp_f32_e32 v16, v20
	v_mul_f32_e32 v20, 0xbfb8aa3b, v21
	v_exp_f32_e32 v21, v20
	v_rcp_f32_e32 v20, v32
	s_and_b64 vcc, exec, s[2:3]
	s_mov_b64 s[14:15], -1
	v_add_f32_e32 v17, 1.0, v21
	v_add_f32_e32 v21, 1.0, v33
	v_rcp_f32_e32 v17, v17
	v_rcp_f32_e32 v21, v21
	v_pk_fma_f32 v[36:37], v[16:17], v[62:63], v[64:65]
	v_pk_fma_f32 v[32:33], v[20:21], v[62:63], v[64:65]
	v_log_f32_e32 v16, v36
	v_log_f32_e32 v17, v32
	v_mul_f32_e32 v20, 0x3f317218, v16
	v_mul_f32_e32 v16, 0x3f317218, v17
	s_cbranch_vccnz .LBB0_2299
	s_nop 0
	v_add_f32_dpp v17, v16, v16 row_shl:1 row_mask:0xf bank_mask:0xf bound_ctrl:1
	v_add_f32_dpp v21, v20, v20 row_shl:1 row_mask:0xf bank_mask:0xf bound_ctrl:1
	s_mov_b64 s[14:15], 0
	v_add_f32_dpp v17, v17, v17 row_shl:2 row_mask:0xf bank_mask:0xf bound_ctrl:1
	v_add_f32_dpp v21, v21, v21 row_shl:2 row_mask:0xf bank_mask:0xf bound_ctrl:1
	s_nop 0
	v_add_f32_dpp v17, v17, v17 row_shl:4 row_mask:0xf bank_mask:0xf bound_ctrl:1
	v_add_f32_dpp v21, v21, v21 row_shl:4 row_mask:0xf bank_mask:0xf bound_ctrl:1
	s_nop 0
	v_add_f32_dpp v49, v17, v17 row_shl:8 row_mask:0xf bank_mask:0xf bound_ctrl:1
	s_nop 0
	s_nop 0
	s_nop 0
	v_add_f32_dpp v21, v21, v21 row_shl:8 row_mask:0xf bank_mask:0xf bound_ctrl:1
	s_waitcnt lgkmcnt(0)
	s_nop 1
	v_add_f32_dpp v17, v49, v21 row_newbcast:0 row_mask:0xf bank_mask:0xf
.LBB0_2299:
	s_andn2_b64 vcc, exec, s[14:15]
	s_cbranch_vccnz .LBB0_2301
	v_add_f32_dpp v17, v20, v20 row_shr:1 row_mask:0xf bank_mask:0xf bound_ctrl:1
	s_nop 0
	s_nop 0
	v_add_f32_dpp v17, v17, v17 row_shr:2 row_mask:0xf bank_mask:0xf bound_ctrl:1
	v_add_f32_dpp v16, v16, v16 row_shr:1 row_mask:0xf bank_mask:0xf bound_ctrl:1
	s_nop 0
	v_add_f32_dpp v17, v17, v17 row_shr:4 row_mask:0xf bank_mask:0xf bound_ctrl:1
	v_add_f32_dpp v16, v16, v16 row_shr:2 row_mask:0xf bank_mask:0xf bound_ctrl:1
	s_nop 0
	v_add_f32_dpp v17, v17, v17 row_shr:8 row_mask:0xf bank_mask:0xf bound_ctrl:1
	s_nop 0
	v_add_f32_dpp v16, v16, v16 row_shr:4 row_mask:0xf bank_mask:0xf bound_ctrl:1
	s_nop 1
	v_add_f32_dpp v16, v16, v16 row_shr:8 row_mask:0xf bank_mask:0xf bound_ctrl:1
	s_waitcnt lgkmcnt(0)
	s_nop 1
	v_add_f32_dpp v49, v17, v16 row_newbcast:15 row_mask:0xf bank_mask:0xf
; DI float sigmoid_f(float x) { return __builtin_amdgcn_rcpf(1.f + __expf(-x)); }
; template <int CTRL> DI float dpp_f(float x) { return __int_as_float(__builtin_amdgcn_update_dpp(0, __float_as_int(x), CTRL, 0xF, 0xF, true)); }
;     DI void operator()(const AccT& acc, int brow, int bcol, int wr, int wc, int fr, int fq) const {
;     ...
;                     for (int j = 0; j < 4; ++j) { fa[j] = lb0[j] + (1.f - lb0[j]) * sigmoid_f(acc[ai][bj][2 * mp][0][j]); fa[4 + j] = lb1[j] + (1.f - lb1[j]) * sigmoid_f(acc[ai][bj][2 * mp][1][j]);
;                                                   fb[j] = lb0[j] + (1.f - lb0[j]) * sigmoid_f(acc[ai][bj][2 * mp + 1][0][j]); fb[4 + j] = lb1[j] + (1.f - lb1[j]) * sigmoid_f(acc[ai][bj][2 * mp + 1][1][j]); }
; #pragma unroll
;                     for (int j = 0; j < 8; ++j) { float x = __builtin_amdgcn_logf(fa[j]) * 0.6931471805599453f, y = __builtin_amdgcn_logf(fb[j]) * 0.6931471805599453f;
;                         if (dir == 0) { x += dpp_f<0x111>(x); x += dpp_f<0x112>(x); x += dpp_f<0x114>(x); x += dpp_f<0x118>(x);
;                                         y += dpp_f<0x111>(y); y += dpp_f<0x112>(y); y += dpp_f<0x114>(y); y += dpp_f<0x118>(y);
;                                         y += __shfl(x, (lane_ & 48) | 15); }
;                         else { x += dpp_f<0x101>(x); x += dpp_f<0x102>(x); x += dpp_f<0x104>(x); x += dpp_f<0x108>(x);
;                                y += dpp_f<0x101>(y); y += dpp_f<0x102>(y); y += dpp_f<0x104>(y); y += dpp_f<0x108>(y);
;                                x += __shfl(y, lane_ & 48); }
;                         xa[j] = x; xb[j] = y; }
.LBB0_2301:
	v_log_f32_e32 v16, v37
	v_log_f32_e32 v21, v33
	s_and_b64 vcc, exec, s[2:3]
	s_mov_b64 s[14:15], -1
	v_mul_f32_e32 v20, 0x3f317218, v16
	v_mul_f32_e32 v16, 0x3f317218, v21
	s_cbranch_vccnz .LBB0_2303
	s_nop 0
	v_add_f32_dpp v21, v16, v16 row_shl:1 row_mask:0xf bank_mask:0xf bound_ctrl:1
	v_add_f32_dpp v34, v20, v20 row_shl:1 row_mask:0xf bank_mask:0xf bound_ctrl:1
	s_mov_b64 s[14:15], 0
	v_add_f32_dpp v21, v21, v21 row_shl:2 row_mask:0xf bank_mask:0xf bound_ctrl:1
	v_add_f32_dpp v34, v34, v34 row_shl:2 row_mask:0xf bank_mask:0xf bound_ctrl:1
	s_nop 0
	v_add_f32_dpp v21, v21, v21 row_shl:4 row_mask:0xf bank_mask:0xf bound_ctrl:1
	v_add_f32_dpp v34, v34, v34 row_shl:4 row_mask:0xf bank_mask:0xf bound_ctrl:1
	s_nop 0
	v_add_f32_dpp v51, v21, v21 row_shl:8 row_mask:0xf bank_mask:0xf bound_ctrl:1
	s_nop 0
	s_nop 0
	s_nop 0
	v_add_f32_dpp v34, v34, v34 row_shl:8 row_mask:0xf bank_mask:0xf bound_ctrl:1
	s_waitcnt lgkmcnt(0)
	s_nop 1
	v_add_f32_dpp v21, v51, v34 row_newbcast:0 row_mask:0xf bank_mask:0xf
.LBB0_2303:
	s_andn2_b64 vcc, exec, s[14:15]
	s_cbranch_vccnz .LBB0_2305
	v_add_f32_dpp v20, v20, v20 row_shr:1 row_mask:0xf bank_mask:0xf bound_ctrl:1
	v_add_f32_dpp v16, v16, v16 row_shr:1 row_mask:0xf bank_mask:0xf bound_ctrl:1
	s_nop 0
	v_add_f32_dpp v20, v20, v20 row_shr:2 row_mask:0xf bank_mask:0xf bound_ctrl:1
	v_add_f32_dpp v16, v16, v16 row_shr:2 row_mask:0xf bank_mask:0xf bound_ctrl:1
	s_nop 0
	v_add_f32_dpp v20, v20, v20 row_shr:4 row_mask:0xf bank_mask:0xf bound_ctrl:1
	v_add_f32_dpp v16, v16, v16 row_shr:4 row_mask:0xf bank_mask:0xf bound_ctrl:1
	s_nop 0
	v_add_f32_dpp v21, v20, v20 row_shr:8 row_mask:0xf bank_mask:0xf bound_ctrl:1
	s_nop 0
	s_nop 0
	s_nop 0
	v_add_f32_dpp v16, v16, v16 row_shr:8 row_mask:0xf bank_mask:0xf bound_ctrl:1
	s_waitcnt lgkmcnt(0)
	s_nop 1
	v_add_f32_dpp v51, v21, v16 row_newbcast:15 row_mask:0xf bank_mask:0xf
.LBB0_2305:
	v_mul_f32_e32 v16, 0xbfb8aa3b, v22
	v_exp_f32_e32 v16, v16
	v_mul_f32_e32 v18, 0xbfb8aa3b, v18
	v_exp_f32_e32 v18, v18
	v_mul_f32_e32 v19, 0xbfb8aa3b, v19
	v_add_f32_e32 v16, 1.0, v16
	s_and_b64 vcc, exec, s[2:3]
	v_add_f32_e32 v20, 1.0, v18
	v_rcp_f32_e32 v18, v16
	v_mul_f32_e32 v16, 0xbfb8aa3b, v23
	v_exp_f32_e32 v16, v16
	v_exp_f32_e32 v23, v19
	v_rcp_f32_e32 v22, v20
	s_mov_b64 s[14:15], -1
	v_add_f32_e32 v16, 1.0, v16
	v_rcp_f32_e32 v19, v16
	v_add_f32_e32 v16, 1.0, v23
	v_rcp_f32_e32 v23, v16
	v_pk_fma_f32 v[38:39], v[18:19], v[72:73], v[66:67]
	s_nop 0
	v_log_f32_e32 v16, v38
	v_pk_fma_f32 v[34:35], v[22:23], v[72:73], v[66:67]
	v_mul_f32_e32 v18, 0x3f317218, v16
	v_log_f32_e32 v19, v34
	s_nop 0
	v_mul_f32_e32 v16, 0x3f317218, v19
	s_cbranch_vccnz .LBB0_2307
	s_nop 0
	v_add_f32_dpp v19, v16, v16 row_shl:1 row_mask:0xf bank_mask:0xf bound_ctrl:1
	v_add_f32_dpp v20, v18, v18 row_shl:1 row_mask:0xf bank_mask:0xf bound_ctrl:1
	s_mov_b64 s[14:15], 0
	v_add_f32_dpp v19, v19, v19 row_shl:2 row_mask:0xf bank_mask:0xf bound_ctrl:1
	v_add_f32_dpp v20, v20, v20 row_shl:2 row_mask:0xf bank_mask:0xf bound_ctrl:1
	s_nop 0
	v_add_f32_dpp v19, v19, v19 row_shl:4 row_mask:0xf bank_mask:0xf bound_ctrl:1
	v_add_f32_dpp v20, v20, v20 row_shl:4 row_mask:0xf bank_mask:0xf bound_ctrl:1
	s_nop 0
	v_add_f32_dpp v52, v19, v19 row_shl:8 row_mask:0xf bank_mask:0xf bound_ctrl:1
	s_nop 0
	s_nop 0
	s_nop 0
	v_add_f32_dpp v20, v20, v20 row_shl:8 row_mask:0xf bank_mask:0xf bound_ctrl:1
	s_waitcnt lgkmcnt(0)
	s_nop 1
	v_add_f32_dpp v19, v52, v20 row_newbcast:0 row_mask:0xf bank_mask:0xf
.LBB0_2307:
	s_andn2_b64 vcc, exec, s[14:15]
	s_cbranch_vccnz .LBB0_2309
	v_add_f32_dpp v18, v18, v18 row_shr:1 row_mask:0xf bank_mask:0xf bound_ctrl:1
	v_add_f32_dpp v16, v16, v16 row_shr:1 row_mask:0xf bank_mask:0xf bound_ctrl:1
	s_nop 0
	v_add_f32_dpp v18, v18, v18 row_shr:2 row_mask:0xf bank_mask:0xf bound_ctrl:1
	v_add_f32_dpp v16, v16, v16 row_shr:2 row_mask:0xf bank_mask:0xf bound_ctrl:1
	s_nop 0
	v_add_f32_dpp v18, v18, v18 row_shr:4 row_mask:0xf bank_mask:0xf bound_ctrl:1
	v_add_f32_dpp v16, v16, v16 row_shr:4 row_mask:0xf bank_mask:0xf bound_ctrl:1
	s_nop 0
	v_add_f32_dpp v19, v18, v18 row_shr:8 row_mask:0xf bank_mask:0xf bound_ctrl:1
	s_nop 0
	s_nop 0
	s_nop 0
	v_add_f32_dpp v16, v16, v16 row_shr:8 row_mask:0xf bank_mask:0xf bound_ctrl:1
	s_waitcnt lgkmcnt(0)
	s_nop 1
	v_add_f32_dpp v52, v19, v16 row_newbcast:15 row_mask:0xf bank_mask:0xf
.LBB0_2309:
	v_log_f32_e32 v16, v39
	v_log_f32_e32 v20, v35
	s_and_b64 vcc, exec, s[2:3]
	s_mov_b64 s[14:15], -1
	v_mul_f32_e32 v18, 0x3f317218, v16
	v_mul_f32_e32 v16, 0x3f317218, v20
	s_cbranch_vccnz .LBB0_2311
	s_nop 0
	v_add_f32_dpp v20, v16, v16 row_shl:1 row_mask:0xf bank_mask:0xf bound_ctrl:1
	v_add_f32_dpp v22, v18, v18 row_shl:1 row_mask:0xf bank_mask:0xf bound_ctrl:1
	s_mov_b64 s[14:15], 0
	v_add_f32_dpp v20, v20, v20 row_shl:2 row_mask:0xf bank_mask:0xf bound_ctrl:1
	v_add_f32_dpp v22, v22, v22 row_shl:2 row_mask:0xf bank_mask:0xf bound_ctrl:1
	s_nop 0
	v_add_f32_dpp v20, v20, v20 row_shl:4 row_mask:0xf bank_mask:0xf bound_ctrl:1
	v_add_f32_dpp v22, v22, v22 row_shl:4 row_mask:0xf bank_mask:0xf bound_ctrl:1
	s_nop 0
	v_add_f32_dpp v53, v20, v20 row_shl:8 row_mask:0xf bank_mask:0xf bound_ctrl:1
	s_nop 0
	s_nop 0
	s_nop 0
	v_add_f32_dpp v22, v22, v22 row_shl:8 row_mask:0xf bank_mask:0xf bound_ctrl:1
	s_waitcnt lgkmcnt(0)
	s_nop 1
	v_add_f32_dpp v23, v53, v22 row_newbcast:0 row_mask:0xf bank_mask:0xf
.LBB0_2311:
	s_andn2_b64 vcc, exec, s[14:15]
	s_cbranch_vccnz .LBB0_2313
	v_add_f32_dpp v18, v18, v18 row_shr:1 row_mask:0xf bank_mask:0xf bound_ctrl:1
	v_add_f32_dpp v16, v16, v16 row_shr:1 row_mask:0xf bank_mask:0xf bound_ctrl:1
	s_nop 0
	v_add_f32_dpp v18, v18, v18 row_shr:2 row_mask:0xf bank_mask:0xf bound_ctrl:1
	v_add_f32_dpp v16, v16, v16 row_shr:2 row_mask:0xf bank_mask:0xf bound_ctrl:1
	s_nop 0
	v_add_f32_dpp v18, v18, v18 row_shr:4 row_mask:0xf bank_mask:0xf bound_ctrl:1
	v_add_f32_dpp v16, v16, v16 row_shr:4 row_mask:0xf bank_mask:0xf bound_ctrl:1
	s_nop 0
	v_add_f32_dpp v23, v18, v18 row_shr:8 row_mask:0xf bank_mask:0xf bound_ctrl:1
	s_nop 0
	s_nop 0
	s_nop 0
	v_add_f32_dpp v16, v16, v16 row_shr:8 row_mask:0xf bank_mask:0xf bound_ctrl:1
	s_waitcnt lgkmcnt(0)
	s_nop 1
	v_add_f32_dpp v53, v23, v16 row_newbcast:15 row_mask:0xf bank_mask:0xf

; DI float sigmoid_f(float x) { return __builtin_amdgcn_rcpf(1.f + __expf(-x)); }
; template <int CTRL> DI float dpp_f(float x) { return __int_as_float(__builtin_amdgcn_update_dpp(0, __float_as_int(x), CTRL, 0xF, 0xF, true)); }
;     DI void operator()(const AccT& acc, int brow, int bcol, int wr, int wc, int fr, int fq) const {
;     ...
;                 for (int mp = 0; mp < 2; ++mp) {
;                     const size_t row0 = brow + ai * 128 + wr * 64 + mp * 32 + fr, row1 = row0 + 16;
;                     float fa[8], fb[8], xa[8], xb[8];
; #pragma unroll
;                     for (int j = 0; j < 4; ++j) { fa[j] = lb0[j] + (1.f - lb0[j]) * sigmoid_f(acc[ai][bj][2 * mp][0][j]); fa[4 + j] = lb1[j] + (1.f - lb1[j]) * sigmoid_f(acc[ai][bj][2 * mp][1][j]);
;                                                   fb[j] = lb0[j] + (1.f - lb0[j]) * sigmoid_f(acc[ai][bj][2 * mp + 1][0][j]); fb[4 + j] = lb1[j] + (1.f - lb1[j]) * sigmoid_f(acc[ai][bj][2 * mp + 1][1][j]); }
; #pragma unroll
;                     for (int j = 0; j < 8; ++j) { float x = __builtin_amdgcn_logf(fa[j]) * 0.6931471805599453f, y = __builtin_amdgcn_logf(fb[j]) * 0.6931471805599453f;
;                         if (dir == 0) { x += dpp_f<0x111>(x); x += dpp_f<0x112>(x); x += dpp_f<0x114>(x); x += dpp_f<0x118>(x);
;                                         y += dpp_f<0x111>(y); y += dpp_f<0x112>(y); y += dpp_f<0x114>(y); y += dpp_f<0x118>(y);
;                                         y += __shfl(x, (lane_ & 48) | 15); }
;                         else { x += dpp_f<0x101>(x); x += dpp_f<0x102>(x); x += dpp_f<0x104>(x); x += dpp_f<0x108>(x);
;                                y += dpp_f<0x101>(y); y += dpp_f<0x102>(y); y += dpp_f<0x104>(y); y += dpp_f<0x108>(y);
;                                x += __shfl(y, lane_ & 48); }
;                         xa[j] = x; xb[j] = y; }
.LBB0_2317:
	s_or_b64 exec, exec, s[14:15]
	v_mul_f32_e32 v12, 0xbfb8aa3b, v12
	v_exp_f32_e32 v12, v12
	v_mul_f32_e32 v8, 0xbfb8aa3b, v8
	v_exp_f32_e32 v8, v8
	v_mul_f32_e32 v9, 0xbfb8aa3b, v9
	v_add_f32_e32 v12, 1.0, v12
	s_and_b64 vcc, exec, s[2:3]
	v_add_f32_e32 v16, 1.0, v8
	v_rcp_f32_e32 v8, v12
	v_mul_f32_e32 v12, 0xbfb8aa3b, v13
	v_exp_f32_e32 v12, v12
	v_exp_f32_e32 v13, v9
	v_rcp_f32_e32 v16, v16
	s_mov_b64 s[14:15], -1
	v_add_f32_e32 v9, 1.0, v12
	v_add_f32_e32 v12, 1.0, v13
	v_rcp_f32_e32 v9, v9
	v_rcp_f32_e32 v17, v12
	v_pk_fma_f32 v[12:13], v[8:9], v[60:61], v[68:69]
	v_pk_fma_f32 v[8:9], v[16:17], v[60:61], v[68:69]
	v_log_f32_e32 v16, v12
	v_log_f32_e32 v18, v8
	v_mul_f32_e32 v17, 0x3f317218, v16
	v_mul_f32_e32 v16, 0x3f317218, v18
	s_cbranch_vccnz .LBB0_2319
	s_nop 0
	v_add_f32_dpp v18, v16, v16 row_shl:1 row_mask:0xf bank_mask:0xf bound_ctrl:1
	v_add_f32_dpp v19, v17, v17 row_shl:1 row_mask:0xf bank_mask:0xf bound_ctrl:1
	s_mov_b64 s[14:15], 0
	v_add_f32_dpp v18, v18, v18 row_shl:2 row_mask:0xf bank_mask:0xf bound_ctrl:1
	v_add_f32_dpp v19, v19, v19 row_shl:2 row_mask:0xf bank_mask:0xf bound_ctrl:1
	s_nop 0
	v_add_f32_dpp v18, v18, v18 row_shl:4 row_mask:0xf bank_mask:0xf bound_ctrl:1
	v_add_f32_dpp v19, v19, v19 row_shl:4 row_mask:0xf bank_mask:0xf bound_ctrl:1
	s_nop 0
	v_add_f32_dpp v26, v18, v18 row_shl:8 row_mask:0xf bank_mask:0xf bound_ctrl:1
	s_nop 0
	s_nop 0
	s_nop 0
	v_add_f32_dpp v19, v19, v19 row_shl:8 row_mask:0xf bank_mask:0xf bound_ctrl:1
	s_waitcnt lgkmcnt(0)
	s_nop 1
	v_add_f32_dpp v29, v26, v19 row_newbcast:0 row_mask:0xf bank_mask:0xf
.LBB0_2319:
	s_andn2_b64 vcc, exec, s[14:15]
	s_cbranch_vccnz .LBB0_2321
	v_add_f32_dpp v17, v17, v17 row_shr:1 row_mask:0xf bank_mask:0xf bound_ctrl:1
	v_add_f32_dpp v16, v16, v16 row_shr:1 row_mask:0xf bank_mask:0xf bound_ctrl:1
	s_nop 0
	v_add_f32_dpp v17, v17, v17 row_shr:2 row_mask:0xf bank_mask:0xf bound_ctrl:1
	v_add_f32_dpp v16, v16, v16 row_shr:2 row_mask:0xf bank_mask:0xf bound_ctrl:1
	s_nop 0
	v_add_f32_dpp v17, v17, v17 row_shr:4 row_mask:0xf bank_mask:0xf bound_ctrl:1
	v_add_f32_dpp v16, v16, v16 row_shr:4 row_mask:0xf bank_mask:0xf bound_ctrl:1
	s_nop 0
	v_add_f32_dpp v29, v17, v17 row_shr:8 row_mask:0xf bank_mask:0xf bound_ctrl:1
	s_nop 0
	s_nop 0
	s_nop 0
	v_add_f32_dpp v16, v16, v16 row_shr:8 row_mask:0xf bank_mask:0xf bound_ctrl:1
	s_waitcnt lgkmcnt(0)
	s_nop 1
	v_add_f32_dpp v26, v29, v16 row_newbcast:15 row_mask:0xf bank_mask:0xf
.LBB0_2321:
	v_log_f32_e32 v16, v13
	v_log_f32_e32 v18, v9
	s_and_b64 vcc, exec, s[2:3]
	s_mov_b64 s[14:15], -1
	v_mul_f32_e32 v17, 0x3f317218, v16
	v_mul_f32_e32 v16, 0x3f317218, v18
	s_cbranch_vccnz .LBB0_2323
	s_nop 0
	v_add_f32_dpp v18, v16, v16 row_shl:1 row_mask:0xf bank_mask:0xf bound_ctrl:1
	v_add_f32_dpp v19, v17, v17 row_shl:1 row_mask:0xf bank_mask:0xf bound_ctrl:1
	s_mov_b64 s[14:15], 0
	v_add_f32_dpp v18, v18, v18 row_shl:2 row_mask:0xf bank_mask:0xf bound_ctrl:1
	v_add_f32_dpp v19, v19, v19 row_shl:2 row_mask:0xf bank_mask:0xf bound_ctrl:1
	s_nop 0
	v_add_f32_dpp v18, v18, v18 row_shl:4 row_mask:0xf bank_mask:0xf bound_ctrl:1
	v_add_f32_dpp v19, v19, v19 row_shl:4 row_mask:0xf bank_mask:0xf bound_ctrl:1
	s_nop 0
	v_add_f32_dpp v27, v18, v18 row_shl:8 row_mask:0xf bank_mask:0xf bound_ctrl:1
	s_nop 0
	s_nop 0
	s_nop 0
	v_add_f32_dpp v19, v19, v19 row_shl:8 row_mask:0xf bank_mask:0xf bound_ctrl:1
	s_waitcnt lgkmcnt(0)
	s_nop 1
	v_add_f32_dpp v31, v27, v19 row_newbcast:0 row_mask:0xf bank_mask:0xf
.LBB0_2323:
	s_andn2_b64 vcc, exec, s[14:15]
	s_cbranch_vccnz .LBB0_2325
	v_add_f32_dpp v17, v17, v17 row_shr:1 row_mask:0xf bank_mask:0xf bound_ctrl:1
	v_add_f32_dpp v16, v16, v16 row_shr:1 row_mask:0xf bank_mask:0xf bound_ctrl:1
	s_nop 0
	v_add_f32_dpp v17, v17, v17 row_shr:2 row_mask:0xf bank_mask:0xf bound_ctrl:1
	v_add_f32_dpp v16, v16, v16 row_shr:2 row_mask:0xf bank_mask:0xf bound_ctrl:1
	s_nop 0
	v_add_f32_dpp v17, v17, v17 row_shr:4 row_mask:0xf bank_mask:0xf bound_ctrl:1
	v_add_f32_dpp v16, v16, v16 row_shr:4 row_mask:0xf bank_mask:0xf bound_ctrl:1
	s_nop 0
	v_add_f32_dpp v31, v17, v17 row_shr:8 row_mask:0xf bank_mask:0xf bound_ctrl:1
	s_nop 0
	s_nop 0
	s_nop 0
	v_add_f32_dpp v16, v16, v16 row_shr:8 row_mask:0xf bank_mask:0xf bound_ctrl:1
	s_waitcnt lgkmcnt(0)
	s_nop 1
	v_add_f32_dpp v27, v31, v16 row_newbcast:15 row_mask:0xf bank_mask:0xf
.LBB0_2325:
	v_mul_f32_e32 v14, 0xbfb8aa3b, v14
	v_exp_f32_e32 v14, v14
	v_mul_f32_e32 v10, 0xbfb8aa3b, v10
	v_exp_f32_e32 v10, v10
	v_mul_f32_e32 v11, 0xbfb8aa3b, v11
	v_add_f32_e32 v14, 1.0, v14
	s_and_b64 vcc, exec, s[2:3]
	v_add_f32_e32 v16, 1.0, v10
	v_rcp_f32_e32 v10, v14
	v_mul_f32_e32 v14, 0xbfb8aa3b, v15
	v_exp_f32_e32 v14, v14
	v_exp_f32_e32 v15, v11
	v_rcp_f32_e32 v16, v16
	s_mov_b64 s[14:15], -1
	v_add_f32_e32 v11, 1.0, v14
	v_add_f32_e32 v14, 1.0, v15
	v_rcp_f32_e32 v11, v11
	v_rcp_f32_e32 v17, v14
	v_pk_fma_f32 v[14:15], v[10:11], v[58:59], v[70:71]
	v_pk_fma_f32 v[10:11], v[16:17], v[58:59], v[70:71]
	v_log_f32_e32 v16, v14
	v_log_f32_e32 v18, v10
	v_mul_f32_e32 v17, 0x3f317218, v16
	v_mul_f32_e32 v16, 0x3f317218, v18
	s_cbranch_vccnz .LBB0_2327
	s_nop 0
	v_add_f32_dpp v18, v16, v16 row_shl:1 row_mask:0xf bank_mask:0xf bound_ctrl:1
	v_add_f32_dpp v19, v17, v17 row_shl:1 row_mask:0xf bank_mask:0xf bound_ctrl:1
	s_mov_b64 s[14:15], 0
	v_add_f32_dpp v18, v18, v18 row_shl:2 row_mask:0xf bank_mask:0xf bound_ctrl:1
	v_add_f32_dpp v19, v19, v19 row_shl:2 row_mask:0xf bank_mask:0xf bound_ctrl:1
	s_nop 0
	v_add_f32_dpp v18, v18, v18 row_shl:4 row_mask:0xf bank_mask:0xf bound_ctrl:1
	v_add_f32_dpp v19, v19, v19 row_shl:4 row_mask:0xf bank_mask:0xf bound_ctrl:1
	s_nop 0
	v_add_f32_dpp v28, v18, v18 row_shl:8 row_mask:0xf bank_mask:0xf bound_ctrl:1
	s_nop 0
	s_nop 0
	s_nop 0
	v_add_f32_dpp v19, v19, v19 row_shl:8 row_mask:0xf bank_mask:0xf bound_ctrl:1
	s_waitcnt lgkmcnt(0)
	s_nop 1
	v_add_f32_dpp v32, v28, v19 row_newbcast:0 row_mask:0xf bank_mask:0xf
; DI float sigmoid_f(float x) { return __builtin_amdgcn_rcpf(1.f + __expf(-x)); }
; template <int CTRL> DI float dpp_f(float x) { return __int_as_float(__builtin_amdgcn_update_dpp(0, __float_as_int(x), CTRL, 0xF, 0xF, true)); }
;     DI void operator()(const AccT& acc, int brow, int bcol, int wr, int wc, int fr, int fq) const {
;     ...
;                     for (int j = 0; j < 4; ++j) { fa[j] = lb0[j] + (1.f - lb0[j]) * sigmoid_f(acc[ai][bj][2 * mp][0][j]); fa[4 + j] = lb1[j] + (1.f - lb1[j]) * sigmoid_f(acc[ai][bj][2 * mp][1][j]);
;                                                   fb[j] = lb0[j] + (1.f - lb0[j]) * sigmoid_f(acc[ai][bj][2 * mp + 1][0][j]); fb[4 + j] = lb1[j] + (1.f - lb1[j]) * sigmoid_f(acc[ai][bj][2 * mp + 1][1][j]); }
; #pragma unroll
;                     for (int j = 0; j < 8; ++j) { float x = __builtin_amdgcn_logf(fa[j]) * 0.6931471805599453f, y = __builtin_amdgcn_logf(fb[j]) * 0.6931471805599453f;
;                         if (dir == 0) { x += dpp_f<0x111>(x); x += dpp_f<0x112>(x); x += dpp_f<0x114>(x); x += dpp_f<0x118>(x);
;                                         y += dpp_f<0x111>(y); y += dpp_f<0x112>(y); y += dpp_f<0x114>(y); y += dpp_f<0x118>(y);
;                                         y += __shfl(x, (lane_ & 48) | 15); }
;                         else { x += dpp_f<0x101>(x); x += dpp_f<0x102>(x); x += dpp_f<0x104>(x); x += dpp_f<0x108>(x);
;                                y += dpp_f<0x101>(y); y += dpp_f<0x102>(y); y += dpp_f<0x104>(y); y += dpp_f<0x108>(y);
;                                x += __shfl(y, lane_ & 48); }
;                         xa[j] = x; xb[j] = y; }
.LBB0_2327:
	s_andn2_b64 vcc, exec, s[14:15]
	s_cbranch_vccnz .LBB0_2329
	v_add_f32_dpp v17, v17, v17 row_shr:1 row_mask:0xf bank_mask:0xf bound_ctrl:1
	v_add_f32_dpp v16, v16, v16 row_shr:1 row_mask:0xf bank_mask:0xf bound_ctrl:1
	s_nop 0
	v_add_f32_dpp v17, v17, v17 row_shr:2 row_mask:0xf bank_mask:0xf bound_ctrl:1
	v_add_f32_dpp v16, v16, v16 row_shr:2 row_mask:0xf bank_mask:0xf bound_ctrl:1
	s_nop 0
	v_add_f32_dpp v17, v17, v17 row_shr:4 row_mask:0xf bank_mask:0xf bound_ctrl:1
	v_add_f32_dpp v16, v16, v16 row_shr:4 row_mask:0xf bank_mask:0xf bound_ctrl:1
	s_nop 0
	v_add_f32_dpp v32, v17, v17 row_shr:8 row_mask:0xf bank_mask:0xf bound_ctrl:1
	s_nop 0
	s_nop 0
	s_nop 0
	v_add_f32_dpp v16, v16, v16 row_shr:8 row_mask:0xf bank_mask:0xf bound_ctrl:1
	s_waitcnt lgkmcnt(0)
	s_nop 1
	v_add_f32_dpp v28, v32, v16 row_newbcast:15 row_mask:0xf bank_mask:0xf
.LBB0_2329:
	v_log_f32_e32 v16, v15
	v_log_f32_e32 v18, v11
	s_and_b64 vcc, exec, s[2:3]
	s_mov_b64 s[14:15], -1
	v_mul_f32_e32 v17, 0x3f317218, v16
	v_mul_f32_e32 v16, 0x3f317218, v18
	s_cbranch_vccnz .LBB0_2331
	s_nop 0
	v_add_f32_dpp v18, v16, v16 row_shl:1 row_mask:0xf bank_mask:0xf bound_ctrl:1
	v_add_f32_dpp v19, v17, v17 row_shl:1 row_mask:0xf bank_mask:0xf bound_ctrl:1
	s_mov_b64 s[14:15], 0
	v_add_f32_dpp v18, v18, v18 row_shl:2 row_mask:0xf bank_mask:0xf bound_ctrl:1
	v_add_f32_dpp v19, v19, v19 row_shl:2 row_mask:0xf bank_mask:0xf bound_ctrl:1
	s_nop 0
	v_add_f32_dpp v18, v18, v18 row_shl:4 row_mask:0xf bank_mask:0xf bound_ctrl:1
	v_add_f32_dpp v19, v19, v19 row_shl:4 row_mask:0xf bank_mask:0xf bound_ctrl:1
	s_nop 0
	v_add_f32_dpp v30, v18, v18 row_shl:8 row_mask:0xf bank_mask:0xf bound_ctrl:1
	s_nop 0
	s_nop 0
	s_nop 0
	v_add_f32_dpp v19, v19, v19 row_shl:8 row_mask:0xf bank_mask:0xf bound_ctrl:1
	s_waitcnt lgkmcnt(0)
	s_nop 1
	v_add_f32_dpp v34, v30, v19 row_newbcast:0 row_mask:0xf bank_mask:0xf
.LBB0_2331:
	s_andn2_b64 vcc, exec, s[14:15]
	s_cbranch_vccnz .LBB0_2333
	v_add_f32_dpp v17, v17, v17 row_shr:1 row_mask:0xf bank_mask:0xf bound_ctrl:1
	v_add_f32_dpp v16, v16, v16 row_shr:1 row_mask:0xf bank_mask:0xf bound_ctrl:1
	s_nop 0
	v_add_f32_dpp v17, v17, v17 row_shr:2 row_mask:0xf bank_mask:0xf bound_ctrl:1
	v_add_f32_dpp v16, v16, v16 row_shr:2 row_mask:0xf bank_mask:0xf bound_ctrl:1
	s_nop 0
	v_add_f32_dpp v17, v17, v17 row_shr:4 row_mask:0xf bank_mask:0xf bound_ctrl:1
	v_add_f32_dpp v16, v16, v16 row_shr:4 row_mask:0xf bank_mask:0xf bound_ctrl:1
	s_nop 0
	v_add_f32_dpp v34, v17, v17 row_shr:8 row_mask:0xf bank_mask:0xf bound_ctrl:1
	s_nop 0
	s_nop 0
	s_nop 0
	v_add_f32_dpp v16, v16, v16 row_shr:8 row_mask:0xf bank_mask:0xf bound_ctrl:1
	s_waitcnt lgkmcnt(0)
	s_nop 1
	v_add_f32_dpp v30, v34, v16 row_newbcast:15 row_mask:0xf bank_mask:0xf
.LBB0_2333:
	v_mul_f32_e32 v4, 0xbfb8aa3b, v4
	v_exp_f32_e32 v4, v4
	v_mul_f32_e32 v0, 0xbfb8aa3b, v0
	v_exp_f32_e32 v0, v0
	v_mul_f32_e32 v1, 0xbfb8aa3b, v1
	v_add_f32_e32 v4, 1.0, v4
	v_exp_f32_e32 v17, v1
	v_add_f32_e32 v16, 1.0, v0
	v_rcp_f32_e32 v0, v4
	v_mul_f32_e32 v4, 0xbfb8aa3b, v5
	v_exp_f32_e32 v5, v4
	v_rcp_f32_e32 v4, v16
	s_and_b64 vcc, exec, s[2:3]
	s_mov_b64 s[14:15], -1
	v_add_f32_e32 v1, 1.0, v5
	v_add_f32_e32 v5, 1.0, v17
	v_rcp_f32_e32 v1, v1
	v_rcp_f32_e32 v5, v5
	v_pk_fma_f32 v[20:21], v[0:1], v[62:63], v[64:65]
	v_pk_fma_f32 v[16:17], v[4:5], v[62:63], v[64:65]
	v_log_f32_e32 v0, v20
	v_log_f32_e32 v1, v16
	v_mul_f32_e32 v4, 0x3f317218, v0
	v_mul_f32_e32 v0, 0x3f317218, v1
	s_cbranch_vccnz .LBB0_2335
	s_nop 0
	v_add_f32_dpp v1, v0, v0 row_shl:1 row_mask:0xf bank_mask:0xf bound_ctrl:1
	v_add_f32_dpp v5, v4, v4 row_shl:1 row_mask:0xf bank_mask:0xf bound_ctrl:1
	s_mov_b64 s[14:15], 0
	v_add_f32_dpp v1, v1, v1 row_shl:2 row_mask:0xf bank_mask:0xf bound_ctrl:1
	v_add_f32_dpp v5, v5, v5 row_shl:2 row_mask:0xf bank_mask:0xf bound_ctrl:1
	s_nop 0
	v_add_f32_dpp v1, v1, v1 row_shl:4 row_mask:0xf bank_mask:0xf bound_ctrl:1
	v_add_f32_dpp v5, v5, v5 row_shl:4 row_mask:0xf bank_mask:0xf bound_ctrl:1
	s_nop 0
	v_add_f32_dpp v33, v1, v1 row_shl:8 row_mask:0xf bank_mask:0xf bound_ctrl:1
	s_nop 0
	s_nop 0
	s_nop 0
	v_add_f32_dpp v5, v5, v5 row_shl:8 row_mask:0xf bank_mask:0xf bound_ctrl:1
	s_waitcnt lgkmcnt(0)
	s_nop 1
	v_add_f32_dpp v1, v33, v5 row_newbcast:0 row_mask:0xf bank_mask:0xf
.LBB0_2335:
	s_andn2_b64 vcc, exec, s[14:15]
	s_cbranch_vccnz .LBB0_2337
	v_add_f32_dpp v1, v4, v4 row_shr:1 row_mask:0xf bank_mask:0xf bound_ctrl:1
	s_nop 0
	s_nop 0
	v_add_f32_dpp v1, v1, v1 row_shr:2 row_mask:0xf bank_mask:0xf bound_ctrl:1
	v_add_f32_dpp v0, v0, v0 row_shr:1 row_mask:0xf bank_mask:0xf bound_ctrl:1
	s_nop 0
	v_add_f32_dpp v1, v1, v1 row_shr:4 row_mask:0xf bank_mask:0xf bound_ctrl:1
	v_add_f32_dpp v0, v0, v0 row_shr:2 row_mask:0xf bank_mask:0xf bound_ctrl:1
	s_nop 0
	v_add_f32_dpp v1, v1, v1 row_shr:8 row_mask:0xf bank_mask:0xf bound_ctrl:1
	s_nop 0
	v_add_f32_dpp v0, v0, v0 row_shr:4 row_mask:0xf bank_mask:0xf bound_ctrl:1
	s_nop 1
	v_add_f32_dpp v0, v0, v0 row_shr:8 row_mask:0xf bank_mask:0xf bound_ctrl:1
	s_waitcnt lgkmcnt(0)
	s_nop 1
	v_add_f32_dpp v33, v1, v0 row_newbcast:15 row_mask:0xf bank_mask:0xf
; DI float sigmoid_f(float x) { return __builtin_amdgcn_rcpf(1.f + __expf(-x)); }
; template <int CTRL> DI float dpp_f(float x) { return __int_as_float(__builtin_amdgcn_update_dpp(0, __float_as_int(x), CTRL, 0xF, 0xF, true)); }
;     DI void operator()(const AccT& acc, int brow, int bcol, int wr, int wc, int fr, int fq) const {
;     ...
;                     for (int j = 0; j < 4; ++j) { fa[j] = lb0[j] + (1.f - lb0[j]) * sigmoid_f(acc[ai][bj][2 * mp][0][j]); fa[4 + j] = lb1[j] + (1.f - lb1[j]) * sigmoid_f(acc[ai][bj][2 * mp][1][j]);
;                                                   fb[j] = lb0[j] + (1.f - lb0[j]) * sigmoid_f(acc[ai][bj][2 * mp + 1][0][j]); fb[4 + j] = lb1[j] + (1.f - lb1[j]) * sigmoid_f(acc[ai][bj][2 * mp + 1][1][j]); }
; #pragma unroll
;                     for (int j = 0; j < 8; ++j) { float x = __builtin_amdgcn_logf(fa[j]) * 0.6931471805599453f, y = __builtin_amdgcn_logf(fb[j]) * 0.6931471805599453f;
;                         if (dir == 0) { x += dpp_f<0x111>(x); x += dpp_f<0x112>(x); x += dpp_f<0x114>(x); x += dpp_f<0x118>(x);
;                                         y += dpp_f<0x111>(y); y += dpp_f<0x112>(y); y += dpp_f<0x114>(y); y += dpp_f<0x118>(y);
;                                         y += __shfl(x, (lane_ & 48) | 15); }
;                         else { x += dpp_f<0x101>(x); x += dpp_f<0x102>(x); x += dpp_f<0x104>(x); x += dpp_f<0x108>(x);
;                                y += dpp_f<0x101>(y); y += dpp_f<0x102>(y); y += dpp_f<0x104>(y); y += dpp_f<0x108>(y);
;                                x += __shfl(y, lane_ & 48); }
;                         xa[j] = x; xb[j] = y; }
.LBB0_2337:
	v_log_f32_e32 v0, v21
	v_log_f32_e32 v5, v17
	s_and_b64 vcc, exec, s[2:3]
	s_mov_b64 s[14:15], -1
	v_mul_f32_e32 v4, 0x3f317218, v0
	v_mul_f32_e32 v0, 0x3f317218, v5
	s_cbranch_vccnz .LBB0_2339
	s_nop 0
	v_add_f32_dpp v5, v0, v0 row_shl:1 row_mask:0xf bank_mask:0xf bound_ctrl:1
	v_add_f32_dpp v18, v4, v4 row_shl:1 row_mask:0xf bank_mask:0xf bound_ctrl:1
	s_mov_b64 s[14:15], 0
	v_add_f32_dpp v5, v5, v5 row_shl:2 row_mask:0xf bank_mask:0xf bound_ctrl:1
	v_add_f32_dpp v18, v18, v18 row_shl:2 row_mask:0xf bank_mask:0xf bound_ctrl:1
	s_nop 0
	v_add_f32_dpp v5, v5, v5 row_shl:4 row_mask:0xf bank_mask:0xf bound_ctrl:1
	v_add_f32_dpp v18, v18, v18 row_shl:4 row_mask:0xf bank_mask:0xf bound_ctrl:1
	s_nop 0
	v_add_f32_dpp v35, v5, v5 row_shl:8 row_mask:0xf bank_mask:0xf bound_ctrl:1
	s_nop 0
	s_nop 0
	s_nop 0
	v_add_f32_dpp v18, v18, v18 row_shl:8 row_mask:0xf bank_mask:0xf bound_ctrl:1
	s_waitcnt lgkmcnt(0)
	s_nop 1
	v_add_f32_dpp v5, v35, v18 row_newbcast:0 row_mask:0xf bank_mask:0xf
.LBB0_2339:
	s_andn2_b64 vcc, exec, s[14:15]
	s_cbranch_vccnz .LBB0_2341
	v_add_f32_dpp v4, v4, v4 row_shr:1 row_mask:0xf bank_mask:0xf bound_ctrl:1
	v_add_f32_dpp v0, v0, v0 row_shr:1 row_mask:0xf bank_mask:0xf bound_ctrl:1
	s_nop 0
	v_add_f32_dpp v4, v4, v4 row_shr:2 row_mask:0xf bank_mask:0xf bound_ctrl:1
	v_add_f32_dpp v0, v0, v0 row_shr:2 row_mask:0xf bank_mask:0xf bound_ctrl:1
	s_nop 0
	v_add_f32_dpp v4, v4, v4 row_shr:4 row_mask:0xf bank_mask:0xf bound_ctrl:1
	v_add_f32_dpp v0, v0, v0 row_shr:4 row_mask:0xf bank_mask:0xf bound_ctrl:1
	s_nop 0
	v_add_f32_dpp v5, v4, v4 row_shr:8 row_mask:0xf bank_mask:0xf bound_ctrl:1
	s_nop 0
	s_nop 0
	s_nop 0
	v_add_f32_dpp v0, v0, v0 row_shr:8 row_mask:0xf bank_mask:0xf bound_ctrl:1
	s_waitcnt lgkmcnt(0)
	s_nop 1
	v_add_f32_dpp v35, v5, v0 row_newbcast:15 row_mask:0xf bank_mask:0xf
.LBB0_2341:
	v_mul_f32_e32 v0, 0xbfb8aa3b, v6
	v_exp_f32_e32 v0, v0
	v_mul_f32_e32 v2, 0xbfb8aa3b, v2
	v_exp_f32_e32 v2, v2
	v_mul_f32_e32 v3, 0xbfb8aa3b, v3
	v_add_f32_e32 v0, 1.0, v0
	s_and_b64 vcc, exec, s[2:3]
	v_add_f32_e32 v4, 1.0, v2
	v_rcp_f32_e32 v2, v0
	v_mul_f32_e32 v0, 0xbfb8aa3b, v7
	v_exp_f32_e32 v0, v0
	v_exp_f32_e32 v7, v3
	v_rcp_f32_e32 v6, v4
	s_mov_b64 s[14:15], -1
	v_add_f32_e32 v0, 1.0, v0
	v_rcp_f32_e32 v3, v0
	v_add_f32_e32 v0, 1.0, v7
	v_rcp_f32_e32 v7, v0
	v_pk_fma_f32 v[22:23], v[2:3], v[72:73], v[66:67]
	s_nop 0
	v_log_f32_e32 v0, v22
	v_pk_fma_f32 v[18:19], v[6:7], v[72:73], v[66:67]
	v_mul_f32_e32 v2, 0x3f317218, v0
	v_log_f32_e32 v3, v18
	s_nop 0
	v_mul_f32_e32 v0, 0x3f317218, v3
	s_cbranch_vccnz .LBB0_2343
	s_nop 0
	v_add_f32_dpp v3, v0, v0 row_shl:1 row_mask:0xf bank_mask:0xf bound_ctrl:1
	v_add_f32_dpp v4, v2, v2 row_shl:1 row_mask:0xf bank_mask:0xf bound_ctrl:1
	s_mov_b64 s[14:15], 0
	v_add_f32_dpp v3, v3, v3 row_shl:2 row_mask:0xf bank_mask:0xf bound_ctrl:1
	v_add_f32_dpp v4, v4, v4 row_shl:2 row_mask:0xf bank_mask:0xf bound_ctrl:1
	s_nop 0
	v_add_f32_dpp v3, v3, v3 row_shl:4 row_mask:0xf bank_mask:0xf bound_ctrl:1
	v_add_f32_dpp v4, v4, v4 row_shl:4 row_mask:0xf bank_mask:0xf bound_ctrl:1
	s_nop 0
	v_add_f32_dpp v36, v3, v3 row_shl:8 row_mask:0xf bank_mask:0xf bound_ctrl:1
	s_nop 0
	s_nop 0
	s_nop 0
	v_add_f32_dpp v4, v4, v4 row_shl:8 row_mask:0xf bank_mask:0xf bound_ctrl:1
	s_waitcnt lgkmcnt(0)
	s_nop 1
	v_add_f32_dpp v3, v36, v4 row_newbcast:0 row_mask:0xf bank_mask:0xf
.LBB0_2343:
	s_andn2_b64 vcc, exec, s[14:15]
	s_cbranch_vccnz .LBB0_2345
	v_add_f32_dpp v2, v2, v2 row_shr:1 row_mask:0xf bank_mask:0xf bound_ctrl:1
	v_add_f32_dpp v0, v0, v0 row_shr:1 row_mask:0xf bank_mask:0xf bound_ctrl:1
	s_nop 0
	v_add_f32_dpp v2, v2, v2 row_shr:2 row_mask:0xf bank_mask:0xf bound_ctrl:1
	v_add_f32_dpp v0, v0, v0 row_shr:2 row_mask:0xf bank_mask:0xf bound_ctrl:1
	s_nop 0
	v_add_f32_dpp v2, v2, v2 row_shr:4 row_mask:0xf bank_mask:0xf bound_ctrl:1
	v_add_f32_dpp v0, v0, v0 row_shr:4 row_mask:0xf bank_mask:0xf bound_ctrl:1
	s_nop 0
	v_add_f32_dpp v3, v2, v2 row_shr:8 row_mask:0xf bank_mask:0xf bound_ctrl:1
	s_nop 0
	s_nop 0
	s_nop 0
	v_add_f32_dpp v0, v0, v0 row_shr:8 row_mask:0xf bank_mask:0xf bound_ctrl:1
	s_waitcnt lgkmcnt(0)
	s_nop 1
	v_add_f32_dpp v36, v3, v0 row_newbcast:15 row_mask:0xf bank_mask:0xf
.LBB0_2345:
	v_log_f32_e32 v0, v23
	v_log_f32_e32 v4, v19
	s_and_b64 vcc, exec, s[2:3]
	s_mov_b64 s[2:3], -1
	v_mul_f32_e32 v2, 0x3f317218, v0
	v_mul_f32_e32 v0, 0x3f317218, v4
	s_cbranch_vccnz .LBB0_2347
	s_nop 0
	v_add_f32_dpp v4, v0, v0 row_shl:1 row_mask:0xf bank_mask:0xf bound_ctrl:1
	v_add_f32_dpp v6, v2, v2 row_shl:1 row_mask:0xf bank_mask:0xf bound_ctrl:1
	s_mov_b64 s[2:3], 0
	v_add_f32_dpp v4, v4, v4 row_shl:2 row_mask:0xf bank_mask:0xf bound_ctrl:1
	v_add_f32_dpp v6, v6, v6 row_shl:2 row_mask:0xf bank_mask:0xf bound_ctrl:1
	s_nop 0
	v_add_f32_dpp v4, v4, v4 row_shl:4 row_mask:0xf bank_mask:0xf bound_ctrl:1
	v_add_f32_dpp v6, v6, v6 row_shl:4 row_mask:0xf bank_mask:0xf bound_ctrl:1
	s_nop 0
	v_add_f32_dpp v37, v4, v4 row_shl:8 row_mask:0xf bank_mask:0xf bound_ctrl:1
	s_nop 0
	s_nop 0
	s_nop 0
	v_add_f32_dpp v6, v6, v6 row_shl:8 row_mask:0xf bank_mask:0xf bound_ctrl:1
	s_waitcnt lgkmcnt(0)
	s_nop 1
	v_add_f32_dpp v7, v37, v6 row_newbcast:0 row_mask:0xf bank_mask:0xf
.LBB0_2347:
	s_andn2_b64 vcc, exec, s[2:3]
	s_cbranch_vccnz .LBB0_2349
	v_add_f32_dpp v2, v2, v2 row_shr:1 row_mask:0xf bank_mask:0xf bound_ctrl:1
	v_add_f32_dpp v0, v0, v0 row_shr:1 row_mask:0xf bank_mask:0xf bound_ctrl:1
	s_nop 0
	v_add_f32_dpp v2, v2, v2 row_shr:2 row_mask:0xf bank_mask:0xf bound_ctrl:1
	v_add_f32_dpp v0, v0, v0 row_shr:2 row_mask:0xf bank_mask:0xf bound_ctrl:1
	s_nop 0
	v_add_f32_dpp v2, v2, v2 row_shr:4 row_mask:0xf bank_mask:0xf bound_ctrl:1
	v_add_f32_dpp v0, v0, v0 row_shr:4 row_mask:0xf bank_mask:0xf bound_ctrl:1
	s_nop 0
	v_add_f32_dpp v7, v2, v2 row_shr:8 row_mask:0xf bank_mask:0xf bound_ctrl:1
	s_nop 0
	s_nop 0
	s_nop 0
	v_add_f32_dpp v0, v0, v0 row_shr:8 row_mask:0xf bank_mask:0xf bound_ctrl:1
	s_waitcnt lgkmcnt(0)
	s_nop 1
	v_add_f32_dpp v37, v7, v0 row_newbcast:15 row_mask:0xf bank_mask:0xf
